# removed s_setprio in GEMM loops; dead zero-inits before full-lane DPP writes removed in the up-GEMM epilogue (hazard pads re-derived)
# speedup vs baseline: 1.0343x; 1.0084x over previous
.LBB0_232:
	s_add_u32 s24, s0, 0xfffc0080
	s_addc_u32 s25, s1, -1
	s_add_i32 s45, 0, 0x10000
	s_cmp_eq_u32 s44, 12
	s_cselect_b32 s27, s7, s25
	s_cselect_b32 s26, s17, s24
	s_cselect_b32 s25, s15, s43
	s_cselect_b32 s24, s41, s42
	s_add_i32 s48, 0, 0x14000
	v_add_u32_e32 v154, s45, v151
	v_add_u32_e32 v166, s48, v151
	ds_read_b128 v[128:131], v154
	ds_read_b128 v[132:135], v154 offset:1024
	ds_read_b128 v[146:149], v154 offset:2048
	ds_read_b128 v[154:157], v154 offset:3072
	ds_read_b128 v[158:161], v166
	ds_read_b128 v[162:165], v166 offset:1024
	ds_read_b128 v[170:173], v166 offset:2048
	ds_read_b128 v[174:177], v166 offset:3072
	v_lshl_add_u64 v[166:167], s[0:1], 0, v[144:145]
	s_add_i32 m0, s23, 0xc000
	ds_read_b128 v[178:181], v153
	ds_read_b128 v[182:185], v153 offset:1024
	ds_read_b128 v[186:189], v153 offset:2048
	ds_read_b128 v[190:193], v153 offset:3072
	ds_read_b128 v[194:197], v153 offset:4096
	ds_read_b128 v[198:201], v153 offset:5120
	ds_read_b128 v[202:205], v153 offset:6144
	ds_read_b128 v[212:215], v153 offset:7168
	global_load_lds_dwordx4 v[166:167], off
	v_lshl_add_u64 v[166:167], s[0:1], 0, v[142:143]
	s_add_i32 m0, s23, 0xe000
	s_nop 0
	global_load_lds_dwordx4 v[166:167], off
	s_waitcnt vmcnt(8)
	s_waitcnt lgkmcnt(0)
	s_barrier
	s_waitcnt lgkmcnt(0)
	v_mfma_f32_16x16x32_bf16 v[120:123], v[128:131], v[178:181], v[120:123]
	v_mfma_f32_16x16x32_bf16 v[124:127], v[146:149], v[178:181], v[124:127]
	v_mfma_f32_16x16x32_bf16 v[104:107], v[128:131], v[186:189], v[104:107]
	v_mfma_f32_16x16x32_bf16 v[108:111], v[146:149], v[186:189], v[108:111]
	v_mfma_f32_16x16x32_bf16 v[88:91], v[128:131], v[194:197], v[88:91]
	v_mfma_f32_16x16x32_bf16 v[92:95], v[146:149], v[194:197], v[92:95]
	v_mfma_f32_16x16x32_bf16 v[72:75], v[128:131], v[202:205], v[72:75]
	v_mfma_f32_16x16x32_bf16 v[76:79], v[146:149], v[202:205], v[76:79]
	v_mfma_f32_16x16x32_bf16 v[120:123], v[132:135], v[182:185], v[120:123]
	v_mfma_f32_16x16x32_bf16 v[124:127], v[154:157], v[182:185], v[124:127]
	v_mfma_f32_16x16x32_bf16 v[104:107], v[132:135], v[190:193], v[104:107]
	v_mfma_f32_16x16x32_bf16 v[108:111], v[154:157], v[190:193], v[108:111]
	v_mfma_f32_16x16x32_bf16 v[88:91], v[132:135], v[198:201], v[88:91]
	v_mfma_f32_16x16x32_bf16 v[92:95], v[154:157], v[198:201], v[92:95]
	v_mfma_f32_16x16x32_bf16 v[72:75], v[132:135], v[212:215], v[72:75]
	v_mfma_f32_16x16x32_bf16 v[76:79], v[154:157], v[212:215], v[76:79]
	v_mfma_f32_16x16x32_bf16 v[112:115], v[158:161], v[178:181], v[112:115]
	v_mfma_f32_16x16x32_bf16 v[116:119], v[170:173], v[178:181], v[116:119]
	v_mfma_f32_16x16x32_bf16 v[96:99], v[158:161], v[186:189], v[96:99]
	v_mfma_f32_16x16x32_bf16 v[100:103], v[170:173], v[186:189], v[100:103]
	v_mfma_f32_16x16x32_bf16 v[80:83], v[158:161], v[194:197], v[80:83]
	v_mfma_f32_16x16x32_bf16 v[84:87], v[170:173], v[194:197], v[84:87]
	v_mfma_f32_16x16x32_bf16 v[64:67], v[158:161], v[202:205], v[64:67]
	v_mfma_f32_16x16x32_bf16 v[68:71], v[170:173], v[202:205], v[68:71]
	v_mfma_f32_16x16x32_bf16 v[112:115], v[162:165], v[182:185], v[112:115]
	v_mfma_f32_16x16x32_bf16 v[116:119], v[174:177], v[182:185], v[116:119]
	v_mfma_f32_16x16x32_bf16 v[96:99], v[162:165], v[190:193], v[96:99]
	v_mfma_f32_16x16x32_bf16 v[100:103], v[174:177], v[190:193], v[100:103]
	v_mfma_f32_16x16x32_bf16 v[80:83], v[162:165], v[198:201], v[80:83]
	v_mfma_f32_16x16x32_bf16 v[84:87], v[174:177], v[198:201], v[84:87]
	v_mfma_f32_16x16x32_bf16 v[64:67], v[162:165], v[212:215], v[64:67]
	v_mfma_f32_16x16x32_bf16 v[68:71], v[174:177], v[212:215], v[68:71]
	s_barrier
	s_add_i32 s45, s45, s34
	v_lshl_add_u64 v[166:167], s[24:25], 0, v[168:169]
	s_mov_b32 m0, s45
	ds_read_b128 v[178:181], v153 offset:16384
	ds_read_b128 v[182:185], v153 offset:17408
	ds_read_b128 v[186:189], v153 offset:18432
	ds_read_b128 v[190:193], v153 offset:19456
	ds_read_b128 v[194:197], v153 offset:20480
	ds_read_b128 v[198:201], v153 offset:21504
	ds_read_b128 v[202:205], v153 offset:22528
	ds_read_b128 v[212:215], v153 offset:23552
	global_load_lds_dwordx4 v[166:167], off
	s_add_i32 m0, s45, 0x2000
	s_add_u32 s46, s24, 0x40000
	v_lshl_add_u64 v[216:217], s[24:25], 0, v[140:141]
	s_addc_u32 s47, s25, 0
	s_add_i32 s45, s48, s34
	global_load_lds_dwordx4 v[216:217], off
	v_lshl_add_u64 v[218:219], s[46:47], 0, v[168:169]
	s_mov_b32 m0, s45
	v_lshl_add_u64 v[220:221], s[26:27], 0, v[138:139]
	global_load_lds_dwordx4 v[218:219], off
	v_lshl_add_u64 v[218:219], s[46:47], 0, v[140:141]
	s_add_i32 m0, s45, 0x2000
	s_nop 0
	global_load_lds_dwordx4 v[218:219], off
	v_lshl_add_u64 v[218:219], s[26:27], 0, v[136:137]
	s_mov_b32 m0, s23
	s_nop 0
	global_load_lds_dwordx4 v[218:219], off
	s_mov_b32 m0, s35
	s_nop 0
	global_load_lds_dwordx4 v[220:221], off
	s_waitcnt vmcnt(8)
	s_waitcnt lgkmcnt(0)
	s_barrier
	s_waitcnt lgkmcnt(0)
	v_mfma_f32_16x16x32_bf16 v[56:59], v[128:131], v[178:181], v[56:59]
	v_mfma_f32_16x16x32_bf16 v[60:63], v[146:149], v[178:181], v[60:63]
	v_mfma_f32_16x16x32_bf16 v[40:43], v[128:131], v[186:189], v[40:43]
	v_mfma_f32_16x16x32_bf16 v[44:47], v[146:149], v[186:189], v[44:47]
	v_mfma_f32_16x16x32_bf16 v[24:27], v[128:131], v[194:197], v[24:27]
	v_mfma_f32_16x16x32_bf16 v[28:31], v[146:149], v[194:197], v[28:31]
	v_mfma_f32_16x16x32_bf16 v[8:11], v[128:131], v[202:205], v[8:11]
	v_mfma_f32_16x16x32_bf16 v[12:15], v[146:149], v[202:205], v[12:15]
	v_mfma_f32_16x16x32_bf16 v[56:59], v[132:135], v[182:185], v[56:59]
	v_mfma_f32_16x16x32_bf16 v[60:63], v[154:157], v[182:185], v[60:63]
	v_mfma_f32_16x16x32_bf16 v[40:43], v[132:135], v[190:193], v[40:43]
	v_mfma_f32_16x16x32_bf16 v[44:47], v[154:157], v[190:193], v[44:47]
	v_mfma_f32_16x16x32_bf16 v[24:27], v[132:135], v[198:201], v[24:27]
	v_mfma_f32_16x16x32_bf16 v[28:31], v[154:157], v[198:201], v[28:31]
	v_mfma_f32_16x16x32_bf16 v[8:11], v[132:135], v[212:215], v[8:11]
	v_mfma_f32_16x16x32_bf16 v[12:15], v[154:157], v[212:215], v[12:15]
	v_mfma_f32_16x16x32_bf16 v[48:51], v[158:161], v[178:181], v[48:51]
	v_mfma_f32_16x16x32_bf16 v[52:55], v[170:173], v[178:181], v[52:55]
	v_mfma_f32_16x16x32_bf16 v[32:35], v[158:161], v[186:189], v[32:35]
	v_mfma_f32_16x16x32_bf16 v[36:39], v[170:173], v[186:189], v[36:39]
	v_mfma_f32_16x16x32_bf16 v[16:19], v[158:161], v[194:197], v[16:19]
	v_mfma_f32_16x16x32_bf16 v[20:23], v[170:173], v[194:197], v[20:23]
	v_mfma_f32_16x16x32_bf16 v[0:3], v[158:161], v[202:205], v[0:3]
	v_mfma_f32_16x16x32_bf16 v[4:7], v[170:173], v[202:205], v[4:7]
	v_mfma_f32_16x16x32_bf16 v[48:51], v[162:165], v[182:185], v[48:51]
	v_mfma_f32_16x16x32_bf16 v[52:55], v[174:177], v[182:185], v[52:55]
	v_mfma_f32_16x16x32_bf16 v[32:35], v[162:165], v[190:193], v[32:35]
	v_mfma_f32_16x16x32_bf16 v[36:39], v[174:177], v[190:193], v[36:39]
	v_mfma_f32_16x16x32_bf16 v[16:19], v[162:165], v[198:201], v[16:19]
	v_mfma_f32_16x16x32_bf16 v[20:23], v[174:177], v[198:201], v[20:23]
	v_mfma_f32_16x16x32_bf16 v[0:3], v[162:165], v[212:215], v[0:3]
	v_mfma_f32_16x16x32_bf16 v[4:7], v[174:177], v[212:215], v[4:7]
	s_barrier
	s_add_i32 s45, 0, 0x18000
	s_add_i32 s46, 0, 0x1c000
	v_add_u32_e32 v154, s45, v151
	v_add_u32_e32 v174, s46, v151
	ds_read_b128 v[128:131], v154
	ds_read_b128 v[132:135], v154 offset:1024
	ds_read_b128 v[146:149], v154 offset:2048
	ds_read_b128 v[154:157], v154 offset:3072
	ds_read_b128 v[158:161], v174
	ds_read_b128 v[162:165], v174 offset:1024
	ds_read_b128 v[170:173], v174 offset:2048
	ds_read_b128 v[174:177], v174 offset:3072
	s_add_u32 s26, s26, 0x40000
	s_addc_u32 s27, s27, 0
	s_mov_b32 m0, s36
	v_lshl_add_u64 v[222:223], s[26:27], 0, v[136:137]
	ds_read_b128 v[178:181], v153 offset:32768
	ds_read_b128 v[182:185], v153 offset:33792
	ds_read_b128 v[186:189], v153 offset:34816
	ds_read_b128 v[190:193], v153 offset:35840
	ds_read_b128 v[194:197], v153 offset:36864
	ds_read_b128 v[198:201], v153 offset:37888
	ds_read_b128 v[202:205], v153 offset:38912
	ds_read_b128 v[212:215], v153 offset:39936
	global_load_lds_dwordx4 v[222:223], off
	v_lshl_add_u64 v[222:223], s[26:27], 0, v[138:139]
	s_mov_b32 m0, s37
	s_nop 0
	global_load_lds_dwordx4 v[222:223], off
	s_waitcnt vmcnt(8)
	s_waitcnt lgkmcnt(0)
	s_barrier
	s_waitcnt lgkmcnt(0)
	v_mfma_f32_16x16x32_bf16 v[120:123], v[128:131], v[178:181], v[120:123]
	v_mfma_f32_16x16x32_bf16 v[124:127], v[146:149], v[178:181], v[124:127]
	v_mfma_f32_16x16x32_bf16 v[104:107], v[128:131], v[186:189], v[104:107]
	v_mfma_f32_16x16x32_bf16 v[108:111], v[146:149], v[186:189], v[108:111]
	v_mfma_f32_16x16x32_bf16 v[88:91], v[128:131], v[194:197], v[88:91]
	v_mfma_f32_16x16x32_bf16 v[92:95], v[146:149], v[194:197], v[92:95]
	v_mfma_f32_16x16x32_bf16 v[72:75], v[128:131], v[202:205], v[72:75]
	v_mfma_f32_16x16x32_bf16 v[76:79], v[146:149], v[202:205], v[76:79]
	v_mfma_f32_16x16x32_bf16 v[120:123], v[132:135], v[182:185], v[120:123]
	v_mfma_f32_16x16x32_bf16 v[124:127], v[154:157], v[182:185], v[124:127]
	v_mfma_f32_16x16x32_bf16 v[104:107], v[132:135], v[190:193], v[104:107]
	v_mfma_f32_16x16x32_bf16 v[108:111], v[154:157], v[190:193], v[108:111]
	v_mfma_f32_16x16x32_bf16 v[88:91], v[132:135], v[198:201], v[88:91]
	v_mfma_f32_16x16x32_bf16 v[92:95], v[154:157], v[198:201], v[92:95]
	v_mfma_f32_16x16x32_bf16 v[72:75], v[132:135], v[212:215], v[72:75]
	v_mfma_f32_16x16x32_bf16 v[76:79], v[154:157], v[212:215], v[76:79]
	v_mfma_f32_16x16x32_bf16 v[112:115], v[158:161], v[178:181], v[112:115]
	v_mfma_f32_16x16x32_bf16 v[116:119], v[170:173], v[178:181], v[116:119]
	v_mfma_f32_16x16x32_bf16 v[96:99], v[158:161], v[186:189], v[96:99]
	v_mfma_f32_16x16x32_bf16 v[100:103], v[170:173], v[186:189], v[100:103]
	v_mfma_f32_16x16x32_bf16 v[80:83], v[158:161], v[194:197], v[80:83]
	v_mfma_f32_16x16x32_bf16 v[84:87], v[170:173], v[194:197], v[84:87]
	v_mfma_f32_16x16x32_bf16 v[64:67], v[158:161], v[202:205], v[64:67]
	v_mfma_f32_16x16x32_bf16 v[68:71], v[170:173], v[202:205], v[68:71]
	v_mfma_f32_16x16x32_bf16 v[112:115], v[162:165], v[182:185], v[112:115]
	v_mfma_f32_16x16x32_bf16 v[116:119], v[174:177], v[182:185], v[116:119]
	v_mfma_f32_16x16x32_bf16 v[96:99], v[162:165], v[190:193], v[96:99]
	v_mfma_f32_16x16x32_bf16 v[100:103], v[174:177], v[190:193], v[100:103]
	v_mfma_f32_16x16x32_bf16 v[80:83], v[162:165], v[198:201], v[80:83]
	v_mfma_f32_16x16x32_bf16 v[84:87], v[174:177], v[198:201], v[84:87]
	v_mfma_f32_16x16x32_bf16 v[64:67], v[162:165], v[212:215], v[64:67]
	v_mfma_f32_16x16x32_bf16 v[68:71], v[174:177], v[212:215], v[68:71]
	s_barrier
	s_add_i32 s26, s45, s34
	v_lshl_add_u64 v[166:167], v[166:167], 0, s[74:75]
	s_mov_b32 m0, s26
	ds_read_b128 v[178:181], v153 offset:49152
	ds_read_b128 v[182:185], v153 offset:50176
	ds_read_b128 v[186:189], v153 offset:51200
	ds_read_b128 v[190:193], v153 offset:52224
	ds_read_b128 v[194:197], v153 offset:53248
	ds_read_b128 v[198:201], v153 offset:54272
	ds_read_b128 v[202:205], v153 offset:55296
	ds_read_b128 v[212:215], v153 offset:56320
	global_load_lds_dwordx4 v[166:167], off
	s_add_i32 m0, s26, 0x2000
	s_add_u32 s24, s24, 0x40080
	v_lshl_add_u64 v[166:167], v[216:217], 0, s[74:75]
	s_addc_u32 s25, s25, 0
	s_add_i32 s26, s46, s34
	global_load_lds_dwordx4 v[166:167], off
	v_lshl_add_u64 v[166:167], s[24:25], 0, v[168:169]
	s_mov_b32 m0, s26
	s_nop 0
	global_load_lds_dwordx4 v[166:167], off
	v_lshl_add_u64 v[166:167], s[24:25], 0, v[140:141]
	s_add_i32 m0, s26, 0x2000
	s_nop 0
	global_load_lds_dwordx4 v[166:167], off
	v_lshl_add_u64 v[166:167], v[218:219], 0, s[74:75]
	s_mov_b32 m0, s38
	s_nop 0
	global_load_lds_dwordx4 v[166:167], off
	v_lshl_add_u64 v[166:167], v[220:221], 0, s[74:75]
	s_mov_b32 m0, s39
	s_nop 0
	global_load_lds_dwordx4 v[166:167], off
	s_waitcnt vmcnt(8)
	s_waitcnt lgkmcnt(0)
	s_barrier
	s_waitcnt lgkmcnt(0)
	v_mfma_f32_16x16x32_bf16 v[56:59], v[128:131], v[178:181], v[56:59]
	v_mfma_f32_16x16x32_bf16 v[60:63], v[146:149], v[178:181], v[60:63]
	v_mfma_f32_16x16x32_bf16 v[40:43], v[128:131], v[186:189], v[40:43]
	v_mfma_f32_16x16x32_bf16 v[44:47], v[146:149], v[186:189], v[44:47]
	v_mfma_f32_16x16x32_bf16 v[24:27], v[128:131], v[194:197], v[24:27]
	v_mfma_f32_16x16x32_bf16 v[28:31], v[146:149], v[194:197], v[28:31]
	v_mfma_f32_16x16x32_bf16 v[8:11], v[128:131], v[202:205], v[8:11]
	v_mfma_f32_16x16x32_bf16 v[12:15], v[146:149], v[202:205], v[12:15]
	v_mfma_f32_16x16x32_bf16 v[56:59], v[132:135], v[182:185], v[56:59]
	v_mfma_f32_16x16x32_bf16 v[60:63], v[154:157], v[182:185], v[60:63]
	v_mfma_f32_16x16x32_bf16 v[40:43], v[132:135], v[190:193], v[40:43]
	v_mfma_f32_16x16x32_bf16 v[44:47], v[154:157], v[190:193], v[44:47]
	v_mfma_f32_16x16x32_bf16 v[24:27], v[132:135], v[198:201], v[24:27]
	v_mfma_f32_16x16x32_bf16 v[28:31], v[154:157], v[198:201], v[28:31]
	v_mfma_f32_16x16x32_bf16 v[8:11], v[132:135], v[212:215], v[8:11]
	v_mfma_f32_16x16x32_bf16 v[12:15], v[154:157], v[212:215], v[12:15]
	v_mfma_f32_16x16x32_bf16 v[48:51], v[158:161], v[178:181], v[48:51]
	v_mfma_f32_16x16x32_bf16 v[52:55], v[170:173], v[178:181], v[52:55]
	v_mfma_f32_16x16x32_bf16 v[32:35], v[158:161], v[186:189], v[32:35]
	v_mfma_f32_16x16x32_bf16 v[36:39], v[170:173], v[186:189], v[36:39]
	v_mfma_f32_16x16x32_bf16 v[16:19], v[158:161], v[194:197], v[16:19]
	v_mfma_f32_16x16x32_bf16 v[20:23], v[170:173], v[194:197], v[20:23]
	v_mfma_f32_16x16x32_bf16 v[0:3], v[158:161], v[202:205], v[0:3]
	v_mfma_f32_16x16x32_bf16 v[4:7], v[170:173], v[202:205], v[4:7]
	v_mfma_f32_16x16x32_bf16 v[48:51], v[162:165], v[182:185], v[48:51]
	v_mfma_f32_16x16x32_bf16 v[52:55], v[174:177], v[182:185], v[52:55]
	v_mfma_f32_16x16x32_bf16 v[32:35], v[162:165], v[190:193], v[32:35]
	v_mfma_f32_16x16x32_bf16 v[36:39], v[174:177], v[190:193], v[36:39]
	v_mfma_f32_16x16x32_bf16 v[16:19], v[162:165], v[198:201], v[16:19]
	v_mfma_f32_16x16x32_bf16 v[20:23], v[174:177], v[198:201], v[20:23]
	v_mfma_f32_16x16x32_bf16 v[0:3], v[162:165], v[212:215], v[0:3]
	v_mfma_f32_16x16x32_bf16 v[4:7], v[174:177], v[212:215], v[4:7]
	s_barrier
	s_add_i32 s44, s44, 2
	s_add_u32 s42, s42, 0x100
	s_addc_u32 s43, s43, 0
	s_add_u32 s0, s0, 0x100
	s_addc_u32 s1, s1, 0
	s_cmp_gt_u32 s44, 13
	s_cbranch_scc0 .LBB0_232
	s_and_b64 vcc, exec, s[12:13]
	s_cbranch_vccz .LBB0_235
	s_barrier

.LBB0_554:
	s_add_i32 s36, 0, 0x10000
	v_add_u32_e32 v13, s36, v12
	ds_read_b128 v[14:17], v13
	ds_read_b128 v[18:21], v13 offset:1024
	ds_read_b128 v[22:25], v13 offset:2048
	ds_read_b128 v[26:29], v13 offset:3072
	s_add_u32 s34, s10, 0x40080
	s_addc_u32 s35, s11, 0
	s_add_i32 s39, s20, 0xc000
	v_lshl_add_u64 v[10:11], s[34:35], 0, v[2:3]
	s_mov_b32 m0, s39
	s_add_i32 s3, s20, 0xe000
	ds_read_b128 v[30:33], v9
	ds_read_b128 v[34:37], v9 offset:1024
	ds_read_b128 v[38:41], v9 offset:2048
	ds_read_b128 v[42:45], v9 offset:3072
	ds_read_b128 v[46:49], v9 offset:4096
	ds_read_b128 v[50:53], v9 offset:5120
	ds_read_b128 v[54:57], v9 offset:6144
	ds_read_b128 v[58:61], v9 offset:7168
	global_load_lds_dwordx4 v[10:11], off
	v_lshl_add_u64 v[10:11], s[34:35], 0, v[0:1]
	s_mov_b32 m0, s3
	s_nop 0
	global_load_lds_dwordx4 v[10:11], off
	s_waitcnt lgkmcnt(8)
	s_barrier
	s_waitcnt lgkmcnt(0)
	s_waitcnt lgkmcnt(0)
	v_mfma_f32_16x16x32_bf16 v[62:65], v[14:17], v[30:33], 0
	v_mfma_f32_16x16x32_bf16 v[66:69], v[22:25], v[30:33], 0
	v_mfma_f32_16x16x32_bf16 v[70:73], v[14:17], v[38:41], 0
	v_mfma_f32_16x16x32_bf16 v[74:77], v[22:25], v[38:41], 0
	v_mfma_f32_16x16x32_bf16 v[78:81], v[14:17], v[46:49], 0
	v_mfma_f32_16x16x32_bf16 v[82:85], v[22:25], v[46:49], 0
	v_mfma_f32_16x16x32_bf16 v[86:89], v[14:17], v[54:57], 0
	v_mfma_f32_16x16x32_bf16 v[90:93], v[22:25], v[54:57], 0
	v_mfma_f32_16x16x32_bf16 v[62:65], v[18:21], v[34:37], v[62:65]
	v_mfma_f32_16x16x32_bf16 v[66:69], v[26:29], v[34:37], v[66:69]
	v_mfma_f32_16x16x32_bf16 v[70:73], v[18:21], v[42:45], v[70:73]
	v_mfma_f32_16x16x32_bf16 v[74:77], v[26:29], v[42:45], v[74:77]
	v_mfma_f32_16x16x32_bf16 v[78:81], v[18:21], v[50:53], v[78:81]
	v_mfma_f32_16x16x32_bf16 v[82:85], v[26:29], v[50:53], v[82:85]
	v_mfma_f32_16x16x32_bf16 v[86:89], v[18:21], v[58:61], v[86:89]
	v_mfma_f32_16x16x32_bf16 v[90:93], v[26:29], v[58:61], v[90:93]
	s_barrier
	s_add_i32 s37, 0, 0x14000
	v_lshl_add_u64 v[10:11], s[12:13], 0, v[2:3]
	s_mov_b64 s[40:41], 0x100
	s_add_i32 s36, s36, s17
	v_add_u32_e32 v168, s37, v12
	v_lshl_add_u64 v[110:111], v[10:11], 0, s[40:41]
	s_mov_b32 m0, s36
	v_lshl_add_u64 v[166:167], s[12:13], 0, v[0:1]
	s_add_i32 s34, s36, 0x2000
	ds_read_b128 v[94:97], v168
	ds_read_b128 v[98:101], v168 offset:1024
	ds_read_b128 v[102:105], v168 offset:2048
	ds_read_b128 v[106:109], v168 offset:3072
	global_load_lds_dwordx4 v[110:111], off
	v_lshl_add_u64 v[110:111], v[166:167], 0, s[40:41]
	s_mov_b32 m0, s34
	s_nop 0
	global_load_lds_dwordx4 v[110:111], off
	s_barrier
	s_waitcnt lgkmcnt(0)
	s_waitcnt lgkmcnt(0)
	v_mfma_f32_16x16x32_bf16 v[110:113], v[94:97], v[30:33], 0
	v_mfma_f32_16x16x32_bf16 v[30:33], v[102:105], v[30:33], 0
	v_mfma_f32_16x16x32_bf16 v[110:113], v[98:101], v[34:37], v[110:113]
	v_mfma_f32_16x16x32_bf16 v[30:33], v[106:109], v[34:37], v[30:33]
	v_mfma_f32_16x16x32_bf16 v[34:37], v[94:97], v[38:41], 0
	v_mfma_f32_16x16x32_bf16 v[38:41], v[102:105], v[38:41], 0
	v_mfma_f32_16x16x32_bf16 v[34:37], v[98:101], v[42:45], v[34:37]
	v_mfma_f32_16x16x32_bf16 v[38:41], v[106:109], v[42:45], v[38:41]
	v_mfma_f32_16x16x32_bf16 v[42:45], v[94:97], v[46:49], 0
	v_mfma_f32_16x16x32_bf16 v[46:49], v[102:105], v[46:49], 0
	v_mfma_f32_16x16x32_bf16 v[42:45], v[98:101], v[50:53], v[42:45]
	v_mfma_f32_16x16x32_bf16 v[46:49], v[106:109], v[50:53], v[46:49]
	v_mfma_f32_16x16x32_bf16 v[50:53], v[94:97], v[54:57], 0
	v_mfma_f32_16x16x32_bf16 v[54:57], v[102:105], v[54:57], 0
	v_mfma_f32_16x16x32_bf16 v[50:53], v[98:101], v[58:61], v[50:53]
	v_mfma_f32_16x16x32_bf16 v[54:57], v[106:109], v[58:61], v[54:57]
	v_lshl_add_u64 v[216:217], s[10:11], 0, v[2:3]
	s_mov_b32 m0, s20
	v_lshl_add_u64 v[142:143], v[216:217], 0, s[40:41]
	v_lshl_add_u64 v[218:219], s[10:11], 0, v[0:1]
	s_barrier
	ds_read_b128 v[58:61], v9 offset:16384
	ds_read_b128 v[114:117], v9 offset:17408
	ds_read_b128 v[118:121], v9 offset:18432
	ds_read_b128 v[122:125], v9 offset:19456
	ds_read_b128 v[126:129], v9 offset:20480
	ds_read_b128 v[130:133], v9 offset:21504
	ds_read_b128 v[134:137], v9 offset:22528
	ds_read_b128 v[138:141], v9 offset:23552
	global_load_lds_dwordx4 v[142:143], off
	v_lshl_add_u64 v[142:143], v[218:219], 0, s[40:41]
	s_mov_b32 m0, s21
	s_nop 0
	global_load_lds_dwordx4 v[142:143], off
	s_barrier
	s_waitcnt lgkmcnt(0)
	s_waitcnt lgkmcnt(0)
	v_mfma_f32_16x16x32_bf16 v[142:145], v[14:17], v[58:61], 0
	v_mfma_f32_16x16x32_bf16 v[150:153], v[14:17], v[118:121], 0
	v_mfma_f32_16x16x32_bf16 v[158:161], v[14:17], v[126:129], 0
	v_mfma_f32_16x16x32_bf16 v[14:17], v[14:17], v[134:137], 0
	v_mfma_f32_16x16x32_bf16 v[142:145], v[18:21], v[114:117], v[142:145]
	v_mfma_f32_16x16x32_bf16 v[146:149], v[22:25], v[58:61], 0
	v_mfma_f32_16x16x32_bf16 v[150:153], v[18:21], v[122:125], v[150:153]
	v_mfma_f32_16x16x32_bf16 v[154:157], v[22:25], v[118:121], 0
	v_mfma_f32_16x16x32_bf16 v[158:161], v[18:21], v[130:133], v[158:161]
	v_mfma_f32_16x16x32_bf16 v[162:165], v[22:25], v[126:129], 0
	v_mfma_f32_16x16x32_bf16 v[14:17], v[18:21], v[138:141], v[14:17]
	v_mfma_f32_16x16x32_bf16 v[18:21], v[22:25], v[134:137], 0
	v_mfma_f32_16x16x32_bf16 v[146:149], v[26:29], v[114:117], v[146:149]
	v_mfma_f32_16x16x32_bf16 v[154:157], v[26:29], v[122:125], v[154:157]
	v_mfma_f32_16x16x32_bf16 v[162:165], v[26:29], v[130:133], v[162:165]
	v_mfma_f32_16x16x32_bf16 v[18:21], v[26:29], v[138:141], v[18:21]
	s_barrier
	s_add_u32 s40, s12, 0x40100
	s_addc_u32 s41, s13, 0
	s_add_i32 s37, s37, s17
	v_lshl_add_u64 v[22:23], s[40:41], 0, v[2:3]
	s_mov_b32 m0, s37
	s_add_i32 s35, s37, 0x2000
	global_load_lds_dwordx4 v[22:23], off
	v_lshl_add_u64 v[22:23], s[40:41], 0, v[0:1]
	s_mov_b32 m0, s35
	s_nop 0
	global_load_lds_dwordx4 v[22:23], off
	s_waitcnt vmcnt(6)
	s_barrier
	v_mfma_f32_16x16x32_bf16 v[22:25], v[94:97], v[58:61], 0
	v_mfma_f32_16x16x32_bf16 v[26:29], v[102:105], v[58:61], 0
	v_mfma_f32_16x16x32_bf16 v[22:25], v[98:101], v[114:117], v[22:25]
	v_mfma_f32_16x16x32_bf16 v[26:29], v[106:109], v[114:117], v[26:29]
	v_mfma_f32_16x16x32_bf16 v[58:61], v[94:97], v[118:121], 0
	v_mfma_f32_16x16x32_bf16 v[114:117], v[102:105], v[118:121], 0
	v_mfma_f32_16x16x32_bf16 v[118:121], v[94:97], v[126:129], 0
	v_mfma_f32_16x16x32_bf16 v[94:97], v[94:97], v[134:137], 0
	v_mfma_f32_16x16x32_bf16 v[58:61], v[98:101], v[122:125], v[58:61]
	v_mfma_f32_16x16x32_bf16 v[114:117], v[106:109], v[122:125], v[114:117]
	v_mfma_f32_16x16x32_bf16 v[118:121], v[98:101], v[130:133], v[118:121]
	v_mfma_f32_16x16x32_bf16 v[122:125], v[102:105], v[126:129], 0
	v_mfma_f32_16x16x32_bf16 v[94:97], v[98:101], v[138:141], v[94:97]
	v_mfma_f32_16x16x32_bf16 v[98:101], v[102:105], v[134:137], 0
	v_mfma_f32_16x16x32_bf16 v[122:125], v[106:109], v[130:133], v[122:125]
	v_mfma_f32_16x16x32_bf16 v[98:101], v[106:109], v[138:141], v[98:101]
	s_add_i32 s38, 0, 0x18000
	v_add_u32_e32 v211, s38, v12
	s_barrier
	ds_read_b128 v[102:105], v211
	ds_read_b128 v[106:109], v211 offset:1024
	ds_read_b128 v[126:129], v211 offset:2048
	ds_read_b128 v[130:133], v211 offset:3072
	s_add_u32 s40, s10, 0x40100
	s_addc_u32 s41, s11, 0
	s_mov_b32 m0, s22
	v_lshl_add_u64 v[194:195], s[40:41], 0, v[2:3]
	ds_read_b128 v[134:137], v9 offset:32768
	ds_read_b128 v[138:141], v9 offset:33792
	ds_read_b128 v[170:173], v9 offset:34816
	ds_read_b128 v[174:177], v9 offset:35840
	ds_read_b128 v[178:181], v9 offset:36864
	ds_read_b128 v[182:185], v9 offset:37888
	ds_read_b128 v[186:189], v9 offset:38912
	ds_read_b128 v[190:193], v9 offset:39936
	global_load_lds_dwordx4 v[194:195], off
	v_lshl_add_u64 v[194:195], s[40:41], 0, v[0:1]
	s_mov_b32 m0, s23
	s_nop 0
	global_load_lds_dwordx4 v[194:195], off
	s_waitcnt lgkmcnt(8)
	s_barrier
	s_waitcnt lgkmcnt(0)
	s_waitcnt lgkmcnt(0)
	v_mfma_f32_16x16x32_bf16 v[62:65], v[102:105], v[134:137], v[62:65]
	v_mfma_f32_16x16x32_bf16 v[66:69], v[126:129], v[134:137], v[66:69]
	v_mfma_f32_16x16x32_bf16 v[70:73], v[102:105], v[170:173], v[70:73]
	v_mfma_f32_16x16x32_bf16 v[74:77], v[126:129], v[170:173], v[74:77]
	v_mfma_f32_16x16x32_bf16 v[78:81], v[102:105], v[178:181], v[78:81]
	v_mfma_f32_16x16x32_bf16 v[82:85], v[126:129], v[178:181], v[82:85]
	v_mfma_f32_16x16x32_bf16 v[86:89], v[102:105], v[186:189], v[86:89]
	v_mfma_f32_16x16x32_bf16 v[90:93], v[126:129], v[186:189], v[90:93]
	v_mfma_f32_16x16x32_bf16 v[62:65], v[106:109], v[138:141], v[62:65]
	v_mfma_f32_16x16x32_bf16 v[66:69], v[130:133], v[138:141], v[66:69]
	v_mfma_f32_16x16x32_bf16 v[70:73], v[106:109], v[174:177], v[70:73]
	v_mfma_f32_16x16x32_bf16 v[74:77], v[130:133], v[174:177], v[74:77]
	v_mfma_f32_16x16x32_bf16 v[78:81], v[106:109], v[182:185], v[78:81]
	v_mfma_f32_16x16x32_bf16 v[82:85], v[130:133], v[182:185], v[82:85]
	v_mfma_f32_16x16x32_bf16 v[86:89], v[106:109], v[190:193], v[86:89]
	v_mfma_f32_16x16x32_bf16 v[90:93], v[130:133], v[190:193], v[90:93]
	s_barrier
	s_add_i32 s41, 0, 0x1c000
	s_mov_b64 s[42:43], 0x180
	s_add_i32 s40, s38, s17
	v_add_u32_e32 v220, s41, v12
	v_lshl_add_u64 v[10:11], v[10:11], 0, s[42:43]
	s_mov_b32 m0, s40
	s_add_i32 s38, s40, 0x2000
	ds_read_b128 v[194:197], v220
	ds_read_b128 v[198:201], v220 offset:1024
	ds_read_b128 v[202:205], v220 offset:2048
	ds_read_b128 v[212:215], v220 offset:3072
	global_load_lds_dwordx4 v[10:11], off
	v_lshl_add_u64 v[10:11], v[166:167], 0, s[42:43]
	s_mov_b32 m0, s38
	s_nop 0
	global_load_lds_dwordx4 v[10:11], off
	s_barrier
	s_waitcnt lgkmcnt(0)
	s_waitcnt lgkmcnt(0)
	v_mfma_f32_16x16x32_bf16 v[110:113], v[194:197], v[134:137], v[110:113]
	v_mfma_f32_16x16x32_bf16 v[30:33], v[202:205], v[134:137], v[30:33]
	v_mfma_f32_16x16x32_bf16 v[34:37], v[194:197], v[170:173], v[34:37]
	v_mfma_f32_16x16x32_bf16 v[38:41], v[202:205], v[170:173], v[38:41]
	v_mfma_f32_16x16x32_bf16 v[42:45], v[194:197], v[178:181], v[42:45]
	v_mfma_f32_16x16x32_bf16 v[46:49], v[202:205], v[178:181], v[46:49]
	v_mfma_f32_16x16x32_bf16 v[50:53], v[194:197], v[186:189], v[50:53]
	v_mfma_f32_16x16x32_bf16 v[54:57], v[202:205], v[186:189], v[54:57]
	v_mfma_f32_16x16x32_bf16 v[110:113], v[198:201], v[138:141], v[110:113]
	v_mfma_f32_16x16x32_bf16 v[30:33], v[212:215], v[138:141], v[30:33]
	v_mfma_f32_16x16x32_bf16 v[34:37], v[198:201], v[174:177], v[34:37]
	v_mfma_f32_16x16x32_bf16 v[38:41], v[212:215], v[174:177], v[38:41]
	v_mfma_f32_16x16x32_bf16 v[42:45], v[198:201], v[182:185], v[42:45]
	v_mfma_f32_16x16x32_bf16 v[46:49], v[212:215], v[182:185], v[46:49]
	v_mfma_f32_16x16x32_bf16 v[50:53], v[198:201], v[190:193], v[50:53]
	v_mfma_f32_16x16x32_bf16 v[54:57], v[212:215], v[190:193], v[54:57]
	s_mov_b32 m0, s26
	v_lshl_add_u64 v[10:11], v[216:217], 0, s[42:43]
	s_barrier
	ds_read_b128 v[134:137], v9 offset:49152
	ds_read_b128 v[138:141], v9 offset:50176
	ds_read_b128 v[170:173], v9 offset:51200
	ds_read_b128 v[174:177], v9 offset:52224
	ds_read_b128 v[178:181], v9 offset:53248
	ds_read_b128 v[182:185], v9 offset:54272
	ds_read_b128 v[186:189], v9 offset:55296
	ds_read_b128 v[190:193], v9 offset:56320
	global_load_lds_dwordx4 v[10:11], off
	v_lshl_add_u64 v[10:11], v[218:219], 0, s[42:43]
	s_mov_b32 m0, s27
	s_nop 0
	global_load_lds_dwordx4 v[10:11], off
	s_barrier
	s_waitcnt lgkmcnt(0)
	s_waitcnt lgkmcnt(0)
	v_mfma_f32_16x16x32_bf16 v[142:145], v[102:105], v[134:137], v[142:145]
	v_mfma_f32_16x16x32_bf16 v[146:149], v[126:129], v[134:137], v[146:149]
	v_mfma_f32_16x16x32_bf16 v[150:153], v[102:105], v[170:173], v[150:153]
	v_mfma_f32_16x16x32_bf16 v[154:157], v[126:129], v[170:173], v[154:157]
	v_mfma_f32_16x16x32_bf16 v[158:161], v[102:105], v[178:181], v[158:161]
	v_mfma_f32_16x16x32_bf16 v[162:165], v[126:129], v[178:181], v[162:165]
	v_mfma_f32_16x16x32_bf16 v[14:17], v[102:105], v[186:189], v[14:17]
	v_mfma_f32_16x16x32_bf16 v[18:21], v[126:129], v[186:189], v[18:21]
	v_mfma_f32_16x16x32_bf16 v[142:145], v[106:109], v[138:141], v[142:145]
	v_mfma_f32_16x16x32_bf16 v[146:149], v[130:133], v[138:141], v[146:149]
	v_mfma_f32_16x16x32_bf16 v[150:153], v[106:109], v[174:177], v[150:153]
	v_mfma_f32_16x16x32_bf16 v[154:157], v[130:133], v[174:177], v[154:157]
	v_mfma_f32_16x16x32_bf16 v[158:161], v[106:109], v[182:185], v[158:161]
	v_mfma_f32_16x16x32_bf16 v[162:165], v[130:133], v[182:185], v[162:165]
	v_mfma_f32_16x16x32_bf16 v[14:17], v[106:109], v[190:193], v[14:17]
	v_mfma_f32_16x16x32_bf16 v[18:21], v[130:133], v[190:193], v[18:21]
	s_barrier
	s_add_u32 s42, s12, 0x40180
	s_addc_u32 s43, s13, 0
	s_add_i32 s13, s41, s17
	v_lshl_add_u64 v[10:11], s[42:43], 0, v[2:3]
	s_mov_b32 m0, s13
	s_add_i32 s12, s13, 0x2000
	global_load_lds_dwordx4 v[10:11], off
	v_lshl_add_u64 v[10:11], s[42:43], 0, v[0:1]
	s_mov_b32 m0, s12
	s_nop 0
	global_load_lds_dwordx4 v[10:11], off
	s_waitcnt vmcnt(6)
	s_barrier
	v_mfma_f32_16x16x32_bf16 v[22:25], v[194:197], v[134:137], v[22:25]
	v_mfma_f32_16x16x32_bf16 v[26:29], v[202:205], v[134:137], v[26:29]
	v_mfma_f32_16x16x32_bf16 v[58:61], v[194:197], v[170:173], v[58:61]
	v_mfma_f32_16x16x32_bf16 v[102:105], v[202:205], v[170:173], v[114:117]
	v_mfma_f32_16x16x32_bf16 v[106:109], v[194:197], v[178:181], v[118:121]
	v_mfma_f32_16x16x32_bf16 v[114:117], v[202:205], v[178:181], v[122:125]
	v_mfma_f32_16x16x32_bf16 v[94:97], v[194:197], v[186:189], v[94:97]
	v_mfma_f32_16x16x32_bf16 v[98:101], v[202:205], v[186:189], v[98:101]
	v_mfma_f32_16x16x32_bf16 v[22:25], v[198:201], v[138:141], v[22:25]
	v_mfma_f32_16x16x32_bf16 v[26:29], v[212:215], v[138:141], v[26:29]
	v_mfma_f32_16x16x32_bf16 v[58:61], v[198:201], v[174:177], v[58:61]
	v_mfma_f32_16x16x32_bf16 v[102:105], v[212:215], v[174:177], v[102:105]
	v_mfma_f32_16x16x32_bf16 v[106:109], v[198:201], v[182:185], v[106:109]
	v_mfma_f32_16x16x32_bf16 v[114:117], v[212:215], v[182:185], v[114:117]
	v_mfma_f32_16x16x32_bf16 v[94:97], v[198:201], v[190:193], v[94:97]
	v_mfma_f32_16x16x32_bf16 v[98:101], v[212:215], v[190:193], v[98:101]
	s_barrier
	ds_read_b128 v[118:121], v13
	ds_read_b128 v[122:125], v13 offset:1024
	ds_read_b128 v[126:129], v13 offset:2048
	ds_read_b128 v[130:133], v13 offset:3072
	s_add_u32 s10, s10, 0x40180
	s_addc_u32 s11, s11, 0
	s_mov_b32 m0, s39
	v_lshl_add_u64 v[10:11], s[10:11], 0, v[2:3]
	ds_read_b128 v[134:137], v9
	ds_read_b128 v[138:141], v9 offset:1024
	ds_read_b128 v[170:173], v9 offset:2048
	ds_read_b128 v[174:177], v9 offset:3072
	ds_read_b128 v[178:181], v9 offset:4096
	ds_read_b128 v[182:185], v9 offset:5120
	ds_read_b128 v[186:189], v9 offset:6144
	ds_read_b128 v[190:193], v9 offset:7168
	global_load_lds_dwordx4 v[10:11], off
	v_lshl_add_u64 v[10:11], s[10:11], 0, v[0:1]
	s_mov_b32 m0, s3
	s_nop 0
	global_load_lds_dwordx4 v[10:11], off
	s_waitcnt lgkmcnt(8)
	s_barrier
	s_waitcnt lgkmcnt(0)
	s_waitcnt lgkmcnt(0)
	v_mfma_f32_16x16x32_bf16 v[62:65], v[118:121], v[134:137], v[62:65]
	v_mfma_f32_16x16x32_bf16 v[66:69], v[126:129], v[134:137], v[66:69]
	v_mfma_f32_16x16x32_bf16 v[70:73], v[118:121], v[170:173], v[70:73]
	v_mfma_f32_16x16x32_bf16 v[74:77], v[126:129], v[170:173], v[74:77]
	v_mfma_f32_16x16x32_bf16 v[78:81], v[118:121], v[178:181], v[78:81]
	v_mfma_f32_16x16x32_bf16 v[82:85], v[126:129], v[178:181], v[82:85]
	v_mfma_f32_16x16x32_bf16 v[86:89], v[118:121], v[186:189], v[86:89]
	v_mfma_f32_16x16x32_bf16 v[90:93], v[126:129], v[186:189], v[90:93]
	v_mfma_f32_16x16x32_bf16 v[62:65], v[122:125], v[138:141], v[62:65]
	v_mfma_f32_16x16x32_bf16 v[66:69], v[130:133], v[138:141], v[66:69]
	v_mfma_f32_16x16x32_bf16 v[70:73], v[122:125], v[174:177], v[70:73]
	v_mfma_f32_16x16x32_bf16 v[74:77], v[130:133], v[174:177], v[74:77]
	v_mfma_f32_16x16x32_bf16 v[78:81], v[122:125], v[182:185], v[78:81]
	v_mfma_f32_16x16x32_bf16 v[82:85], v[130:133], v[182:185], v[82:85]
	v_mfma_f32_16x16x32_bf16 v[86:89], v[122:125], v[190:193], v[86:89]
	v_mfma_f32_16x16x32_bf16 v[90:93], v[130:133], v[190:193], v[90:93]
	s_barrier
	s_mov_b32 m0, s36
	v_lshl_add_u64 v[10:11], s[6:7], 0, v[2:3]
	ds_read_b128 v[194:197], v168
	ds_read_b128 v[198:201], v168 offset:1024
	ds_read_b128 v[202:205], v168 offset:2048
	ds_read_b128 v[212:215], v168 offset:3072
	global_load_lds_dwordx4 v[10:11], off
	v_lshl_add_u64 v[166:167], s[6:7], 0, v[0:1]
	s_mov_b32 m0, s34
	s_nop 0
	global_load_lds_dwordx4 v[166:167], off
	s_barrier
	s_waitcnt lgkmcnt(0)
	s_waitcnt lgkmcnt(0)
	v_mfma_f32_16x16x32_bf16 v[110:113], v[194:197], v[134:137], v[110:113]
	v_mfma_f32_16x16x32_bf16 v[30:33], v[202:205], v[134:137], v[30:33]
	v_mfma_f32_16x16x32_bf16 v[34:37], v[194:197], v[170:173], v[34:37]
	v_mfma_f32_16x16x32_bf16 v[38:41], v[202:205], v[170:173], v[38:41]
	v_mfma_f32_16x16x32_bf16 v[42:45], v[194:197], v[178:181], v[42:45]
	v_mfma_f32_16x16x32_bf16 v[46:49], v[202:205], v[178:181], v[46:49]
	v_mfma_f32_16x16x32_bf16 v[50:53], v[194:197], v[186:189], v[50:53]
	v_mfma_f32_16x16x32_bf16 v[54:57], v[202:205], v[186:189], v[54:57]
	v_mfma_f32_16x16x32_bf16 v[110:113], v[198:201], v[138:141], v[110:113]
	v_mfma_f32_16x16x32_bf16 v[30:33], v[212:215], v[138:141], v[30:33]
	v_mfma_f32_16x16x32_bf16 v[34:37], v[198:201], v[174:177], v[34:37]
	v_mfma_f32_16x16x32_bf16 v[38:41], v[212:215], v[174:177], v[38:41]
	v_mfma_f32_16x16x32_bf16 v[42:45], v[198:201], v[182:185], v[42:45]
	v_mfma_f32_16x16x32_bf16 v[46:49], v[212:215], v[182:185], v[46:49]
	v_mfma_f32_16x16x32_bf16 v[50:53], v[198:201], v[190:193], v[50:53]
	v_mfma_f32_16x16x32_bf16 v[54:57], v[212:215], v[190:193], v[54:57]
	s_mov_b32 m0, s20
	v_lshl_add_u64 v[216:217], s[0:1], 0, v[2:3]
	s_barrier
	ds_read_b128 v[134:137], v9 offset:16384
	ds_read_b128 v[138:141], v9 offset:17408
	ds_read_b128 v[170:173], v9 offset:18432
	ds_read_b128 v[174:177], v9 offset:19456
	ds_read_b128 v[178:181], v9 offset:20480
	ds_read_b128 v[182:185], v9 offset:21504
	ds_read_b128 v[186:189], v9 offset:22528
	ds_read_b128 v[190:193], v9 offset:23552
	global_load_lds_dwordx4 v[216:217], off
	v_lshl_add_u64 v[218:219], s[0:1], 0, v[0:1]
	s_mov_b32 m0, s21
	s_nop 0
	global_load_lds_dwordx4 v[218:219], off
	s_barrier
	s_waitcnt lgkmcnt(0)
	s_waitcnt lgkmcnt(0)
	v_mfma_f32_16x16x32_bf16 v[142:145], v[118:121], v[134:137], v[142:145]
	v_mfma_f32_16x16x32_bf16 v[146:149], v[126:129], v[134:137], v[146:149]
	v_mfma_f32_16x16x32_bf16 v[150:153], v[118:121], v[170:173], v[150:153]
	v_mfma_f32_16x16x32_bf16 v[154:157], v[126:129], v[170:173], v[154:157]
	v_mfma_f32_16x16x32_bf16 v[158:161], v[118:121], v[178:181], v[158:161]
	v_mfma_f32_16x16x32_bf16 v[162:165], v[126:129], v[178:181], v[162:165]
	v_mfma_f32_16x16x32_bf16 v[14:17], v[118:121], v[186:189], v[14:17]
	v_mfma_f32_16x16x32_bf16 v[18:21], v[126:129], v[186:189], v[18:21]
	v_mfma_f32_16x16x32_bf16 v[142:145], v[122:125], v[138:141], v[142:145]
	v_mfma_f32_16x16x32_bf16 v[146:149], v[130:133], v[138:141], v[146:149]
	v_mfma_f32_16x16x32_bf16 v[150:153], v[122:125], v[174:177], v[150:153]
	v_mfma_f32_16x16x32_bf16 v[154:157], v[130:133], v[174:177], v[154:157]
	v_mfma_f32_16x16x32_bf16 v[158:161], v[122:125], v[182:185], v[158:161]
	v_mfma_f32_16x16x32_bf16 v[162:165], v[130:133], v[182:185], v[162:165]
	v_mfma_f32_16x16x32_bf16 v[14:17], v[122:125], v[190:193], v[14:17]
	v_mfma_f32_16x16x32_bf16 v[18:21], v[130:133], v[190:193], v[18:21]
	s_barrier
	s_add_u32 s10, s6, 0x40000
	s_addc_u32 s11, s7, 0
	s_mov_b32 m0, s37
	v_lshl_add_u64 v[118:119], s[10:11], 0, v[2:3]
	global_load_lds_dwordx4 v[118:119], off
	v_lshl_add_u64 v[118:119], s[10:11], 0, v[0:1]
	s_mov_b32 m0, s35
	s_nop 0
	global_load_lds_dwordx4 v[118:119], off
	s_waitcnt vmcnt(6)
	s_barrier
	v_mfma_f32_16x16x32_bf16 v[22:25], v[194:197], v[134:137], v[22:25]
	v_mfma_f32_16x16x32_bf16 v[26:29], v[202:205], v[134:137], v[26:29]
	v_mfma_f32_16x16x32_bf16 v[58:61], v[194:197], v[170:173], v[58:61]
	v_mfma_f32_16x16x32_bf16 v[102:105], v[202:205], v[170:173], v[102:105]
	v_mfma_f32_16x16x32_bf16 v[106:109], v[194:197], v[178:181], v[106:109]
	v_mfma_f32_16x16x32_bf16 v[114:117], v[202:205], v[178:181], v[114:117]
	v_mfma_f32_16x16x32_bf16 v[94:97], v[194:197], v[186:189], v[94:97]
	v_mfma_f32_16x16x32_bf16 v[98:101], v[202:205], v[186:189], v[98:101]
	v_mfma_f32_16x16x32_bf16 v[22:25], v[198:201], v[138:141], v[22:25]
	v_mfma_f32_16x16x32_bf16 v[26:29], v[212:215], v[138:141], v[26:29]
	v_mfma_f32_16x16x32_bf16 v[58:61], v[198:201], v[174:177], v[58:61]
	v_mfma_f32_16x16x32_bf16 v[102:105], v[212:215], v[174:177], v[102:105]
	v_mfma_f32_16x16x32_bf16 v[106:109], v[198:201], v[182:185], v[106:109]
	v_mfma_f32_16x16x32_bf16 v[114:117], v[212:215], v[182:185], v[114:117]
	v_mfma_f32_16x16x32_bf16 v[94:97], v[198:201], v[190:193], v[94:97]
	v_mfma_f32_16x16x32_bf16 v[98:101], v[212:215], v[190:193], v[98:101]
	s_barrier
	ds_read_b128 v[118:121], v211
	ds_read_b128 v[122:125], v211 offset:1024
	ds_read_b128 v[126:129], v211 offset:2048
	ds_read_b128 v[130:133], v211 offset:3072
	s_add_u32 s10, s0, 0x40000
	s_addc_u32 s11, s1, 0
	s_mov_b32 m0, s22
	v_lshl_add_u64 v[194:195], s[10:11], 0, v[2:3]
	ds_read_b128 v[134:137], v9 offset:32768
	ds_read_b128 v[138:141], v9 offset:33792
	ds_read_b128 v[170:173], v9 offset:34816
	ds_read_b128 v[174:177], v9 offset:35840
	ds_read_b128 v[178:181], v9 offset:36864
	ds_read_b128 v[182:185], v9 offset:37888
	ds_read_b128 v[186:189], v9 offset:38912
	ds_read_b128 v[190:193], v9 offset:39936
	global_load_lds_dwordx4 v[194:195], off
	v_lshl_add_u64 v[194:195], s[10:11], 0, v[0:1]
	s_mov_b32 m0, s23
	s_nop 0
	global_load_lds_dwordx4 v[194:195], off
	s_waitcnt lgkmcnt(8)
	s_barrier
	s_waitcnt lgkmcnt(0)
	s_waitcnt lgkmcnt(0)
	v_mfma_f32_16x16x32_bf16 v[62:65], v[118:121], v[134:137], v[62:65]
	v_mfma_f32_16x16x32_bf16 v[66:69], v[126:129], v[134:137], v[66:69]
	v_mfma_f32_16x16x32_bf16 v[70:73], v[118:121], v[170:173], v[70:73]
	v_mfma_f32_16x16x32_bf16 v[74:77], v[126:129], v[170:173], v[74:77]
	v_mfma_f32_16x16x32_bf16 v[78:81], v[118:121], v[178:181], v[78:81]
	v_mfma_f32_16x16x32_bf16 v[82:85], v[126:129], v[178:181], v[82:85]
	v_mfma_f32_16x16x32_bf16 v[86:89], v[118:121], v[186:189], v[86:89]
	v_mfma_f32_16x16x32_bf16 v[90:93], v[126:129], v[186:189], v[90:93]
	v_mfma_f32_16x16x32_bf16 v[62:65], v[122:125], v[138:141], v[62:65]
	v_mfma_f32_16x16x32_bf16 v[66:69], v[130:133], v[138:141], v[66:69]
	v_mfma_f32_16x16x32_bf16 v[70:73], v[122:125], v[174:177], v[70:73]
	v_mfma_f32_16x16x32_bf16 v[74:77], v[130:133], v[174:177], v[74:77]
	v_mfma_f32_16x16x32_bf16 v[78:81], v[122:125], v[182:185], v[78:81]
	v_mfma_f32_16x16x32_bf16 v[82:85], v[130:133], v[182:185], v[82:85]
	v_mfma_f32_16x16x32_bf16 v[86:89], v[122:125], v[190:193], v[86:89]
	v_mfma_f32_16x16x32_bf16 v[90:93], v[130:133], v[190:193], v[90:93]
	s_barrier
	s_mov_b32 m0, s40
	v_lshl_add_u64 v[10:11], v[10:11], 0, s[74:75]
	ds_read_b128 v[194:197], v220
	ds_read_b128 v[198:201], v220 offset:1024
	ds_read_b128 v[202:205], v220 offset:2048
	ds_read_b128 v[212:215], v220 offset:3072
	global_load_lds_dwordx4 v[10:11], off
	v_lshl_add_u64 v[10:11], v[166:167], 0, s[74:75]
	s_mov_b32 m0, s38
	s_nop 0
	global_load_lds_dwordx4 v[10:11], off
	s_barrier
	s_waitcnt lgkmcnt(0)
	s_waitcnt lgkmcnt(0)
	v_mfma_f32_16x16x32_bf16 v[110:113], v[194:197], v[134:137], v[110:113]
	v_mfma_f32_16x16x32_bf16 v[30:33], v[202:205], v[134:137], v[30:33]
	v_mfma_f32_16x16x32_bf16 v[34:37], v[194:197], v[170:173], v[34:37]
	v_mfma_f32_16x16x32_bf16 v[38:41], v[202:205], v[170:173], v[38:41]
	v_mfma_f32_16x16x32_bf16 v[42:45], v[194:197], v[178:181], v[42:45]
	v_mfma_f32_16x16x32_bf16 v[46:49], v[202:205], v[178:181], v[46:49]
	v_mfma_f32_16x16x32_bf16 v[50:53], v[194:197], v[186:189], v[50:53]
	v_mfma_f32_16x16x32_bf16 v[54:57], v[202:205], v[186:189], v[54:57]
	v_mfma_f32_16x16x32_bf16 v[110:113], v[198:201], v[138:141], v[110:113]
	v_mfma_f32_16x16x32_bf16 v[30:33], v[212:215], v[138:141], v[30:33]
	v_mfma_f32_16x16x32_bf16 v[34:37], v[198:201], v[174:177], v[34:37]
	v_mfma_f32_16x16x32_bf16 v[38:41], v[212:215], v[174:177], v[38:41]
	v_mfma_f32_16x16x32_bf16 v[42:45], v[198:201], v[182:185], v[42:45]
	v_mfma_f32_16x16x32_bf16 v[46:49], v[212:215], v[182:185], v[46:49]
	v_mfma_f32_16x16x32_bf16 v[50:53], v[198:201], v[190:193], v[50:53]
	v_mfma_f32_16x16x32_bf16 v[54:57], v[212:215], v[190:193], v[54:57]
	s_mov_b32 m0, s26
	v_lshl_add_u64 v[10:11], v[216:217], 0, s[74:75]
	s_barrier
	ds_read_b128 v[134:137], v9 offset:49152
	ds_read_b128 v[138:141], v9 offset:50176
	ds_read_b128 v[170:173], v9 offset:51200
	ds_read_b128 v[174:177], v9 offset:52224
	ds_read_b128 v[178:181], v9 offset:53248
	ds_read_b128 v[182:185], v9 offset:54272
	ds_read_b128 v[186:189], v9 offset:55296
	ds_read_b128 v[190:193], v9 offset:56320
	global_load_lds_dwordx4 v[10:11], off
	v_lshl_add_u64 v[10:11], v[218:219], 0, s[74:75]
	s_mov_b32 m0, s27
	s_nop 0
	global_load_lds_dwordx4 v[10:11], off
	s_barrier
	s_waitcnt lgkmcnt(0)
	s_waitcnt lgkmcnt(0)
	v_mfma_f32_16x16x32_bf16 v[142:145], v[118:121], v[134:137], v[142:145]
	v_mfma_f32_16x16x32_bf16 v[146:149], v[126:129], v[134:137], v[146:149]
	v_mfma_f32_16x16x32_bf16 v[150:153], v[118:121], v[170:173], v[150:153]
	v_mfma_f32_16x16x32_bf16 v[154:157], v[126:129], v[170:173], v[154:157]
	v_mfma_f32_16x16x32_bf16 v[158:161], v[118:121], v[178:181], v[158:161]
	v_mfma_f32_16x16x32_bf16 v[162:165], v[126:129], v[178:181], v[162:165]
	v_mfma_f32_16x16x32_bf16 v[14:17], v[118:121], v[186:189], v[14:17]
	v_mfma_f32_16x16x32_bf16 v[18:21], v[126:129], v[186:189], v[18:21]
	v_mfma_f32_16x16x32_bf16 v[142:145], v[122:125], v[138:141], v[142:145]
	v_mfma_f32_16x16x32_bf16 v[146:149], v[130:133], v[138:141], v[146:149]
	v_mfma_f32_16x16x32_bf16 v[150:153], v[122:125], v[174:177], v[150:153]
	v_mfma_f32_16x16x32_bf16 v[154:157], v[130:133], v[174:177], v[154:157]
	v_mfma_f32_16x16x32_bf16 v[158:161], v[122:125], v[182:185], v[158:161]
	v_mfma_f32_16x16x32_bf16 v[162:165], v[130:133], v[182:185], v[162:165]
	v_mfma_f32_16x16x32_bf16 v[14:17], v[122:125], v[190:193], v[14:17]
	v_mfma_f32_16x16x32_bf16 v[18:21], v[130:133], v[190:193], v[18:21]
	s_barrier
	s_add_u32 s10, s6, 0x40080
	s_addc_u32 s11, s7, 0
	s_mov_b32 m0, s13
	v_lshl_add_u64 v[10:11], s[10:11], 0, v[2:3]
	global_load_lds_dwordx4 v[10:11], off
	v_lshl_add_u64 v[10:11], s[10:11], 0, v[0:1]
	s_mov_b32 m0, s12
	s_nop 0
	global_load_lds_dwordx4 v[10:11], off
	s_waitcnt vmcnt(6)
	s_barrier
	v_mfma_f32_16x16x32_bf16 v[22:25], v[194:197], v[134:137], v[22:25]
	v_mfma_f32_16x16x32_bf16 v[26:29], v[202:205], v[134:137], v[26:29]
	v_mfma_f32_16x16x32_bf16 v[58:61], v[194:197], v[170:173], v[58:61]
	v_mfma_f32_16x16x32_bf16 v[102:105], v[202:205], v[170:173], v[102:105]
	v_mfma_f32_16x16x32_bf16 v[106:109], v[194:197], v[178:181], v[106:109]
	v_mfma_f32_16x16x32_bf16 v[114:117], v[202:205], v[178:181], v[114:117]
	v_mfma_f32_16x16x32_bf16 v[94:97], v[194:197], v[186:189], v[94:97]
	v_mfma_f32_16x16x32_bf16 v[98:101], v[202:205], v[186:189], v[98:101]
	v_mfma_f32_16x16x32_bf16 v[22:25], v[198:201], v[138:141], v[22:25]
	v_mfma_f32_16x16x32_bf16 v[26:29], v[212:215], v[138:141], v[26:29]
	v_mfma_f32_16x16x32_bf16 v[58:61], v[198:201], v[174:177], v[58:61]
	v_mfma_f32_16x16x32_bf16 v[102:105], v[212:215], v[174:177], v[102:105]
	v_mfma_f32_16x16x32_bf16 v[106:109], v[198:201], v[182:185], v[106:109]
	v_mfma_f32_16x16x32_bf16 v[114:117], v[212:215], v[182:185], v[114:117]
	v_mfma_f32_16x16x32_bf16 v[94:97], v[198:201], v[190:193], v[94:97]
	v_mfma_f32_16x16x32_bf16 v[98:101], v[212:215], v[190:193], v[98:101]
	s_lshl_b32 s3, s9, 8
	s_ashr_i32 s9, s8, 31
	v_add_u32_e32 v10, s3, v4
	s_lshl_b64 s[8:9], s[8:9], 21
	v_ashrrev_i32_e32 v11, 31, v10
	s_add_u32 s8, s24, s8
	s_addc_u32 s9, s25, s9
	v_lshlrev_b64 v[118:119], 12, v[10:11]
	v_lshl_or_b32 v168, s31, 8, v8
	v_lshl_add_u64 v[118:119], s[8:9], 0, v[118:119]
	v_lshlrev_b64 v[120:121], 2, v[168:169]
	v_lshl_add_u64 v[118:119], v[118:119], 0, v[120:121]
	s_barrier
	global_store_dwordx4 v[118:119], v[62:65], off
	global_store_dwordx4 v[118:119], v[66:69], off offset:64
	global_store_dwordx4 v[118:119], v[110:113], off offset:512
	global_store_dwordx4 v[118:119], v[30:33], off offset:576
	s_andn2_b64 vcc, exec, s[4:5]
	s_mov_b32 s31, s30
	v_add_u32_e32 v30, s3, v5
	v_ashrrev_i32_e32 v31, 31, v30
	v_lshlrev_b64 v[30:31], 12, v[30:31]
	v_lshl_add_u64 v[30:31], s[8:9], 0, v[30:31]
	v_lshl_add_u64 v[30:31], v[30:31], 0, v[120:121]
	global_store_dwordx4 v[30:31], v[70:73], off
	global_store_dwordx4 v[30:31], v[74:77], off offset:64
	global_store_dwordx4 v[30:31], v[34:37], off offset:512
	global_store_dwordx4 v[30:31], v[38:41], off offset:576
	v_add_u32_e32 v30, s3, v6
	v_ashrrev_i32_e32 v31, 31, v30
	v_lshlrev_b64 v[30:31], 12, v[30:31]
	v_lshl_add_u64 v[30:31], s[8:9], 0, v[30:31]
	v_lshl_add_u64 v[30:31], v[30:31], 0, v[120:121]
	global_store_dwordx4 v[30:31], v[78:81], off
	global_store_dwordx4 v[30:31], v[82:85], off offset:64
	global_store_dwordx4 v[30:31], v[42:45], off offset:512
	global_store_dwordx4 v[30:31], v[46:49], off offset:576
	v_add_u32_e32 v30, s3, v7
	v_ashrrev_i32_e32 v31, 31, v30
	v_lshlrev_b64 v[30:31], 12, v[30:31]
	v_lshl_add_u64 v[30:31], s[8:9], 0, v[30:31]
	v_lshl_add_u64 v[30:31], v[30:31], 0, v[120:121]
	global_store_dwordx4 v[30:31], v[86:89], off
	global_store_dwordx4 v[30:31], v[90:93], off offset:64
	global_store_dwordx4 v[30:31], v[50:53], off offset:512
	global_store_dwordx4 v[30:31], v[54:57], off offset:576
	v_add_u32_e32 v30, 0x80, v10
	v_ashrrev_i32_e32 v31, 31, v30
	v_lshlrev_b64 v[30:31], 12, v[30:31]
	v_lshl_add_u64 v[30:31], s[8:9], 0, v[30:31]
	v_lshl_add_u64 v[30:31], v[30:31], 0, v[120:121]
	global_store_dwordx4 v[30:31], v[142:145], off
	global_store_dwordx4 v[30:31], v[146:149], off offset:64
	global_store_dwordx4 v[30:31], v[22:25], off offset:512
	global_store_dwordx4 v[30:31], v[26:29], off offset:576
	s_mov_b64 s[12:13], s[6:7]
	v_add_u32_e32 v22, 0x90, v10
	v_ashrrev_i32_e32 v23, 31, v22
	v_lshlrev_b64 v[22:23], 12, v[22:23]
	v_lshl_add_u64 v[22:23], s[8:9], 0, v[22:23]
	v_lshl_add_u64 v[22:23], v[22:23], 0, v[120:121]
	global_store_dwordx4 v[22:23], v[150:153], off
	global_store_dwordx4 v[22:23], v[154:157], off offset:64
	global_store_dwordx4 v[22:23], v[58:61], off offset:512
	global_store_dwordx4 v[22:23], v[102:105], off offset:576
	v_add_u32_e32 v22, 0xa0, v10
	v_add_u32_e32 v10, 0xb0, v10
	v_ashrrev_i32_e32 v23, 31, v22
	v_ashrrev_i32_e32 v11, 31, v10
	v_lshlrev_b64 v[22:23], 12, v[22:23]
	v_lshlrev_b64 v[10:11], 12, v[10:11]
	v_lshl_add_u64 v[22:23], s[8:9], 0, v[22:23]
	v_lshl_add_u64 v[10:11], s[8:9], 0, v[10:11]
	v_lshl_add_u64 v[22:23], v[22:23], 0, v[120:121]
	v_lshl_add_u64 v[10:11], v[10:11], 0, v[120:121]
	s_mov_b32 s8, s2
	s_mov_b32 s9, s29
	s_mov_b64 s[10:11], s[0:1]
	global_store_dwordx4 v[22:23], v[158:161], off
	global_store_dwordx4 v[22:23], v[162:165], off offset:64
	global_store_dwordx4 v[22:23], v[106:109], off offset:512
	global_store_dwordx4 v[22:23], v[114:117], off offset:576
	global_store_dwordx4 v[10:11], v[14:17], off
	global_store_dwordx4 v[10:11], v[18:21], off offset:64
	global_store_dwordx4 v[10:11], v[94:97], off offset:512
	global_store_dwordx4 v[10:11], v[98:101], off offset:576
	s_cbranch_vccz .LBB0_559

.LBB0_578:
	s_add_u32 s24, s22, 0xfffc0080
	s_addc_u32 s25, s23, -1
	s_add_i32 s53, 0, 0x10000
	s_cmp_eq_u32 s52, 12
	s_cselect_b32 s27, s17, s25
	s_cselect_b32 s26, s48, s24
	s_cselect_b32 s25, s15, s51
	s_cselect_b32 s24, s49, s50
	s_add_i32 s56, 0, 0x14000
	v_add_u32_e32 v140, s53, v163
	v_add_u32_e32 v166, s56, v163
	ds_read_b128 v[128:131], v140
	ds_read_b128 v[132:135], v140 offset:1024
	ds_read_b128 v[136:139], v140 offset:2048
	ds_read_b128 v[140:143], v140 offset:3072
	ds_read_b128 v[154:157], v166
	ds_read_b128 v[158:161], v166 offset:1024
	ds_read_b128 v[170:173], v166 offset:2048
	ds_read_b128 v[174:177], v166 offset:3072
	v_lshl_add_u64 v[166:167], s[22:23], 0, v[152:153]
	s_add_i32 m0, s29, 0xc000
	ds_read_b128 v[178:181], v165
	ds_read_b128 v[182:185], v165 offset:1024
	ds_read_b128 v[186:189], v165 offset:2048
	ds_read_b128 v[190:193], v165 offset:3072
	ds_read_b128 v[194:197], v165 offset:4096
	ds_read_b128 v[198:201], v165 offset:5120
	ds_read_b128 v[202:205], v165 offset:6144
	ds_read_b128 v[212:215], v165 offset:7168
	global_load_lds_dwordx4 v[166:167], off
	v_lshl_add_u64 v[166:167], s[22:23], 0, v[150:151]
	s_add_i32 m0, s29, 0xe000
	s_nop 0
	global_load_lds_dwordx4 v[166:167], off
	s_waitcnt vmcnt(8)
	s_waitcnt lgkmcnt(0)
	s_barrier
	s_waitcnt lgkmcnt(0)
	v_mfma_f32_16x16x32_bf16 v[124:127], v[128:131], v[178:181], v[124:127]
	v_mfma_f32_16x16x32_bf16 v[120:123], v[136:139], v[178:181], v[120:123]
	v_mfma_f32_16x16x32_bf16 v[112:115], v[128:131], v[186:189], v[112:115]
	v_mfma_f32_16x16x32_bf16 v[104:107], v[136:139], v[186:189], v[104:107]
	v_mfma_f32_16x16x32_bf16 v[92:95], v[128:131], v[194:197], v[92:95]
	v_mfma_f32_16x16x32_bf16 v[88:91], v[136:139], v[194:197], v[88:91]
	v_mfma_f32_16x16x32_bf16 v[76:79], v[128:131], v[202:205], v[76:79]
	v_mfma_f32_16x16x32_bf16 v[72:75], v[136:139], v[202:205], v[72:75]
	v_mfma_f32_16x16x32_bf16 v[124:127], v[132:135], v[182:185], v[124:127]
	v_mfma_f32_16x16x32_bf16 v[120:123], v[140:143], v[182:185], v[120:123]
	v_mfma_f32_16x16x32_bf16 v[112:115], v[132:135], v[190:193], v[112:115]
	v_mfma_f32_16x16x32_bf16 v[104:107], v[140:143], v[190:193], v[104:107]
	v_mfma_f32_16x16x32_bf16 v[92:95], v[132:135], v[198:201], v[92:95]
	v_mfma_f32_16x16x32_bf16 v[88:91], v[140:143], v[198:201], v[88:91]
	v_mfma_f32_16x16x32_bf16 v[76:79], v[132:135], v[212:215], v[76:79]
	v_mfma_f32_16x16x32_bf16 v[72:75], v[140:143], v[212:215], v[72:75]
	v_mfma_f32_16x16x32_bf16 v[116:119], v[154:157], v[178:181], v[116:119]
	v_mfma_f32_16x16x32_bf16 v[108:111], v[170:173], v[178:181], v[108:111]
	v_mfma_f32_16x16x32_bf16 v[100:103], v[154:157], v[186:189], v[100:103]
	v_mfma_f32_16x16x32_bf16 v[96:99], v[170:173], v[186:189], v[96:99]
	v_mfma_f32_16x16x32_bf16 v[84:87], v[154:157], v[194:197], v[84:87]
	v_mfma_f32_16x16x32_bf16 v[80:83], v[170:173], v[194:197], v[80:83]
	v_mfma_f32_16x16x32_bf16 v[68:71], v[154:157], v[202:205], v[68:71]
	v_mfma_f32_16x16x32_bf16 v[64:67], v[170:173], v[202:205], v[64:67]
	v_mfma_f32_16x16x32_bf16 v[116:119], v[158:161], v[182:185], v[116:119]
	v_mfma_f32_16x16x32_bf16 v[108:111], v[174:177], v[182:185], v[108:111]
	v_mfma_f32_16x16x32_bf16 v[100:103], v[158:161], v[190:193], v[100:103]
	v_mfma_f32_16x16x32_bf16 v[96:99], v[174:177], v[190:193], v[96:99]
	v_mfma_f32_16x16x32_bf16 v[84:87], v[158:161], v[198:201], v[84:87]
	v_mfma_f32_16x16x32_bf16 v[80:83], v[174:177], v[198:201], v[80:83]
	v_mfma_f32_16x16x32_bf16 v[68:71], v[158:161], v[212:215], v[68:71]
	v_mfma_f32_16x16x32_bf16 v[64:67], v[174:177], v[212:215], v[64:67]
	s_barrier
	s_add_i32 s53, s53, s28
	v_lshl_add_u64 v[166:167], s[24:25], 0, v[168:169]
	s_mov_b32 m0, s53
	ds_read_b128 v[178:181], v165 offset:16384
	ds_read_b128 v[182:185], v165 offset:17408
	ds_read_b128 v[186:189], v165 offset:18432
	ds_read_b128 v[190:193], v165 offset:19456
	ds_read_b128 v[194:197], v165 offset:20480
	ds_read_b128 v[198:201], v165 offset:21504
	ds_read_b128 v[202:205], v165 offset:22528
	ds_read_b128 v[212:215], v165 offset:23552
	global_load_lds_dwordx4 v[166:167], off
	s_add_i32 m0, s53, 0x2000
	s_add_u32 s54, s24, 0x40000
	v_lshl_add_u64 v[216:217], s[24:25], 0, v[144:145]
	s_addc_u32 s55, s25, 0
	s_add_i32 s53, s56, s28
	global_load_lds_dwordx4 v[216:217], off
	v_lshl_add_u64 v[220:221], s[54:55], 0, v[168:169]
	s_mov_b32 m0, s53
	v_lshl_add_u64 v[222:223], s[26:27], 0, v[146:147]
	global_load_lds_dwordx4 v[220:221], off
	v_lshl_add_u64 v[220:221], s[54:55], 0, v[144:145]
	s_add_i32 m0, s53, 0x2000
	s_nop 0
	global_load_lds_dwordx4 v[220:221], off
	v_lshl_add_u64 v[220:221], s[26:27], 0, v[148:149]
	s_mov_b32 m0, s29
	s_nop 0
	global_load_lds_dwordx4 v[220:221], off
	s_mov_b32 m0, s30
	s_nop 0
	global_load_lds_dwordx4 v[222:223], off
	s_waitcnt vmcnt(8)
	s_waitcnt lgkmcnt(0)
	s_barrier
	s_waitcnt lgkmcnt(0)
	v_mfma_f32_16x16x32_bf16 v[60:63], v[128:131], v[178:181], v[60:63]
	v_mfma_f32_16x16x32_bf16 v[56:59], v[136:139], v[178:181], v[56:59]
	v_mfma_f32_16x16x32_bf16 v[44:47], v[128:131], v[186:189], v[44:47]
	v_mfma_f32_16x16x32_bf16 v[40:43], v[136:139], v[186:189], v[40:43]
	v_mfma_f32_16x16x32_bf16 v[28:31], v[128:131], v[194:197], v[28:31]
	v_mfma_f32_16x16x32_bf16 v[24:27], v[136:139], v[194:197], v[24:27]
	v_mfma_f32_16x16x32_bf16 v[12:15], v[128:131], v[202:205], v[12:15]
	v_mfma_f32_16x16x32_bf16 v[8:11], v[136:139], v[202:205], v[8:11]
	v_mfma_f32_16x16x32_bf16 v[60:63], v[132:135], v[182:185], v[60:63]
	v_mfma_f32_16x16x32_bf16 v[56:59], v[140:143], v[182:185], v[56:59]
	v_mfma_f32_16x16x32_bf16 v[44:47], v[132:135], v[190:193], v[44:47]
	v_mfma_f32_16x16x32_bf16 v[40:43], v[140:143], v[190:193], v[40:43]
	v_mfma_f32_16x16x32_bf16 v[28:31], v[132:135], v[198:201], v[28:31]
	v_mfma_f32_16x16x32_bf16 v[24:27], v[140:143], v[198:201], v[24:27]
	v_mfma_f32_16x16x32_bf16 v[12:15], v[132:135], v[212:215], v[12:15]
	v_mfma_f32_16x16x32_bf16 v[8:11], v[140:143], v[212:215], v[8:11]
	v_mfma_f32_16x16x32_bf16 v[52:55], v[154:157], v[178:181], v[52:55]
	v_mfma_f32_16x16x32_bf16 v[48:51], v[170:173], v[178:181], v[48:51]
	v_mfma_f32_16x16x32_bf16 v[36:39], v[154:157], v[186:189], v[36:39]
	v_mfma_f32_16x16x32_bf16 v[32:35], v[170:173], v[186:189], v[32:35]
	v_mfma_f32_16x16x32_bf16 v[20:23], v[154:157], v[194:197], v[20:23]
	v_mfma_f32_16x16x32_bf16 v[16:19], v[170:173], v[194:197], v[16:19]
	v_mfma_f32_16x16x32_bf16 v[4:7], v[154:157], v[202:205], v[4:7]
	v_mfma_f32_16x16x32_bf16 v[0:3], v[170:173], v[202:205], v[0:3]
	v_mfma_f32_16x16x32_bf16 v[52:55], v[158:161], v[182:185], v[52:55]
	v_mfma_f32_16x16x32_bf16 v[48:51], v[174:177], v[182:185], v[48:51]
	v_mfma_f32_16x16x32_bf16 v[36:39], v[158:161], v[190:193], v[36:39]
	v_mfma_f32_16x16x32_bf16 v[32:35], v[174:177], v[190:193], v[32:35]
	v_mfma_f32_16x16x32_bf16 v[20:23], v[158:161], v[198:201], v[20:23]
	v_mfma_f32_16x16x32_bf16 v[16:19], v[174:177], v[198:201], v[16:19]
	v_mfma_f32_16x16x32_bf16 v[4:7], v[158:161], v[212:215], v[4:7]
	v_mfma_f32_16x16x32_bf16 v[0:3], v[174:177], v[212:215], v[0:3]
	s_barrier
	s_add_i32 s53, 0, 0x18000
	s_add_i32 s54, 0, 0x1c000
	v_add_u32_e32 v140, s53, v163
	v_add_u32_e32 v174, s54, v163
	ds_read_b128 v[128:131], v140
	ds_read_b128 v[132:135], v140 offset:1024
	ds_read_b128 v[136:139], v140 offset:2048
	ds_read_b128 v[140:143], v140 offset:3072
	ds_read_b128 v[154:157], v174
	ds_read_b128 v[158:161], v174 offset:1024
	ds_read_b128 v[170:173], v174 offset:2048
	ds_read_b128 v[174:177], v174 offset:3072
	s_add_u32 s26, s26, 0x40000
	s_addc_u32 s27, s27, 0
	s_mov_b32 m0, s31
	v_lshl_add_u64 v[224:225], s[26:27], 0, v[148:149]
	ds_read_b128 v[178:181], v165 offset:32768
	ds_read_b128 v[182:185], v165 offset:33792
	ds_read_b128 v[186:189], v165 offset:34816
	ds_read_b128 v[190:193], v165 offset:35840
	ds_read_b128 v[194:197], v165 offset:36864
	ds_read_b128 v[198:201], v165 offset:37888
	ds_read_b128 v[202:205], v165 offset:38912
	ds_read_b128 v[212:215], v165 offset:39936
	global_load_lds_dwordx4 v[224:225], off
	v_lshl_add_u64 v[224:225], s[26:27], 0, v[146:147]
	s_mov_b32 m0, s40
	s_nop 0
	global_load_lds_dwordx4 v[224:225], off
	s_waitcnt vmcnt(8)
	s_waitcnt lgkmcnt(0)
	s_barrier
	s_waitcnt lgkmcnt(0)
	v_mfma_f32_16x16x32_bf16 v[124:127], v[128:131], v[178:181], v[124:127]
	v_mfma_f32_16x16x32_bf16 v[120:123], v[136:139], v[178:181], v[120:123]
	v_mfma_f32_16x16x32_bf16 v[112:115], v[128:131], v[186:189], v[112:115]
	v_mfma_f32_16x16x32_bf16 v[104:107], v[136:139], v[186:189], v[104:107]
	v_mfma_f32_16x16x32_bf16 v[92:95], v[128:131], v[194:197], v[92:95]
	v_mfma_f32_16x16x32_bf16 v[88:91], v[136:139], v[194:197], v[88:91]
	v_mfma_f32_16x16x32_bf16 v[76:79], v[128:131], v[202:205], v[76:79]
	v_mfma_f32_16x16x32_bf16 v[72:75], v[136:139], v[202:205], v[72:75]
	v_mfma_f32_16x16x32_bf16 v[124:127], v[132:135], v[182:185], v[124:127]
	v_mfma_f32_16x16x32_bf16 v[120:123], v[140:143], v[182:185], v[120:123]
	v_mfma_f32_16x16x32_bf16 v[112:115], v[132:135], v[190:193], v[112:115]
	v_mfma_f32_16x16x32_bf16 v[104:107], v[140:143], v[190:193], v[104:107]
	v_mfma_f32_16x16x32_bf16 v[92:95], v[132:135], v[198:201], v[92:95]
	v_mfma_f32_16x16x32_bf16 v[88:91], v[140:143], v[198:201], v[88:91]
	v_mfma_f32_16x16x32_bf16 v[76:79], v[132:135], v[212:215], v[76:79]
	v_mfma_f32_16x16x32_bf16 v[72:75], v[140:143], v[212:215], v[72:75]
	v_mfma_f32_16x16x32_bf16 v[116:119], v[154:157], v[178:181], v[116:119]
	v_mfma_f32_16x16x32_bf16 v[108:111], v[170:173], v[178:181], v[108:111]
	v_mfma_f32_16x16x32_bf16 v[100:103], v[154:157], v[186:189], v[100:103]
	v_mfma_f32_16x16x32_bf16 v[96:99], v[170:173], v[186:189], v[96:99]
	v_mfma_f32_16x16x32_bf16 v[84:87], v[154:157], v[194:197], v[84:87]
	v_mfma_f32_16x16x32_bf16 v[80:83], v[170:173], v[194:197], v[80:83]
	v_mfma_f32_16x16x32_bf16 v[68:71], v[154:157], v[202:205], v[68:71]
	v_mfma_f32_16x16x32_bf16 v[64:67], v[170:173], v[202:205], v[64:67]
	v_mfma_f32_16x16x32_bf16 v[116:119], v[158:161], v[182:185], v[116:119]
	v_mfma_f32_16x16x32_bf16 v[108:111], v[174:177], v[182:185], v[108:111]
	v_mfma_f32_16x16x32_bf16 v[100:103], v[158:161], v[190:193], v[100:103]
	v_mfma_f32_16x16x32_bf16 v[96:99], v[174:177], v[190:193], v[96:99]
	v_mfma_f32_16x16x32_bf16 v[84:87], v[158:161], v[198:201], v[84:87]
	v_mfma_f32_16x16x32_bf16 v[80:83], v[174:177], v[198:201], v[80:83]
	v_mfma_f32_16x16x32_bf16 v[68:71], v[158:161], v[212:215], v[68:71]
	v_mfma_f32_16x16x32_bf16 v[64:67], v[174:177], v[212:215], v[64:67]
	s_barrier
	s_add_i32 s26, s53, s28
	v_lshl_add_u64 v[166:167], v[166:167], 0, s[74:75]
	s_mov_b32 m0, s26
	ds_read_b128 v[178:181], v165 offset:49152
	ds_read_b128 v[182:185], v165 offset:50176
	ds_read_b128 v[186:189], v165 offset:51200
	ds_read_b128 v[190:193], v165 offset:52224
	ds_read_b128 v[194:197], v165 offset:53248
	ds_read_b128 v[198:201], v165 offset:54272
	ds_read_b128 v[202:205], v165 offset:55296
	ds_read_b128 v[212:215], v165 offset:56320
	global_load_lds_dwordx4 v[166:167], off
	s_add_i32 m0, s26, 0x2000
	s_add_u32 s24, s24, 0x40080
	v_lshl_add_u64 v[166:167], v[216:217], 0, s[74:75]
	s_addc_u32 s25, s25, 0
	s_add_i32 s26, s54, s28
	global_load_lds_dwordx4 v[166:167], off
	v_lshl_add_u64 v[166:167], s[24:25], 0, v[168:169]
	s_mov_b32 m0, s26
	s_nop 0
	global_load_lds_dwordx4 v[166:167], off
	v_lshl_add_u64 v[166:167], s[24:25], 0, v[144:145]
	s_add_i32 m0, s26, 0x2000
	s_nop 0
	global_load_lds_dwordx4 v[166:167], off
	v_lshl_add_u64 v[166:167], v[220:221], 0, s[74:75]
	s_mov_b32 m0, s43
	s_nop 0
	global_load_lds_dwordx4 v[166:167], off
	v_lshl_add_u64 v[166:167], v[222:223], 0, s[74:75]
	s_mov_b32 m0, s44
	s_nop 0
	global_load_lds_dwordx4 v[166:167], off
	s_waitcnt vmcnt(8)
	s_waitcnt lgkmcnt(0)
	s_barrier
	s_waitcnt lgkmcnt(0)
	v_mfma_f32_16x16x32_bf16 v[60:63], v[128:131], v[178:181], v[60:63]
	v_mfma_f32_16x16x32_bf16 v[56:59], v[136:139], v[178:181], v[56:59]
	v_mfma_f32_16x16x32_bf16 v[44:47], v[128:131], v[186:189], v[44:47]
	v_mfma_f32_16x16x32_bf16 v[40:43], v[136:139], v[186:189], v[40:43]
	v_mfma_f32_16x16x32_bf16 v[28:31], v[128:131], v[194:197], v[28:31]
	v_mfma_f32_16x16x32_bf16 v[24:27], v[136:139], v[194:197], v[24:27]
	v_mfma_f32_16x16x32_bf16 v[12:15], v[128:131], v[202:205], v[12:15]
	v_mfma_f32_16x16x32_bf16 v[8:11], v[136:139], v[202:205], v[8:11]
	v_mfma_f32_16x16x32_bf16 v[60:63], v[132:135], v[182:185], v[60:63]
	v_mfma_f32_16x16x32_bf16 v[56:59], v[140:143], v[182:185], v[56:59]
	v_mfma_f32_16x16x32_bf16 v[44:47], v[132:135], v[190:193], v[44:47]
	v_mfma_f32_16x16x32_bf16 v[40:43], v[140:143], v[190:193], v[40:43]
	v_mfma_f32_16x16x32_bf16 v[28:31], v[132:135], v[198:201], v[28:31]
	v_mfma_f32_16x16x32_bf16 v[24:27], v[140:143], v[198:201], v[24:27]
	v_mfma_f32_16x16x32_bf16 v[12:15], v[132:135], v[212:215], v[12:15]
	v_mfma_f32_16x16x32_bf16 v[8:11], v[140:143], v[212:215], v[8:11]
	v_mfma_f32_16x16x32_bf16 v[52:55], v[154:157], v[178:181], v[52:55]
	v_mfma_f32_16x16x32_bf16 v[48:51], v[170:173], v[178:181], v[48:51]
	v_mfma_f32_16x16x32_bf16 v[36:39], v[154:157], v[186:189], v[36:39]
	v_mfma_f32_16x16x32_bf16 v[32:35], v[170:173], v[186:189], v[32:35]
	v_mfma_f32_16x16x32_bf16 v[20:23], v[154:157], v[194:197], v[20:23]
	v_mfma_f32_16x16x32_bf16 v[16:19], v[170:173], v[194:197], v[16:19]
	v_mfma_f32_16x16x32_bf16 v[4:7], v[154:157], v[202:205], v[4:7]
	v_mfma_f32_16x16x32_bf16 v[0:3], v[170:173], v[202:205], v[0:3]
	v_mfma_f32_16x16x32_bf16 v[52:55], v[158:161], v[182:185], v[52:55]
	v_mfma_f32_16x16x32_bf16 v[48:51], v[174:177], v[182:185], v[48:51]
	v_mfma_f32_16x16x32_bf16 v[36:39], v[158:161], v[190:193], v[36:39]
	v_mfma_f32_16x16x32_bf16 v[32:35], v[174:177], v[190:193], v[32:35]
	v_mfma_f32_16x16x32_bf16 v[20:23], v[158:161], v[198:201], v[20:23]
	v_mfma_f32_16x16x32_bf16 v[16:19], v[174:177], v[198:201], v[16:19]
	v_mfma_f32_16x16x32_bf16 v[4:7], v[158:161], v[212:215], v[4:7]
	v_mfma_f32_16x16x32_bf16 v[0:3], v[174:177], v[212:215], v[0:3]
	s_barrier
	s_add_i32 s52, s52, 2
	s_add_u32 s50, s50, 0x100
	s_addc_u32 s51, s51, 0
	s_add_u32 s22, s22, 0x100
	s_addc_u32 s23, s23, 0
	s_cmp_gt_u32 s52, 13
	s_cbranch_scc0 .LBB0_578
	v_readlane_b32 s52, v254, 51
	s_and_b64 vcc, exec, s[12:13]
	v_readlane_b32 s53, v254, 52
	s_cbranch_vccz .LBB0_581
	s_barrier

.LBB0_599:
	s_add_u32 s28, s16, s26
	s_addc_u32 s29, s17, s27
	s_add_u32 s28, s28, 0x100
	s_addc_u32 s29, s29, 0
	s_add_u32 s57, s52, s26
	s_addc_u32 s58, s53, s27
	s_add_i32 s59, 0, 0x10000
	s_cmpk_eq_i32 s26, 0x700
	s_cselect_b32 s31, s21, s29
	s_cselect_b32 s30, s54, s28
	s_cselect_b32 s29, s19, s58
	s_cselect_b32 s28, s55, s57
	s_add_i32 s57, 0, 0x14000
	v_add_u32_e32 v156, s59, v142
	v_add_u32_e32 v174, s57, v142
	ds_read_b128 v[144:147], v156
	ds_read_b128 v[148:151], v156 offset:1024
	ds_read_b128 v[152:155], v156 offset:2048
	ds_read_b128 v[156:159], v156 offset:3072
	ds_read_b128 v[160:163], v174
	ds_read_b128 v[164:167], v174 offset:1024
	ds_read_b128 v[170:173], v174 offset:2048
	ds_read_b128 v[174:177], v174 offset:3072
	v_lshl_add_u64 v[178:179], v[140:141], 0, s[26:27]
	s_add_i32 m0, s44, 0xc000
	ds_read_b128 v[184:187], v143
	ds_read_b128 v[188:191], v143 offset:1024
	ds_read_b128 v[192:195], v143 offset:2048
	ds_read_b128 v[196:199], v143 offset:3072
	ds_read_b128 v[200:203], v143 offset:4096
	ds_read_b128 v[212:215], v143 offset:5120
	ds_read_b128 v[220:223], v143 offset:6144
	ds_read_b128 v[224:227], v143 offset:7168
	global_load_lds_dwordx4 v[178:179], off
	v_lshl_add_u64 v[178:179], v[138:139], 0, s[26:27]
	s_add_i32 m0, s44, 0xe000
	s_nop 0
	global_load_lds_dwordx4 v[178:179], off
	s_waitcnt vmcnt(8)
	s_waitcnt lgkmcnt(0)
	s_barrier
	s_waitcnt lgkmcnt(0)
	v_mfma_f32_16x16x32_bf16 v[124:127], v[144:147], v[184:187], v[124:127]
	v_mfma_f32_16x16x32_bf16 v[120:123], v[152:155], v[184:187], v[120:123]
	v_mfma_f32_16x16x32_bf16 v[108:111], v[144:147], v[192:195], v[108:111]
	v_mfma_f32_16x16x32_bf16 v[104:107], v[152:155], v[192:195], v[104:107]
	v_mfma_f32_16x16x32_bf16 v[92:95], v[144:147], v[200:203], v[92:95]
	v_mfma_f32_16x16x32_bf16 v[88:91], v[152:155], v[200:203], v[88:91]
	v_mfma_f32_16x16x32_bf16 v[76:79], v[144:147], v[220:223], v[76:79]
	v_mfma_f32_16x16x32_bf16 v[72:75], v[152:155], v[220:223], v[72:75]
	v_mfma_f32_16x16x32_bf16 v[124:127], v[148:151], v[188:191], v[124:127]
	v_mfma_f32_16x16x32_bf16 v[120:123], v[156:159], v[188:191], v[120:123]
	v_mfma_f32_16x16x32_bf16 v[108:111], v[148:151], v[196:199], v[108:111]
	v_mfma_f32_16x16x32_bf16 v[104:107], v[156:159], v[196:199], v[104:107]
	v_mfma_f32_16x16x32_bf16 v[92:95], v[148:151], v[212:215], v[92:95]
	v_mfma_f32_16x16x32_bf16 v[88:91], v[156:159], v[212:215], v[88:91]
	v_mfma_f32_16x16x32_bf16 v[76:79], v[148:151], v[224:227], v[76:79]
	v_mfma_f32_16x16x32_bf16 v[72:75], v[156:159], v[224:227], v[72:75]
	v_mfma_f32_16x16x32_bf16 v[116:119], v[160:163], v[184:187], v[116:119]
	v_mfma_f32_16x16x32_bf16 v[112:115], v[170:173], v[184:187], v[112:115]
	v_mfma_f32_16x16x32_bf16 v[100:103], v[160:163], v[192:195], v[100:103]
	v_mfma_f32_16x16x32_bf16 v[96:99], v[170:173], v[192:195], v[96:99]
	v_mfma_f32_16x16x32_bf16 v[84:87], v[160:163], v[200:203], v[84:87]
	v_mfma_f32_16x16x32_bf16 v[80:83], v[170:173], v[200:203], v[80:83]
	v_mfma_f32_16x16x32_bf16 v[68:71], v[160:163], v[220:223], v[68:71]
	v_mfma_f32_16x16x32_bf16 v[64:67], v[170:173], v[220:223], v[64:67]
	v_mfma_f32_16x16x32_bf16 v[116:119], v[164:167], v[188:191], v[116:119]
	v_mfma_f32_16x16x32_bf16 v[112:115], v[174:177], v[188:191], v[112:115]
	v_mfma_f32_16x16x32_bf16 v[100:103], v[164:167], v[196:199], v[100:103]
	v_mfma_f32_16x16x32_bf16 v[96:99], v[174:177], v[196:199], v[96:99]
	v_mfma_f32_16x16x32_bf16 v[84:87], v[164:167], v[212:215], v[84:87]
	v_mfma_f32_16x16x32_bf16 v[80:83], v[174:177], v[212:215], v[80:83]
	v_mfma_f32_16x16x32_bf16 v[68:71], v[164:167], v[224:227], v[68:71]
	v_mfma_f32_16x16x32_bf16 v[64:67], v[174:177], v[224:227], v[64:67]
	s_barrier
	s_add_i32 s58, s59, s42
	v_lshl_add_u64 v[178:179], s[28:29], 0, v[168:169]
	s_mov_b32 m0, s58
	ds_read_b128 v[184:187], v143 offset:16384
	ds_read_b128 v[188:191], v143 offset:17408
	ds_read_b128 v[192:195], v143 offset:18432
	ds_read_b128 v[196:199], v143 offset:19456
	ds_read_b128 v[200:203], v143 offset:20480
	ds_read_b128 v[212:215], v143 offset:21504
	ds_read_b128 v[220:223], v143 offset:22528
	ds_read_b128 v[224:227], v143 offset:23552
	global_load_lds_dwordx4 v[178:179], off
	s_add_i32 m0, s58, 0x2000
	s_add_u32 s58, s28, 0x40000
	v_lshl_add_u64 v[204:205], s[28:29], 0, v[128:129]
	s_addc_u32 s59, s29, 0
	s_add_i32 s57, s57, s42
	global_load_lds_dwordx4 v[204:205], off
	v_lshl_add_u64 v[216:217], s[58:59], 0, v[168:169]
	s_mov_b32 m0, s57
	v_lshl_add_u64 v[228:229], s[30:31], 0, v[130:131]
	global_load_lds_dwordx4 v[216:217], off
	v_lshl_add_u64 v[216:217], s[58:59], 0, v[128:129]
	s_add_i32 m0, s57, 0x2000
	s_nop 0
	global_load_lds_dwordx4 v[216:217], off
	v_lshl_add_u64 v[216:217], s[30:31], 0, v[132:133]
	s_mov_b32 m0, s44
	s_nop 0
	global_load_lds_dwordx4 v[216:217], off
	s_mov_b32 m0, s45
	s_nop 0
	global_load_lds_dwordx4 v[228:229], off
	s_waitcnt vmcnt(8)
	s_waitcnt lgkmcnt(0)
	s_barrier
	s_waitcnt lgkmcnt(0)
	v_mfma_f32_16x16x32_bf16 v[60:63], v[144:147], v[184:187], v[60:63]
	v_mfma_f32_16x16x32_bf16 v[56:59], v[152:155], v[184:187], v[56:59]
	v_mfma_f32_16x16x32_bf16 v[44:47], v[144:147], v[192:195], v[44:47]
	v_mfma_f32_16x16x32_bf16 v[40:43], v[152:155], v[192:195], v[40:43]
	v_mfma_f32_16x16x32_bf16 v[28:31], v[144:147], v[200:203], v[28:31]
	v_mfma_f32_16x16x32_bf16 v[24:27], v[152:155], v[200:203], v[24:27]
	v_mfma_f32_16x16x32_bf16 v[12:15], v[144:147], v[220:223], v[12:15]
	v_mfma_f32_16x16x32_bf16 v[8:11], v[152:155], v[220:223], v[8:11]
	v_mfma_f32_16x16x32_bf16 v[60:63], v[148:151], v[188:191], v[60:63]
	v_mfma_f32_16x16x32_bf16 v[56:59], v[156:159], v[188:191], v[56:59]
	v_mfma_f32_16x16x32_bf16 v[44:47], v[148:151], v[196:199], v[44:47]
	v_mfma_f32_16x16x32_bf16 v[40:43], v[156:159], v[196:199], v[40:43]
	v_mfma_f32_16x16x32_bf16 v[28:31], v[148:151], v[212:215], v[28:31]
	v_mfma_f32_16x16x32_bf16 v[24:27], v[156:159], v[212:215], v[24:27]
	v_mfma_f32_16x16x32_bf16 v[12:15], v[148:151], v[224:227], v[12:15]
	v_mfma_f32_16x16x32_bf16 v[8:11], v[156:159], v[224:227], v[8:11]
	v_mfma_f32_16x16x32_bf16 v[52:55], v[160:163], v[184:187], v[52:55]
	v_mfma_f32_16x16x32_bf16 v[48:51], v[170:173], v[184:187], v[48:51]
	v_mfma_f32_16x16x32_bf16 v[36:39], v[160:163], v[192:195], v[36:39]
	v_mfma_f32_16x16x32_bf16 v[32:35], v[170:173], v[192:195], v[32:35]
	v_mfma_f32_16x16x32_bf16 v[20:23], v[160:163], v[200:203], v[20:23]
	v_mfma_f32_16x16x32_bf16 v[16:19], v[170:173], v[200:203], v[16:19]
	v_mfma_f32_16x16x32_bf16 v[4:7], v[160:163], v[220:223], v[4:7]
	v_mfma_f32_16x16x32_bf16 v[0:3], v[170:173], v[220:223], v[0:3]
	v_mfma_f32_16x16x32_bf16 v[52:55], v[164:167], v[188:191], v[52:55]
	v_mfma_f32_16x16x32_bf16 v[48:51], v[174:177], v[188:191], v[48:51]
	v_mfma_f32_16x16x32_bf16 v[36:39], v[164:167], v[196:199], v[36:39]
	v_mfma_f32_16x16x32_bf16 v[32:35], v[174:177], v[196:199], v[32:35]
	v_mfma_f32_16x16x32_bf16 v[20:23], v[164:167], v[212:215], v[20:23]
	v_mfma_f32_16x16x32_bf16 v[16:19], v[174:177], v[212:215], v[16:19]
	v_mfma_f32_16x16x32_bf16 v[4:7], v[164:167], v[224:227], v[4:7]
	v_mfma_f32_16x16x32_bf16 v[0:3], v[174:177], v[224:227], v[0:3]
	s_barrier
	s_add_i32 s57, 0, 0x18000
	s_add_i32 s58, 0, 0x1c000
	v_add_u32_e32 v156, s57, v142
	v_add_u32_e32 v174, s58, v142
	ds_read_b128 v[144:147], v156
	ds_read_b128 v[148:151], v156 offset:1024
	ds_read_b128 v[152:155], v156 offset:2048
	ds_read_b128 v[156:159], v156 offset:3072
	ds_read_b128 v[160:163], v174
	ds_read_b128 v[164:167], v174 offset:1024
	ds_read_b128 v[170:173], v174 offset:2048
	ds_read_b128 v[174:177], v174 offset:3072
	s_add_u32 s30, s30, 0x40000
	s_addc_u32 s31, s31, 0
	s_mov_b32 m0, s46
	v_lshl_add_u64 v[230:231], s[30:31], 0, v[132:133]
	ds_read_b128 v[184:187], v143 offset:32768
	ds_read_b128 v[188:191], v143 offset:33792
	ds_read_b128 v[192:195], v143 offset:34816
	ds_read_b128 v[196:199], v143 offset:35840
	ds_read_b128 v[200:203], v143 offset:36864
	ds_read_b128 v[212:215], v143 offset:37888
	ds_read_b128 v[220:223], v143 offset:38912
	ds_read_b128 v[224:227], v143 offset:39936
	global_load_lds_dwordx4 v[230:231], off
	v_lshl_add_u64 v[230:231], s[30:31], 0, v[130:131]
	s_mov_b32 m0, s47
	s_nop 0
	global_load_lds_dwordx4 v[230:231], off
	s_waitcnt vmcnt(8)
	s_waitcnt lgkmcnt(0)
	s_barrier
	s_waitcnt lgkmcnt(0)
	v_mfma_f32_16x16x32_bf16 v[124:127], v[144:147], v[184:187], v[124:127]
	v_mfma_f32_16x16x32_bf16 v[120:123], v[152:155], v[184:187], v[120:123]
	v_mfma_f32_16x16x32_bf16 v[108:111], v[144:147], v[192:195], v[108:111]
	v_mfma_f32_16x16x32_bf16 v[104:107], v[152:155], v[192:195], v[104:107]
	v_mfma_f32_16x16x32_bf16 v[92:95], v[144:147], v[200:203], v[92:95]
	v_mfma_f32_16x16x32_bf16 v[88:91], v[152:155], v[200:203], v[88:91]
	v_mfma_f32_16x16x32_bf16 v[76:79], v[144:147], v[220:223], v[76:79]
	v_mfma_f32_16x16x32_bf16 v[72:75], v[152:155], v[220:223], v[72:75]
	v_mfma_f32_16x16x32_bf16 v[124:127], v[148:151], v[188:191], v[124:127]
	v_mfma_f32_16x16x32_bf16 v[120:123], v[156:159], v[188:191], v[120:123]
	v_mfma_f32_16x16x32_bf16 v[108:111], v[148:151], v[196:199], v[108:111]
	v_mfma_f32_16x16x32_bf16 v[104:107], v[156:159], v[196:199], v[104:107]
	v_mfma_f32_16x16x32_bf16 v[92:95], v[148:151], v[212:215], v[92:95]
	v_mfma_f32_16x16x32_bf16 v[88:91], v[156:159], v[212:215], v[88:91]
	v_mfma_f32_16x16x32_bf16 v[76:79], v[148:151], v[224:227], v[76:79]
	v_mfma_f32_16x16x32_bf16 v[72:75], v[156:159], v[224:227], v[72:75]
	v_mfma_f32_16x16x32_bf16 v[116:119], v[160:163], v[184:187], v[116:119]
	v_mfma_f32_16x16x32_bf16 v[112:115], v[170:173], v[184:187], v[112:115]
	v_mfma_f32_16x16x32_bf16 v[100:103], v[160:163], v[192:195], v[100:103]
	v_mfma_f32_16x16x32_bf16 v[96:99], v[170:173], v[192:195], v[96:99]
	v_mfma_f32_16x16x32_bf16 v[84:87], v[160:163], v[200:203], v[84:87]
	v_mfma_f32_16x16x32_bf16 v[80:83], v[170:173], v[200:203], v[80:83]
	v_mfma_f32_16x16x32_bf16 v[68:71], v[160:163], v[220:223], v[68:71]
	v_mfma_f32_16x16x32_bf16 v[64:67], v[170:173], v[220:223], v[64:67]
	v_mfma_f32_16x16x32_bf16 v[116:119], v[164:167], v[188:191], v[116:119]
	v_mfma_f32_16x16x32_bf16 v[112:115], v[174:177], v[188:191], v[112:115]
	v_mfma_f32_16x16x32_bf16 v[100:103], v[164:167], v[196:199], v[100:103]
	v_mfma_f32_16x16x32_bf16 v[96:99], v[174:177], v[196:199], v[96:99]
	v_mfma_f32_16x16x32_bf16 v[84:87], v[164:167], v[212:215], v[84:87]
	v_mfma_f32_16x16x32_bf16 v[80:83], v[174:177], v[212:215], v[80:83]
	v_mfma_f32_16x16x32_bf16 v[68:71], v[164:167], v[224:227], v[68:71]
	v_mfma_f32_16x16x32_bf16 v[64:67], v[174:177], v[224:227], v[64:67]
	s_barrier
	s_add_i32 s30, s57, s42
	v_lshl_add_u64 v[178:179], v[178:179], 0, s[74:75]
	s_mov_b32 m0, s30
	ds_read_b128 v[184:187], v143 offset:49152
	ds_read_b128 v[188:191], v143 offset:50176
	ds_read_b128 v[192:195], v143 offset:51200
	ds_read_b128 v[196:199], v143 offset:52224
	ds_read_b128 v[200:203], v143 offset:53248
	ds_read_b128 v[212:215], v143 offset:54272
	ds_read_b128 v[220:223], v143 offset:55296
	ds_read_b128 v[224:227], v143 offset:56320
	global_load_lds_dwordx4 v[178:179], off
	s_add_i32 m0, s30, 0x2000
	s_add_u32 s28, s28, 0x40080
	v_lshl_add_u64 v[178:179], v[204:205], 0, s[74:75]
	s_addc_u32 s29, s29, 0
	s_add_i32 s30, s58, s42
	global_load_lds_dwordx4 v[178:179], off
	v_lshl_add_u64 v[178:179], s[28:29], 0, v[168:169]
	s_mov_b32 m0, s30
	s_nop 0
	global_load_lds_dwordx4 v[178:179], off
	v_lshl_add_u64 v[178:179], s[28:29], 0, v[128:129]
	s_add_i32 m0, s30, 0x2000
	s_nop 0
	global_load_lds_dwordx4 v[178:179], off
	v_lshl_add_u64 v[178:179], v[216:217], 0, s[74:75]
	s_mov_b32 m0, s48
	s_nop 0
	global_load_lds_dwordx4 v[178:179], off
	v_lshl_add_u64 v[178:179], v[228:229], 0, s[74:75]
	s_mov_b32 m0, s49
	s_nop 0
	global_load_lds_dwordx4 v[178:179], off
	s_waitcnt vmcnt(8)
	s_waitcnt lgkmcnt(0)
	s_barrier
	s_waitcnt lgkmcnt(0)
	v_mfma_f32_16x16x32_bf16 v[60:63], v[144:147], v[184:187], v[60:63]
	v_mfma_f32_16x16x32_bf16 v[56:59], v[152:155], v[184:187], v[56:59]
	v_mfma_f32_16x16x32_bf16 v[44:47], v[144:147], v[192:195], v[44:47]
	v_mfma_f32_16x16x32_bf16 v[40:43], v[152:155], v[192:195], v[40:43]
	v_mfma_f32_16x16x32_bf16 v[28:31], v[144:147], v[200:203], v[28:31]
	v_mfma_f32_16x16x32_bf16 v[24:27], v[152:155], v[200:203], v[24:27]
	v_mfma_f32_16x16x32_bf16 v[12:15], v[144:147], v[220:223], v[12:15]
	v_mfma_f32_16x16x32_bf16 v[8:11], v[152:155], v[220:223], v[8:11]
	v_mfma_f32_16x16x32_bf16 v[60:63], v[148:151], v[188:191], v[60:63]
	v_mfma_f32_16x16x32_bf16 v[56:59], v[156:159], v[188:191], v[56:59]
	v_mfma_f32_16x16x32_bf16 v[44:47], v[148:151], v[196:199], v[44:47]
	v_mfma_f32_16x16x32_bf16 v[40:43], v[156:159], v[196:199], v[40:43]
	v_mfma_f32_16x16x32_bf16 v[28:31], v[148:151], v[212:215], v[28:31]
	v_mfma_f32_16x16x32_bf16 v[24:27], v[156:159], v[212:215], v[24:27]
	v_mfma_f32_16x16x32_bf16 v[12:15], v[148:151], v[224:227], v[12:15]
	v_mfma_f32_16x16x32_bf16 v[8:11], v[156:159], v[224:227], v[8:11]
	v_mfma_f32_16x16x32_bf16 v[52:55], v[160:163], v[184:187], v[52:55]
	v_mfma_f32_16x16x32_bf16 v[48:51], v[170:173], v[184:187], v[48:51]
	v_mfma_f32_16x16x32_bf16 v[36:39], v[160:163], v[192:195], v[36:39]
	v_mfma_f32_16x16x32_bf16 v[32:35], v[170:173], v[192:195], v[32:35]
	v_mfma_f32_16x16x32_bf16 v[20:23], v[160:163], v[200:203], v[20:23]
	v_mfma_f32_16x16x32_bf16 v[16:19], v[170:173], v[200:203], v[16:19]
	v_mfma_f32_16x16x32_bf16 v[4:7], v[160:163], v[220:223], v[4:7]
	v_mfma_f32_16x16x32_bf16 v[0:3], v[170:173], v[220:223], v[0:3]
	v_mfma_f32_16x16x32_bf16 v[52:55], v[164:167], v[188:191], v[52:55]
	v_mfma_f32_16x16x32_bf16 v[48:51], v[174:177], v[188:191], v[48:51]
	v_mfma_f32_16x16x32_bf16 v[36:39], v[164:167], v[196:199], v[36:39]
	v_mfma_f32_16x16x32_bf16 v[32:35], v[174:177], v[196:199], v[32:35]
	v_mfma_f32_16x16x32_bf16 v[20:23], v[164:167], v[212:215], v[20:23]
	v_mfma_f32_16x16x32_bf16 v[16:19], v[174:177], v[212:215], v[16:19]
	v_mfma_f32_16x16x32_bf16 v[4:7], v[164:167], v[224:227], v[4:7]
	v_mfma_f32_16x16x32_bf16 v[0:3], v[174:177], v[224:227], v[0:3]
	s_barrier
	s_add_i32 s56, s56, 2
	s_add_u32 s26, s26, 0x100
	s_addc_u32 s27, s27, 0
	s_cmp_gt_u32 s56, 13
	s_cbranch_scc0 .LBB0_599
	s_add_u32 s26, s52, 0xffffff00
	s_addc_u32 s27, s53, -1
	s_andn2_b64 vcc, exec, s[2:3]
	s_cbranch_vccnz .LBB0_602
	v_mov_b32_e32 v0, 0
	s_mov_b32 s14, s18
	s_mov_b32 s41, s20
	s_mov_b64 s[16:17], s[24:25]
	s_mov_b32 s50, s51
	v_mov_b32_e32 v1, v0
	v_mov_b32_e32 v2, v0
	v_mov_b32_e32 v3, v0
	v_mov_b32_e32 v4, v0
	v_mov_b32_e32 v5, v0
	v_mov_b32_e32 v6, v0
	v_mov_b32_e32 v7, v0
	v_mov_b32_e32 v16, v0
	v_mov_b32_e32 v17, v0
	v_mov_b32_e32 v18, v0
	v_mov_b32_e32 v19, v0
	v_mov_b32_e32 v20, v0
	v_mov_b32_e32 v21, v0
	v_mov_b32_e32 v22, v0
	v_mov_b32_e32 v23, v0
	v_mov_b32_e32 v32, v0
	v_mov_b32_e32 v33, v0
	v_mov_b32_e32 v34, v0
	v_mov_b32_e32 v35, v0
	v_mov_b32_e32 v36, v0
	v_mov_b32_e32 v37, v0
	v_mov_b32_e32 v38, v0
	v_mov_b32_e32 v39, v0
	v_mov_b32_e32 v48, v0
	v_mov_b32_e32 v49, v0
	v_mov_b32_e32 v50, v0
	v_mov_b32_e32 v51, v0
	v_mov_b32_e32 v52, v0
	v_mov_b32_e32 v53, v0
	v_mov_b32_e32 v54, v0
	v_mov_b32_e32 v55, v0
	v_mov_b32_e32 v8, v0
	v_mov_b32_e32 v9, v0
	v_mov_b32_e32 v10, v0
	v_mov_b32_e32 v11, v0
	v_mov_b32_e32 v12, v0
	v_mov_b32_e32 v13, v0
	v_mov_b32_e32 v14, v0
	v_mov_b32_e32 v15, v0
	v_mov_b32_e32 v24, v0
	v_mov_b32_e32 v25, v0
	v_mov_b32_e32 v26, v0
	v_mov_b32_e32 v27, v0
	v_mov_b32_e32 v28, v0
	v_mov_b32_e32 v29, v0
	v_mov_b32_e32 v30, v0
	v_mov_b32_e32 v31, v0
	v_mov_b32_e32 v40, v0
	v_mov_b32_e32 v41, v0
	v_mov_b32_e32 v42, v0
	v_mov_b32_e32 v43, v0
	v_mov_b32_e32 v44, v0
	v_mov_b32_e32 v45, v0
	v_mov_b32_e32 v46, v0
	v_mov_b32_e32 v47, v0
	v_mov_b32_e32 v56, v0
	v_mov_b32_e32 v57, v0
	v_mov_b32_e32 v58, v0
	v_mov_b32_e32 v59, v0
	v_mov_b32_e32 v60, v0
	v_mov_b32_e32 v61, v0
	v_mov_b32_e32 v62, v0
	v_mov_b32_e32 v63, v0
	v_mov_b32_e32 v64, v0
	v_mov_b32_e32 v65, v0
	v_mov_b32_e32 v66, v0
	v_mov_b32_e32 v67, v0
	v_mov_b32_e32 v68, v0
	v_mov_b32_e32 v69, v0
	v_mov_b32_e32 v70, v0
	v_mov_b32_e32 v71, v0
	v_mov_b32_e32 v80, v0
	v_mov_b32_e32 v81, v0
	v_mov_b32_e32 v82, v0
	v_mov_b32_e32 v83, v0
	v_mov_b32_e32 v84, v0
	v_mov_b32_e32 v85, v0
	v_mov_b32_e32 v86, v0
	v_mov_b32_e32 v87, v0
	v_mov_b32_e32 v96, v0
	v_mov_b32_e32 v97, v0
	v_mov_b32_e32 v98, v0
	v_mov_b32_e32 v99, v0
	v_mov_b32_e32 v100, v0
	v_mov_b32_e32 v101, v0
	v_mov_b32_e32 v102, v0
	v_mov_b32_e32 v103, v0
	v_mov_b32_e32 v112, v0
	v_mov_b32_e32 v113, v0
	v_mov_b32_e32 v114, v0
	v_mov_b32_e32 v115, v0
	v_mov_b32_e32 v116, v0
	v_mov_b32_e32 v117, v0
	v_mov_b32_e32 v118, v0
	v_mov_b32_e32 v119, v0
	v_mov_b32_e32 v72, v0
	v_mov_b32_e32 v73, v0
	v_mov_b32_e32 v74, v0
	v_mov_b32_e32 v75, v0
	v_mov_b32_e32 v76, v0
	v_mov_b32_e32 v77, v0
	v_mov_b32_e32 v78, v0
	v_mov_b32_e32 v79, v0
	v_mov_b32_e32 v88, v0
	v_mov_b32_e32 v89, v0
	v_mov_b32_e32 v90, v0
	v_mov_b32_e32 v91, v0
	v_mov_b32_e32 v92, v0
	v_mov_b32_e32 v93, v0
	v_mov_b32_e32 v94, v0
	v_mov_b32_e32 v95, v0
	v_mov_b32_e32 v104, v0
	v_mov_b32_e32 v105, v0
	v_mov_b32_e32 v106, v0
	v_mov_b32_e32 v107, v0
	v_mov_b32_e32 v108, v0
	v_mov_b32_e32 v109, v0
	v_mov_b32_e32 v110, v0
	v_mov_b32_e32 v111, v0
	v_mov_b32_e32 v120, v0
	v_mov_b32_e32 v121, v0
	v_mov_b32_e32 v122, v0
	v_mov_b32_e32 v123, v0
	v_mov_b32_e32 v124, v0
	v_mov_b32_e32 v125, v0
	v_mov_b32_e32 v126, v0
	v_mov_b32_e32 v127, v0
	s_branch .LBB0_603

.LBB0_655:
	s_add_u32 s20, s18, 0xfffc0080
	s_addc_u32 s21, s19, -1
	s_add_i32 s47, 0, 0x10000
	s_cmp_eq_u32 s46, 12
	s_cselect_b32 s23, s13, s21
	s_cselect_b32 s22, s42, s20
	s_cselect_b32 s21, s11, s45
	s_cselect_b32 s20, s43, s44
	s_add_i32 s50, 0, 0x14000
	v_add_u32_e32 v76, s47, v159
	v_add_u32_e32 v166, s50, v159
	ds_read_b128 v[64:67], v76
	ds_read_b128 v[68:71], v76 offset:1024
	ds_read_b128 v[72:75], v76 offset:2048
	ds_read_b128 v[76:79], v76 offset:3072
	ds_read_b128 v[154:157], v166
	ds_read_b128 v[162:165], v166 offset:1024
	ds_read_b128 v[170:173], v166 offset:2048
	ds_read_b128 v[174:177], v166 offset:3072
	v_lshl_add_u64 v[166:167], s[18:19], 0, v[152:153]
	s_add_i32 m0, s25, 0xc000
	ds_read_b128 v[178:181], v161
	ds_read_b128 v[182:185], v161 offset:1024
	ds_read_b128 v[186:189], v161 offset:2048
	ds_read_b128 v[190:193], v161 offset:3072
	ds_read_b128 v[194:197], v161 offset:4096
	ds_read_b128 v[198:201], v161 offset:5120
	ds_read_b128 v[202:205], v161 offset:6144
	ds_read_b128 v[212:215], v161 offset:7168
	global_load_lds_dwordx4 v[166:167], off
	v_lshl_add_u64 v[166:167], s[18:19], 0, v[150:151]
	s_add_i32 m0, s25, 0xe000
	s_nop 0
	global_load_lds_dwordx4 v[166:167], off
	s_waitcnt vmcnt(8)
	s_waitcnt lgkmcnt(0)
	s_barrier
	s_waitcnt lgkmcnt(0)
	v_mfma_f32_16x16x32_bf16 v[140:143], v[64:67], v[178:181], v[140:143]
	v_mfma_f32_16x16x32_bf16 v[136:139], v[72:75], v[178:181], v[136:139]
	v_mfma_f32_16x16x32_bf16 v[132:135], v[64:67], v[186:189], v[132:135]
	v_mfma_f32_16x16x32_bf16 v[128:131], v[72:75], v[186:189], v[128:131]
	v_mfma_f32_16x16x32_bf16 v[108:111], v[64:67], v[194:197], v[108:111]
	v_mfma_f32_16x16x32_bf16 v[104:107], v[72:75], v[194:197], v[104:107]
	v_mfma_f32_16x16x32_bf16 v[100:103], v[64:67], v[202:205], v[100:103]
	v_mfma_f32_16x16x32_bf16 v[96:99], v[72:75], v[202:205], v[96:99]
	v_mfma_f32_16x16x32_bf16 v[140:143], v[68:71], v[182:185], v[140:143]
	v_mfma_f32_16x16x32_bf16 v[136:139], v[76:79], v[182:185], v[136:139]
	v_mfma_f32_16x16x32_bf16 v[132:135], v[68:71], v[190:193], v[132:135]
	v_mfma_f32_16x16x32_bf16 v[128:131], v[76:79], v[190:193], v[128:131]
	v_mfma_f32_16x16x32_bf16 v[108:111], v[68:71], v[198:201], v[108:111]
	v_mfma_f32_16x16x32_bf16 v[104:107], v[76:79], v[198:201], v[104:107]
	v_mfma_f32_16x16x32_bf16 v[100:103], v[68:71], v[212:215], v[100:103]
	v_mfma_f32_16x16x32_bf16 v[96:99], v[76:79], v[212:215], v[96:99]
	v_mfma_f32_16x16x32_bf16 v[124:127], v[154:157], v[178:181], v[124:127]
	v_mfma_f32_16x16x32_bf16 v[120:123], v[170:173], v[178:181], v[120:123]
	v_mfma_f32_16x16x32_bf16 v[116:119], v[154:157], v[186:189], v[116:119]
	v_mfma_f32_16x16x32_bf16 v[112:115], v[170:173], v[186:189], v[112:115]
	v_mfma_f32_16x16x32_bf16 v[92:95], v[154:157], v[194:197], v[92:95]
	v_mfma_f32_16x16x32_bf16 v[88:91], v[170:173], v[194:197], v[88:91]
	v_mfma_f32_16x16x32_bf16 v[84:87], v[154:157], v[202:205], v[84:87]
	v_mfma_f32_16x16x32_bf16 v[80:83], v[170:173], v[202:205], v[80:83]
	v_mfma_f32_16x16x32_bf16 v[124:127], v[162:165], v[182:185], v[124:127]
	v_mfma_f32_16x16x32_bf16 v[120:123], v[174:177], v[182:185], v[120:123]
	v_mfma_f32_16x16x32_bf16 v[116:119], v[162:165], v[190:193], v[116:119]
	v_mfma_f32_16x16x32_bf16 v[112:115], v[174:177], v[190:193], v[112:115]
	v_mfma_f32_16x16x32_bf16 v[92:95], v[162:165], v[198:201], v[92:95]
	v_mfma_f32_16x16x32_bf16 v[88:91], v[174:177], v[198:201], v[88:91]
	v_mfma_f32_16x16x32_bf16 v[84:87], v[162:165], v[212:215], v[84:87]
	v_mfma_f32_16x16x32_bf16 v[80:83], v[174:177], v[212:215], v[80:83]
	s_barrier
	s_add_i32 s47, s47, s24
	v_lshl_add_u64 v[166:167], s[20:21], 0, v[168:169]
	s_mov_b32 m0, s47
	ds_read_b128 v[178:181], v161 offset:16384
	ds_read_b128 v[182:185], v161 offset:17408
	ds_read_b128 v[186:189], v161 offset:18432
	ds_read_b128 v[190:193], v161 offset:19456
	ds_read_b128 v[194:197], v161 offset:20480
	ds_read_b128 v[198:201], v161 offset:21504
	ds_read_b128 v[202:205], v161 offset:22528
	ds_read_b128 v[212:215], v161 offset:23552
	global_load_lds_dwordx4 v[166:167], off
	s_add_i32 m0, s47, 0x2000
	s_add_u32 s48, s20, 0x40000
	v_lshl_add_u64 v[216:217], s[20:21], 0, v[144:145]
	s_addc_u32 s49, s21, 0
	s_add_i32 s47, s50, s24
	global_load_lds_dwordx4 v[216:217], off
	v_lshl_add_u64 v[218:219], s[48:49], 0, v[168:169]
	s_mov_b32 m0, s47
	v_lshl_add_u64 v[220:221], s[22:23], 0, v[146:147]
	global_load_lds_dwordx4 v[218:219], off
	v_lshl_add_u64 v[218:219], s[48:49], 0, v[144:145]
	s_add_i32 m0, s47, 0x2000
	s_nop 0
	global_load_lds_dwordx4 v[218:219], off
	v_lshl_add_u64 v[218:219], s[22:23], 0, v[148:149]
	s_mov_b32 m0, s25
	s_nop 0
	global_load_lds_dwordx4 v[218:219], off
	s_mov_b32 m0, s26
	s_nop 0
	global_load_lds_dwordx4 v[220:221], off
	s_waitcnt vmcnt(8)
	s_waitcnt lgkmcnt(0)
	s_barrier
	s_waitcnt lgkmcnt(0)
	v_mfma_f32_16x16x32_bf16 v[60:63], v[64:67], v[178:181], v[60:63]
	v_mfma_f32_16x16x32_bf16 v[56:59], v[72:75], v[178:181], v[56:59]
	v_mfma_f32_16x16x32_bf16 v[52:55], v[64:67], v[186:189], v[52:55]
	v_mfma_f32_16x16x32_bf16 v[48:51], v[72:75], v[186:189], v[48:51]
	v_mfma_f32_16x16x32_bf16 v[28:31], v[64:67], v[194:197], v[28:31]
	v_mfma_f32_16x16x32_bf16 v[24:27], v[72:75], v[194:197], v[24:27]
	v_mfma_f32_16x16x32_bf16 v[20:23], v[64:67], v[202:205], v[20:23]
	v_mfma_f32_16x16x32_bf16 v[16:19], v[72:75], v[202:205], v[16:19]
	v_mfma_f32_16x16x32_bf16 v[60:63], v[68:71], v[182:185], v[60:63]
	v_mfma_f32_16x16x32_bf16 v[56:59], v[76:79], v[182:185], v[56:59]
	v_mfma_f32_16x16x32_bf16 v[52:55], v[68:71], v[190:193], v[52:55]
	v_mfma_f32_16x16x32_bf16 v[48:51], v[76:79], v[190:193], v[48:51]
	v_mfma_f32_16x16x32_bf16 v[28:31], v[68:71], v[198:201], v[28:31]
	v_mfma_f32_16x16x32_bf16 v[24:27], v[76:79], v[198:201], v[24:27]
	v_mfma_f32_16x16x32_bf16 v[20:23], v[68:71], v[212:215], v[20:23]
	v_mfma_f32_16x16x32_bf16 v[16:19], v[76:79], v[212:215], v[16:19]
	v_mfma_f32_16x16x32_bf16 v[44:47], v[154:157], v[178:181], v[44:47]
	v_mfma_f32_16x16x32_bf16 v[40:43], v[170:173], v[178:181], v[40:43]
	v_mfma_f32_16x16x32_bf16 v[36:39], v[154:157], v[186:189], v[36:39]
	v_mfma_f32_16x16x32_bf16 v[32:35], v[170:173], v[186:189], v[32:35]
	v_mfma_f32_16x16x32_bf16 v[12:15], v[154:157], v[194:197], v[12:15]
	v_mfma_f32_16x16x32_bf16 v[8:11], v[170:173], v[194:197], v[8:11]
	v_mfma_f32_16x16x32_bf16 v[4:7], v[154:157], v[202:205], v[4:7]
	v_mfma_f32_16x16x32_bf16 v[0:3], v[170:173], v[202:205], v[0:3]
	v_mfma_f32_16x16x32_bf16 v[44:47], v[162:165], v[182:185], v[44:47]
	v_mfma_f32_16x16x32_bf16 v[40:43], v[174:177], v[182:185], v[40:43]
	v_mfma_f32_16x16x32_bf16 v[36:39], v[162:165], v[190:193], v[36:39]
	v_mfma_f32_16x16x32_bf16 v[32:35], v[174:177], v[190:193], v[32:35]
	v_mfma_f32_16x16x32_bf16 v[12:15], v[162:165], v[198:201], v[12:15]
	v_mfma_f32_16x16x32_bf16 v[8:11], v[174:177], v[198:201], v[8:11]
	v_mfma_f32_16x16x32_bf16 v[4:7], v[162:165], v[212:215], v[4:7]
	v_mfma_f32_16x16x32_bf16 v[0:3], v[174:177], v[212:215], v[0:3]
	s_barrier
	s_add_i32 s47, 0, 0x18000
	s_add_i32 s48, 0, 0x1c000
	v_add_u32_e32 v76, s47, v159
	v_add_u32_e32 v174, s48, v159
	ds_read_b128 v[64:67], v76
	ds_read_b128 v[68:71], v76 offset:1024
	ds_read_b128 v[72:75], v76 offset:2048
	ds_read_b128 v[76:79], v76 offset:3072
	ds_read_b128 v[154:157], v174
	ds_read_b128 v[162:165], v174 offset:1024
	ds_read_b128 v[170:173], v174 offset:2048
	ds_read_b128 v[174:177], v174 offset:3072
	s_add_u32 s22, s22, 0x40000
	s_addc_u32 s23, s23, 0
	s_mov_b32 m0, s27
	v_lshl_add_u64 v[222:223], s[22:23], 0, v[148:149]
	ds_read_b128 v[178:181], v161 offset:32768
	ds_read_b128 v[182:185], v161 offset:33792
	ds_read_b128 v[186:189], v161 offset:34816
	ds_read_b128 v[190:193], v161 offset:35840
	ds_read_b128 v[194:197], v161 offset:36864
	ds_read_b128 v[198:201], v161 offset:37888
	ds_read_b128 v[202:205], v161 offset:38912
	ds_read_b128 v[212:215], v161 offset:39936
	global_load_lds_dwordx4 v[222:223], off
	v_lshl_add_u64 v[222:223], s[22:23], 0, v[146:147]
	s_mov_b32 m0, s28
	s_nop 0
	global_load_lds_dwordx4 v[222:223], off
	s_waitcnt vmcnt(8)
	s_waitcnt lgkmcnt(0)
	s_barrier
	s_waitcnt lgkmcnt(0)
	v_mfma_f32_16x16x32_bf16 v[140:143], v[64:67], v[178:181], v[140:143]
	v_mfma_f32_16x16x32_bf16 v[136:139], v[72:75], v[178:181], v[136:139]
	v_mfma_f32_16x16x32_bf16 v[132:135], v[64:67], v[186:189], v[132:135]
	v_mfma_f32_16x16x32_bf16 v[128:131], v[72:75], v[186:189], v[128:131]
	v_mfma_f32_16x16x32_bf16 v[108:111], v[64:67], v[194:197], v[108:111]
	v_mfma_f32_16x16x32_bf16 v[104:107], v[72:75], v[194:197], v[104:107]
	v_mfma_f32_16x16x32_bf16 v[100:103], v[64:67], v[202:205], v[100:103]
	v_mfma_f32_16x16x32_bf16 v[96:99], v[72:75], v[202:205], v[96:99]
	v_mfma_f32_16x16x32_bf16 v[140:143], v[68:71], v[182:185], v[140:143]
	v_mfma_f32_16x16x32_bf16 v[136:139], v[76:79], v[182:185], v[136:139]
	v_mfma_f32_16x16x32_bf16 v[132:135], v[68:71], v[190:193], v[132:135]
	v_mfma_f32_16x16x32_bf16 v[128:131], v[76:79], v[190:193], v[128:131]
	v_mfma_f32_16x16x32_bf16 v[108:111], v[68:71], v[198:201], v[108:111]
	v_mfma_f32_16x16x32_bf16 v[104:107], v[76:79], v[198:201], v[104:107]
	v_mfma_f32_16x16x32_bf16 v[100:103], v[68:71], v[212:215], v[100:103]
	v_mfma_f32_16x16x32_bf16 v[96:99], v[76:79], v[212:215], v[96:99]
	v_mfma_f32_16x16x32_bf16 v[124:127], v[154:157], v[178:181], v[124:127]
	v_mfma_f32_16x16x32_bf16 v[120:123], v[170:173], v[178:181], v[120:123]
	v_mfma_f32_16x16x32_bf16 v[116:119], v[154:157], v[186:189], v[116:119]
	v_mfma_f32_16x16x32_bf16 v[112:115], v[170:173], v[186:189], v[112:115]
	v_mfma_f32_16x16x32_bf16 v[92:95], v[154:157], v[194:197], v[92:95]
	v_mfma_f32_16x16x32_bf16 v[88:91], v[170:173], v[194:197], v[88:91]
	v_mfma_f32_16x16x32_bf16 v[84:87], v[154:157], v[202:205], v[84:87]
	v_mfma_f32_16x16x32_bf16 v[80:83], v[170:173], v[202:205], v[80:83]
	v_mfma_f32_16x16x32_bf16 v[124:127], v[162:165], v[182:185], v[124:127]
	v_mfma_f32_16x16x32_bf16 v[120:123], v[174:177], v[182:185], v[120:123]
	v_mfma_f32_16x16x32_bf16 v[116:119], v[162:165], v[190:193], v[116:119]
	v_mfma_f32_16x16x32_bf16 v[112:115], v[174:177], v[190:193], v[112:115]
	v_mfma_f32_16x16x32_bf16 v[92:95], v[162:165], v[198:201], v[92:95]
	v_mfma_f32_16x16x32_bf16 v[88:91], v[174:177], v[198:201], v[88:91]
	v_mfma_f32_16x16x32_bf16 v[84:87], v[162:165], v[212:215], v[84:87]
	v_mfma_f32_16x16x32_bf16 v[80:83], v[174:177], v[212:215], v[80:83]
	s_barrier
	s_add_i32 s22, s47, s24
	v_lshl_add_u64 v[166:167], v[166:167], 0, s[74:75]
	s_mov_b32 m0, s22
	ds_read_b128 v[178:181], v161 offset:49152
	ds_read_b128 v[182:185], v161 offset:50176
	ds_read_b128 v[186:189], v161 offset:51200
	ds_read_b128 v[190:193], v161 offset:52224
	ds_read_b128 v[194:197], v161 offset:53248
	ds_read_b128 v[198:201], v161 offset:54272
	ds_read_b128 v[202:205], v161 offset:55296
	ds_read_b128 v[212:215], v161 offset:56320
	global_load_lds_dwordx4 v[166:167], off
	s_add_i32 m0, s22, 0x2000
	s_add_u32 s20, s20, 0x40080
	v_lshl_add_u64 v[166:167], v[216:217], 0, s[74:75]
	s_addc_u32 s21, s21, 0
	s_add_i32 s22, s48, s24
	global_load_lds_dwordx4 v[166:167], off
	v_lshl_add_u64 v[166:167], s[20:21], 0, v[168:169]
	s_mov_b32 m0, s22
	s_nop 0
	global_load_lds_dwordx4 v[166:167], off
	v_lshl_add_u64 v[166:167], s[20:21], 0, v[144:145]
	s_add_i32 m0, s22, 0x2000
	s_nop 0
	global_load_lds_dwordx4 v[166:167], off
	v_lshl_add_u64 v[166:167], v[218:219], 0, s[74:75]
	s_mov_b32 m0, s31
	s_nop 0
	global_load_lds_dwordx4 v[166:167], off
	v_lshl_add_u64 v[166:167], v[220:221], 0, s[74:75]
	s_mov_b32 m0, s38
	s_nop 0
	global_load_lds_dwordx4 v[166:167], off
	s_waitcnt vmcnt(8)
	s_waitcnt lgkmcnt(0)
	s_barrier
	s_waitcnt lgkmcnt(0)
	v_mfma_f32_16x16x32_bf16 v[60:63], v[64:67], v[178:181], v[60:63]
	v_mfma_f32_16x16x32_bf16 v[56:59], v[72:75], v[178:181], v[56:59]
	v_mfma_f32_16x16x32_bf16 v[52:55], v[64:67], v[186:189], v[52:55]
	v_mfma_f32_16x16x32_bf16 v[48:51], v[72:75], v[186:189], v[48:51]
	v_mfma_f32_16x16x32_bf16 v[28:31], v[64:67], v[194:197], v[28:31]
	v_mfma_f32_16x16x32_bf16 v[24:27], v[72:75], v[194:197], v[24:27]
	v_mfma_f32_16x16x32_bf16 v[20:23], v[64:67], v[202:205], v[20:23]
	v_mfma_f32_16x16x32_bf16 v[16:19], v[72:75], v[202:205], v[16:19]
	v_mfma_f32_16x16x32_bf16 v[60:63], v[68:71], v[182:185], v[60:63]
	v_mfma_f32_16x16x32_bf16 v[56:59], v[76:79], v[182:185], v[56:59]
	v_mfma_f32_16x16x32_bf16 v[52:55], v[68:71], v[190:193], v[52:55]
	v_mfma_f32_16x16x32_bf16 v[48:51], v[76:79], v[190:193], v[48:51]
	v_mfma_f32_16x16x32_bf16 v[28:31], v[68:71], v[198:201], v[28:31]
	v_mfma_f32_16x16x32_bf16 v[24:27], v[76:79], v[198:201], v[24:27]
	v_mfma_f32_16x16x32_bf16 v[20:23], v[68:71], v[212:215], v[20:23]
	v_mfma_f32_16x16x32_bf16 v[16:19], v[76:79], v[212:215], v[16:19]
	v_mfma_f32_16x16x32_bf16 v[44:47], v[154:157], v[178:181], v[44:47]
	v_mfma_f32_16x16x32_bf16 v[40:43], v[170:173], v[178:181], v[40:43]
	v_mfma_f32_16x16x32_bf16 v[36:39], v[154:157], v[186:189], v[36:39]
	v_mfma_f32_16x16x32_bf16 v[32:35], v[170:173], v[186:189], v[32:35]
	v_mfma_f32_16x16x32_bf16 v[12:15], v[154:157], v[194:197], v[12:15]
	v_mfma_f32_16x16x32_bf16 v[8:11], v[170:173], v[194:197], v[8:11]
	v_mfma_f32_16x16x32_bf16 v[4:7], v[154:157], v[202:205], v[4:7]
	v_mfma_f32_16x16x32_bf16 v[0:3], v[170:173], v[202:205], v[0:3]
	v_mfma_f32_16x16x32_bf16 v[44:47], v[162:165], v[182:185], v[44:47]
	v_mfma_f32_16x16x32_bf16 v[40:43], v[174:177], v[182:185], v[40:43]
	v_mfma_f32_16x16x32_bf16 v[36:39], v[162:165], v[190:193], v[36:39]
	v_mfma_f32_16x16x32_bf16 v[32:35], v[174:177], v[190:193], v[32:35]
	v_mfma_f32_16x16x32_bf16 v[12:15], v[162:165], v[198:201], v[12:15]
	v_mfma_f32_16x16x32_bf16 v[8:11], v[174:177], v[198:201], v[8:11]
	v_mfma_f32_16x16x32_bf16 v[4:7], v[162:165], v[212:215], v[4:7]
	v_mfma_f32_16x16x32_bf16 v[0:3], v[174:177], v[212:215], v[0:3]
	s_barrier
	s_add_i32 s46, s46, 2
	s_add_u32 s44, s44, 0x100
	s_addc_u32 s45, s45, 0
	s_add_u32 s18, s18, 0x100
	s_addc_u32 s19, s19, 0
	s_cmp_gt_u32 s46, 13
	s_cbranch_scc0 .LBB0_655
	s_and_b64 vcc, exec, s[8:9]
	s_cbranch_vccz .LBB0_658
	s_barrier

.LBB0_779:
	s_add_u32 s26, s24, 0xfffc0080
	s_addc_u32 s27, s25, -1
	s_add_i32 s51, 0, 0x10000
	s_cmp_eq_u32 s50, 12
	s_cselect_b32 s29, s19, s27
	s_cselect_b32 s28, s46, s26
	s_cselect_b32 s27, s17, s49
	s_cselect_b32 s26, s47, s48
	s_add_i32 s54, 0, 0x14000
	v_add_u32_e32 v140, s51, v191
	v_add_u32_e32 v156, s54, v191
	ds_read_b128 v[116:119], v140
	ds_read_b128 v[120:123], v140 offset:1024
	ds_read_b128 v[124:127], v140 offset:2048
	ds_read_b128 v[140:143], v140 offset:3072
	ds_read_b128 v[144:147], v156
	ds_read_b128 v[148:151], v156 offset:1024
	ds_read_b128 v[152:155], v156 offset:2048
	ds_read_b128 v[156:159], v156 offset:3072
	v_lshl_add_u64 v[188:189], s[24:25], 0, v[174:175]
	s_add_i32 m0, s37, 0xc000
	ds_read_b128 v[170:173], v193
	ds_read_b128 v[176:179], v193 offset:1024
	ds_read_b128 v[180:183], v193 offset:2048
	ds_read_b128 v[184:187], v193 offset:3072
	ds_read_b128 v[194:197], v193 offset:4096
	ds_read_b128 v[198:201], v193 offset:5120
	ds_read_b128 v[202:205], v193 offset:6144
	ds_read_b128 v[212:215], v193 offset:7168
	global_load_lds_dwordx4 v[188:189], off
	v_lshl_add_u64 v[188:189], s[24:25], 0, v[166:167]
	s_add_i32 m0, s37, 0xe000
	s_nop 0
	global_load_lds_dwordx4 v[188:189], off
	s_waitcnt vmcnt(8)
	s_waitcnt lgkmcnt(0)
	s_barrier
	s_waitcnt lgkmcnt(0)
	v_mfma_f32_16x16x32_bf16 v[136:139], v[116:119], v[170:173], v[136:139]
	v_mfma_f32_16x16x32_bf16 v[92:95], v[124:127], v[170:173], v[92:95]
	v_mfma_f32_16x16x32_bf16 v[132:135], v[116:119], v[180:183], v[132:135]
	v_mfma_f32_16x16x32_bf16 v[88:91], v[124:127], v[180:183], v[88:91]
	v_mfma_f32_16x16x32_bf16 v[112:115], v[116:119], v[194:197], v[112:115]
	v_mfma_f32_16x16x32_bf16 v[80:83], v[124:127], v[194:197], v[80:83]
	v_mfma_f32_16x16x32_bf16 v[104:107], v[116:119], v[202:205], v[104:107]
	v_mfma_f32_16x16x32_bf16 v[72:75], v[124:127], v[202:205], v[72:75]
	v_mfma_f32_16x16x32_bf16 v[136:139], v[120:123], v[176:179], v[136:139]
	v_mfma_f32_16x16x32_bf16 v[92:95], v[140:143], v[176:179], v[92:95]
	v_mfma_f32_16x16x32_bf16 v[132:135], v[120:123], v[184:187], v[132:135]
	v_mfma_f32_16x16x32_bf16 v[88:91], v[140:143], v[184:187], v[88:91]
	v_mfma_f32_16x16x32_bf16 v[112:115], v[120:123], v[198:201], v[112:115]
	v_mfma_f32_16x16x32_bf16 v[80:83], v[140:143], v[198:201], v[80:83]
	v_mfma_f32_16x16x32_bf16 v[104:107], v[120:123], v[212:215], v[104:107]
	v_mfma_f32_16x16x32_bf16 v[72:75], v[140:143], v[212:215], v[72:75]
	v_mfma_f32_16x16x32_bf16 v[128:131], v[144:147], v[170:173], v[128:131]
	v_mfma_f32_16x16x32_bf16 v[84:87], v[152:155], v[170:173], v[84:87]
	v_mfma_f32_16x16x32_bf16 v[108:111], v[144:147], v[180:183], v[108:111]
	v_mfma_f32_16x16x32_bf16 v[76:79], v[152:155], v[180:183], v[76:79]
	v_mfma_f32_16x16x32_bf16 v[100:103], v[144:147], v[194:197], v[100:103]
	v_mfma_f32_16x16x32_bf16 v[68:71], v[152:155], v[194:197], v[68:71]
	v_mfma_f32_16x16x32_bf16 v[96:99], v[144:147], v[202:205], v[96:99]
	v_mfma_f32_16x16x32_bf16 v[64:67], v[152:155], v[202:205], v[64:67]
	v_mfma_f32_16x16x32_bf16 v[128:131], v[148:151], v[176:179], v[128:131]
	v_mfma_f32_16x16x32_bf16 v[84:87], v[156:159], v[176:179], v[84:87]
	v_mfma_f32_16x16x32_bf16 v[108:111], v[148:151], v[184:187], v[108:111]
	v_mfma_f32_16x16x32_bf16 v[76:79], v[156:159], v[184:187], v[76:79]
	v_mfma_f32_16x16x32_bf16 v[100:103], v[148:151], v[198:201], v[100:103]
	v_mfma_f32_16x16x32_bf16 v[68:71], v[156:159], v[198:201], v[68:71]
	v_mfma_f32_16x16x32_bf16 v[96:99], v[148:151], v[212:215], v[96:99]
	v_mfma_f32_16x16x32_bf16 v[64:67], v[156:159], v[212:215], v[64:67]
	s_barrier
	s_add_i32 s51, s51, s36
	v_lshl_add_u64 v[188:189], s[26:27], 0, v[168:169]
	s_mov_b32 m0, s51
	ds_read_b128 v[170:173], v193 offset:16384
	ds_read_b128 v[176:179], v193 offset:17408
	ds_read_b128 v[180:183], v193 offset:18432
	ds_read_b128 v[184:187], v193 offset:19456
	ds_read_b128 v[194:197], v193 offset:20480
	ds_read_b128 v[198:201], v193 offset:21504
	ds_read_b128 v[202:205], v193 offset:22528
	ds_read_b128 v[212:215], v193 offset:23552
	global_load_lds_dwordx4 v[188:189], off
	s_add_i32 m0, s51, 0x2000
	s_add_u32 s52, s26, 0x40000
	v_lshl_add_u64 v[216:217], s[26:27], 0, v[160:161]
	s_addc_u32 s53, s27, 0
	s_add_i32 s51, s54, s36
	global_load_lds_dwordx4 v[216:217], off
	v_lshl_add_u64 v[218:219], s[52:53], 0, v[168:169]
	s_mov_b32 m0, s51
	v_lshl_add_u64 v[220:221], s[28:29], 0, v[162:163]
	global_load_lds_dwordx4 v[218:219], off
	v_lshl_add_u64 v[218:219], s[52:53], 0, v[160:161]
	s_add_i32 m0, s51, 0x2000
	s_nop 0
	global_load_lds_dwordx4 v[218:219], off
	v_lshl_add_u64 v[218:219], s[28:29], 0, v[164:165]
	s_mov_b32 m0, s37
	s_nop 0
	global_load_lds_dwordx4 v[218:219], off
	s_mov_b32 m0, s38
	s_nop 0
	global_load_lds_dwordx4 v[220:221], off
	s_waitcnt vmcnt(8)
	s_waitcnt lgkmcnt(0)
	s_barrier
	s_waitcnt lgkmcnt(0)
	v_mfma_f32_16x16x32_bf16 v[60:63], v[116:119], v[170:173], v[60:63]
	v_mfma_f32_16x16x32_bf16 v[28:31], v[124:127], v[170:173], v[28:31]
	v_mfma_f32_16x16x32_bf16 v[56:59], v[116:119], v[180:183], v[56:59]
	v_mfma_f32_16x16x32_bf16 v[24:27], v[124:127], v[180:183], v[24:27]
	v_mfma_f32_16x16x32_bf16 v[48:51], v[116:119], v[194:197], v[48:51]
	v_mfma_f32_16x16x32_bf16 v[16:19], v[124:127], v[194:197], v[16:19]
	v_mfma_f32_16x16x32_bf16 v[40:43], v[116:119], v[202:205], v[40:43]
	v_mfma_f32_16x16x32_bf16 v[8:11], v[124:127], v[202:205], v[8:11]
	v_mfma_f32_16x16x32_bf16 v[60:63], v[120:123], v[176:179], v[60:63]
	v_mfma_f32_16x16x32_bf16 v[28:31], v[140:143], v[176:179], v[28:31]
	v_mfma_f32_16x16x32_bf16 v[56:59], v[120:123], v[184:187], v[56:59]
	v_mfma_f32_16x16x32_bf16 v[24:27], v[140:143], v[184:187], v[24:27]
	v_mfma_f32_16x16x32_bf16 v[48:51], v[120:123], v[198:201], v[48:51]
	v_mfma_f32_16x16x32_bf16 v[16:19], v[140:143], v[198:201], v[16:19]
	v_mfma_f32_16x16x32_bf16 v[40:43], v[120:123], v[212:215], v[40:43]
	v_mfma_f32_16x16x32_bf16 v[8:11], v[140:143], v[212:215], v[8:11]
	v_mfma_f32_16x16x32_bf16 v[52:55], v[144:147], v[170:173], v[52:55]
	v_mfma_f32_16x16x32_bf16 v[20:23], v[152:155], v[170:173], v[20:23]
	v_mfma_f32_16x16x32_bf16 v[44:47], v[144:147], v[180:183], v[44:47]
	v_mfma_f32_16x16x32_bf16 v[12:15], v[152:155], v[180:183], v[12:15]
	v_mfma_f32_16x16x32_bf16 v[36:39], v[144:147], v[194:197], v[36:39]
	v_mfma_f32_16x16x32_bf16 v[4:7], v[152:155], v[194:197], v[4:7]
	v_mfma_f32_16x16x32_bf16 v[32:35], v[144:147], v[202:205], v[32:35]
	v_mfma_f32_16x16x32_bf16 v[0:3], v[152:155], v[202:205], v[0:3]
	v_mfma_f32_16x16x32_bf16 v[52:55], v[148:151], v[176:179], v[52:55]
	v_mfma_f32_16x16x32_bf16 v[20:23], v[156:159], v[176:179], v[20:23]
	v_mfma_f32_16x16x32_bf16 v[44:47], v[148:151], v[184:187], v[44:47]
	v_mfma_f32_16x16x32_bf16 v[12:15], v[156:159], v[184:187], v[12:15]
	v_mfma_f32_16x16x32_bf16 v[36:39], v[148:151], v[198:201], v[36:39]
	v_mfma_f32_16x16x32_bf16 v[4:7], v[156:159], v[198:201], v[4:7]
	v_mfma_f32_16x16x32_bf16 v[32:35], v[148:151], v[212:215], v[32:35]
	v_mfma_f32_16x16x32_bf16 v[0:3], v[156:159], v[212:215], v[0:3]
	s_barrier
	s_add_i32 s51, 0, 0x18000
	s_add_i32 s52, 0, 0x1c000
	v_add_u32_e32 v140, s51, v191
	v_add_u32_e32 v156, s52, v191
	ds_read_b128 v[116:119], v140
	ds_read_b128 v[120:123], v140 offset:1024
	ds_read_b128 v[124:127], v140 offset:2048
	ds_read_b128 v[140:143], v140 offset:3072
	ds_read_b128 v[144:147], v156
	ds_read_b128 v[148:151], v156 offset:1024
	ds_read_b128 v[152:155], v156 offset:2048
	ds_read_b128 v[156:159], v156 offset:3072
	s_add_u32 s28, s28, 0x40000
	s_addc_u32 s29, s29, 0
	s_mov_b32 m0, s39
	v_lshl_add_u64 v[222:223], s[28:29], 0, v[164:165]
	ds_read_b128 v[170:173], v193 offset:32768
	ds_read_b128 v[176:179], v193 offset:33792
	ds_read_b128 v[180:183], v193 offset:34816
	ds_read_b128 v[184:187], v193 offset:35840
	ds_read_b128 v[194:197], v193 offset:36864
	ds_read_b128 v[198:201], v193 offset:37888
	ds_read_b128 v[202:205], v193 offset:38912
	ds_read_b128 v[212:215], v193 offset:39936
	global_load_lds_dwordx4 v[222:223], off
	v_lshl_add_u64 v[222:223], s[28:29], 0, v[162:163]
	s_mov_b32 m0, s40
	s_nop 0
	global_load_lds_dwordx4 v[222:223], off
	s_waitcnt vmcnt(8)
	s_waitcnt lgkmcnt(0)
	s_barrier
	s_waitcnt lgkmcnt(0)
	v_mfma_f32_16x16x32_bf16 v[136:139], v[116:119], v[170:173], v[136:139]
	v_mfma_f32_16x16x32_bf16 v[92:95], v[124:127], v[170:173], v[92:95]
	v_mfma_f32_16x16x32_bf16 v[132:135], v[116:119], v[180:183], v[132:135]
	v_mfma_f32_16x16x32_bf16 v[88:91], v[124:127], v[180:183], v[88:91]
	v_mfma_f32_16x16x32_bf16 v[112:115], v[116:119], v[194:197], v[112:115]
	v_mfma_f32_16x16x32_bf16 v[80:83], v[124:127], v[194:197], v[80:83]
	v_mfma_f32_16x16x32_bf16 v[104:107], v[116:119], v[202:205], v[104:107]
	v_mfma_f32_16x16x32_bf16 v[72:75], v[124:127], v[202:205], v[72:75]
	v_mfma_f32_16x16x32_bf16 v[136:139], v[120:123], v[176:179], v[136:139]
	v_mfma_f32_16x16x32_bf16 v[92:95], v[140:143], v[176:179], v[92:95]
	v_mfma_f32_16x16x32_bf16 v[132:135], v[120:123], v[184:187], v[132:135]
	v_mfma_f32_16x16x32_bf16 v[88:91], v[140:143], v[184:187], v[88:91]
	v_mfma_f32_16x16x32_bf16 v[112:115], v[120:123], v[198:201], v[112:115]
	v_mfma_f32_16x16x32_bf16 v[80:83], v[140:143], v[198:201], v[80:83]
	v_mfma_f32_16x16x32_bf16 v[104:107], v[120:123], v[212:215], v[104:107]
	v_mfma_f32_16x16x32_bf16 v[72:75], v[140:143], v[212:215], v[72:75]
	v_mfma_f32_16x16x32_bf16 v[128:131], v[144:147], v[170:173], v[128:131]
	v_mfma_f32_16x16x32_bf16 v[84:87], v[152:155], v[170:173], v[84:87]
	v_mfma_f32_16x16x32_bf16 v[108:111], v[144:147], v[180:183], v[108:111]
	v_mfma_f32_16x16x32_bf16 v[76:79], v[152:155], v[180:183], v[76:79]
	v_mfma_f32_16x16x32_bf16 v[100:103], v[144:147], v[194:197], v[100:103]
	v_mfma_f32_16x16x32_bf16 v[68:71], v[152:155], v[194:197], v[68:71]
	v_mfma_f32_16x16x32_bf16 v[96:99], v[144:147], v[202:205], v[96:99]
	v_mfma_f32_16x16x32_bf16 v[64:67], v[152:155], v[202:205], v[64:67]
	v_mfma_f32_16x16x32_bf16 v[128:131], v[148:151], v[176:179], v[128:131]
	v_mfma_f32_16x16x32_bf16 v[84:87], v[156:159], v[176:179], v[84:87]
	v_mfma_f32_16x16x32_bf16 v[108:111], v[148:151], v[184:187], v[108:111]
	v_mfma_f32_16x16x32_bf16 v[76:79], v[156:159], v[184:187], v[76:79]
	v_mfma_f32_16x16x32_bf16 v[100:103], v[148:151], v[198:201], v[100:103]
	v_mfma_f32_16x16x32_bf16 v[68:71], v[156:159], v[198:201], v[68:71]
	v_mfma_f32_16x16x32_bf16 v[96:99], v[148:151], v[212:215], v[96:99]
	v_mfma_f32_16x16x32_bf16 v[64:67], v[156:159], v[212:215], v[64:67]
	s_barrier
	s_add_i32 s28, s51, s36
	v_lshl_add_u64 v[188:189], v[188:189], 0, s[74:75]
	s_mov_b32 m0, s28
	ds_read_b128 v[170:173], v193 offset:49152
	ds_read_b128 v[176:179], v193 offset:50176
	ds_read_b128 v[180:183], v193 offset:51200
	ds_read_b128 v[184:187], v193 offset:52224
	ds_read_b128 v[194:197], v193 offset:53248
	ds_read_b128 v[198:201], v193 offset:54272
	ds_read_b128 v[202:205], v193 offset:55296
	ds_read_b128 v[212:215], v193 offset:56320
	global_load_lds_dwordx4 v[188:189], off
	s_add_i32 m0, s28, 0x2000
	s_add_u32 s26, s26, 0x40080
	v_lshl_add_u64 v[188:189], v[216:217], 0, s[74:75]
	s_addc_u32 s27, s27, 0
	s_add_i32 s28, s52, s36
	global_load_lds_dwordx4 v[188:189], off
	v_lshl_add_u64 v[188:189], s[26:27], 0, v[168:169]
	s_mov_b32 m0, s28
	s_nop 0
	global_load_lds_dwordx4 v[188:189], off
	v_lshl_add_u64 v[188:189], s[26:27], 0, v[160:161]
	s_add_i32 m0, s28, 0x2000
	s_nop 0
	global_load_lds_dwordx4 v[188:189], off
	v_lshl_add_u64 v[188:189], v[218:219], 0, s[74:75]
	s_mov_b32 m0, s41
	s_nop 0
	global_load_lds_dwordx4 v[188:189], off
	v_lshl_add_u64 v[188:189], v[220:221], 0, s[74:75]
	s_mov_b32 m0, s42
	s_nop 0
	global_load_lds_dwordx4 v[188:189], off
	s_waitcnt vmcnt(8)
	s_waitcnt lgkmcnt(0)
	s_barrier
	s_waitcnt lgkmcnt(0)
	v_mfma_f32_16x16x32_bf16 v[60:63], v[116:119], v[170:173], v[60:63]
	v_mfma_f32_16x16x32_bf16 v[28:31], v[124:127], v[170:173], v[28:31]
	v_mfma_f32_16x16x32_bf16 v[56:59], v[116:119], v[180:183], v[56:59]
	v_mfma_f32_16x16x32_bf16 v[24:27], v[124:127], v[180:183], v[24:27]
	v_mfma_f32_16x16x32_bf16 v[48:51], v[116:119], v[194:197], v[48:51]
	v_mfma_f32_16x16x32_bf16 v[16:19], v[124:127], v[194:197], v[16:19]
	v_mfma_f32_16x16x32_bf16 v[40:43], v[116:119], v[202:205], v[40:43]
	v_mfma_f32_16x16x32_bf16 v[8:11], v[124:127], v[202:205], v[8:11]
	v_mfma_f32_16x16x32_bf16 v[60:63], v[120:123], v[176:179], v[60:63]
	v_mfma_f32_16x16x32_bf16 v[28:31], v[140:143], v[176:179], v[28:31]
	v_mfma_f32_16x16x32_bf16 v[56:59], v[120:123], v[184:187], v[56:59]
	v_mfma_f32_16x16x32_bf16 v[24:27], v[140:143], v[184:187], v[24:27]
	v_mfma_f32_16x16x32_bf16 v[48:51], v[120:123], v[198:201], v[48:51]
	v_mfma_f32_16x16x32_bf16 v[16:19], v[140:143], v[198:201], v[16:19]
	v_mfma_f32_16x16x32_bf16 v[40:43], v[120:123], v[212:215], v[40:43]
	v_mfma_f32_16x16x32_bf16 v[8:11], v[140:143], v[212:215], v[8:11]
	v_mfma_f32_16x16x32_bf16 v[52:55], v[144:147], v[170:173], v[52:55]
	v_mfma_f32_16x16x32_bf16 v[20:23], v[152:155], v[170:173], v[20:23]
	v_mfma_f32_16x16x32_bf16 v[44:47], v[144:147], v[180:183], v[44:47]
	v_mfma_f32_16x16x32_bf16 v[12:15], v[152:155], v[180:183], v[12:15]
	v_mfma_f32_16x16x32_bf16 v[36:39], v[144:147], v[194:197], v[36:39]
	v_mfma_f32_16x16x32_bf16 v[4:7], v[152:155], v[194:197], v[4:7]
	v_mfma_f32_16x16x32_bf16 v[32:35], v[144:147], v[202:205], v[32:35]
	v_mfma_f32_16x16x32_bf16 v[0:3], v[152:155], v[202:205], v[0:3]
	v_mfma_f32_16x16x32_bf16 v[52:55], v[148:151], v[176:179], v[52:55]
	v_mfma_f32_16x16x32_bf16 v[20:23], v[156:159], v[176:179], v[20:23]
	v_mfma_f32_16x16x32_bf16 v[44:47], v[148:151], v[184:187], v[44:47]
	v_mfma_f32_16x16x32_bf16 v[12:15], v[156:159], v[184:187], v[12:15]
	v_mfma_f32_16x16x32_bf16 v[36:39], v[148:151], v[198:201], v[36:39]
	v_mfma_f32_16x16x32_bf16 v[4:7], v[156:159], v[198:201], v[4:7]
	v_mfma_f32_16x16x32_bf16 v[32:35], v[148:151], v[212:215], v[32:35]
	v_mfma_f32_16x16x32_bf16 v[0:3], v[156:159], v[212:215], v[0:3]
	s_barrier
	s_add_i32 s50, s50, 2
	s_add_u32 s48, s48, 0x100
	s_addc_u32 s49, s49, 0
	s_add_u32 s24, s24, 0x100
	s_addc_u32 s25, s25, 0
	s_cmp_gt_u32 s50, 13
	s_cbranch_scc0 .LBB0_779
	s_and_b64 vcc, exec, s[10:11]
	s_cbranch_vccz .LBB0_782
	s_barrier
.LBB0_782:
	v_lshl_or_b32 v184, s44, 7, v192
	v_ashrrev_i32_e32 v185, 31, v184
	v_lshlrev_b64 v[116:117], 2, v[184:185]
	v_lshl_add_u64 v[182:183], s[0:1], 0, v[116:117]
	v_lshl_add_u64 v[180:181], s[12:13], 0, v[116:117]
	v_lshl_add_u64 v[178:179], s[14:15], 0, v[116:117]
	v_lshl_add_u64 v[176:177], s[2:3], 0, v[116:117]
	global_load_dwordx4 v[140:143], v[182:183], off offset:16
	global_load_dwordx4 v[156:159], v[182:183], off
	global_load_dwordx4 v[116:119], v[180:181], off offset:16
	global_load_dwordx4 v[144:147], v[180:181], off
	global_load_dwordx4 v[120:123], v[178:179], off offset:16
	global_load_dwordx4 v[148:151], v[178:179], off
	global_load_dwordx4 v[124:127], v[176:177], off offset:16
	global_load_dwordx4 v[152:155], v[176:177], off
	v_mov_b32_e32 v186, v169
	v_mov_b32_dpp v187, v132 row_ror:15 row_mask:0xf bank_mask:0xf
	s_nop 0
	v_mov_b32_dpp v186, v136 row_shr:1 row_mask:0xf bank_mask:0xf
	v_mov_b32_dpp v170, v136 row_ror:1 row_mask:0xf bank_mask:0xf
	v_mov_b32_dpp v187, v136 row_shl:1 row_mask:0xf bank_mask:0xf
	s_nop 0
	v_mov_b32_dpp v170, v132 row_shr:1 row_mask:0xf bank_mask:0xf
	v_mov_b32_dpp v171, v112 row_ror:15 row_mask:0xf bank_mask:0xf
	v_mov_b32_dpp v172, v132 row_ror:1 row_mask:0xf bank_mask:0xf
	s_nop 0
	v_mov_b32_dpp v171, v132 row_shl:1 row_mask:0xf bank_mask:0xf
	v_mov_b32_dpp v173, v104 row_ror:15 row_mask:0xf bank_mask:0xf
	v_mov_b32_dpp v172, v112 row_shr:1 row_mask:0xf bank_mask:0xf
	s_nop 0
	v_mov_b32_dpp v173, v112 row_shl:1 row_mask:0xf bank_mask:0xf
	v_mov_b32_e32 v189, v169
	v_mov_b32_dpp v188, v112 row_ror:1 row_mask:0xf bank_mask:0xf
	v_lshl_add_u32 v194, s45, 8, v190
	v_mov_b32_dpp v189, v104 row_shl:1 row_mask:0xf bank_mask:0xf
	v_mov_b32_dpp v188, v104 row_shr:1 row_mask:0xf bank_mask:0xf
	s_movk_i32 s17, 0xb00
	v_readlane_b32 s24, v253, 0
	v_readlane_b32 s25, v253, 1
	v_readlane_b32 s26, v253, 2
	v_readlane_b32 s27, v253, 3
	s_andn2_b64 vcc, exec, s[6:7]
	s_waitcnt vmcnt(0)
	v_mov_b32_e32 v196, v156
	v_mov_b32_e32 v197, v148
	v_pk_mul_f32 v[186:187], v[196:197], v[186:187]
	v_pk_mul_f32 v[170:171], v[196:197], v[170:171]
	v_fma_f32 v136, v136, v144, v186
	v_add_f32_e32 v136, v136, v187
	v_add_f32_e32 v136, v152, v136
	v_mul_f32_e32 v148, 0xbfb8aa3b, v136
	v_exp_f32_e32 v148, v148
	v_fma_f32 v132, v132, v144, v170
	v_add_f32_e32 v132, v132, v171
	v_add_f32_e32 v132, v152, v132
	v_add_f32_e32 v148, 1.0, v148
	v_rcp_f32_e32 v148, v148
	v_pk_mul_f32 v[170:171], v[196:197], v[172:173]
	v_fma_f32 v112, v112, v144, v170
	v_mul_f32_e32 v136, v136, v148
	v_mul_f32_e32 v128, v128, v136
	v_mul_f32_e32 v136, 0xbfb8aa3b, v132
	v_exp_f32_e32 v136, v136
	v_add_f32_e32 v112, v112, v171
	v_add_f32_e32 v112, v152, v112
	v_pk_mul_f32 v[170:171], v[196:197], v[188:189]
	v_add_f32_e32 v136, 1.0, v136
	v_rcp_f32_e32 v136, v136
	v_mov_b32_e32 v148, v157
	v_mul_f32_e32 v132, v132, v136
	v_mul_f32_e32 v108, v108, v132
	v_mul_f32_e32 v132, 0xbfb8aa3b, v112
	v_exp_f32_e32 v132, v132
	v_mov_b32_dpp v188, v137 row_ror:1 row_mask:0xf bank_mask:0xf
	v_mov_b32_dpp v189, v113 row_ror:15 row_mask:0xf bank_mask:0xf
	v_add_f32_e32 v132, 1.0, v132
	v_rcp_f32_e32 v132, v132
	v_mov_b32_dpp v188, v133 row_shr:1 row_mask:0xf bank_mask:0xf
	v_mov_b32_dpp v189, v133 row_shl:1 row_mask:0xf bank_mask:0xf
	v_mov_b32_dpp v186, v133 row_ror:1 row_mask:0xf bank_mask:0xf
	v_mul_f32_e32 v112, v112, v132
	v_mul_f32_e32 v112, v100, v112
	v_fma_f32 v100, v104, v144, v170
	v_add_f32_e32 v100, v100, v171
	v_add_f32_e32 v100, v152, v100
	v_mul_f32_e32 v104, 0xbfb8aa3b, v100
	v_exp_f32_e32 v104, v104
	v_mov_b32_e32 v170, v169
	v_mov_b32_dpp v187, v105 row_ror:15 row_mask:0xf bank_mask:0xf
	v_add_f32_e32 v104, 1.0, v104
	v_rcp_f32_e32 v104, v104
	v_mov_b32_dpp v171, v133 row_ror:15 row_mask:0xf bank_mask:0xf
	v_mov_b32_dpp v170, v137 row_shr:1 row_mask:0xf bank_mask:0xf
	v_mov_b32_dpp v186, v113 row_shr:1 row_mask:0xf bank_mask:0xf
	v_mov_b32_dpp v171, v137 row_shl:1 row_mask:0xf bank_mask:0xf
	v_pk_mul_f32 v[156:157], v[148:149], v[170:171]
	v_mul_f32_e32 v100, v100, v104
	v_fma_f32 v104, v137, v145, v156
	v_add_f32_e32 v104, v104, v157
	v_add_f32_e32 v104, v153, v104
	v_mul_f32_e32 v132, 0xbfb8aa3b, v104
	v_exp_f32_e32 v132, v132
	v_pk_mul_f32 v[136:137], v[148:149], v[188:189]
	v_mov_b32_dpp v187, v113 row_shl:1 row_mask:0xf bank_mask:0xf
	v_mul_f32_e32 v96, v96, v100
	v_add_f32_e32 v132, 1.0, v132
	v_rcp_f32_e32 v132, v132
	v_mov_b32_e32 v144, v169
	v_mov_b32_e32 v152, v158
	v_mul_f32_e32 v104, v104, v132
	v_mul_f32_e32 v104, v129, v104
	v_fma_f32 v129, v133, v145, v136
	v_add_f32_e32 v129, v129, v137
	v_add_f32_e32 v129, v153, v129
	v_mul_f32_e32 v132, 0xbfb8aa3b, v129
	v_exp_f32_e32 v132, v132
	v_mov_b32_dpp v100, v113 row_ror:1 row_mask:0xf bank_mask:0xf
	v_mov_b32_dpp v144, v138 row_shr:1 row_mask:0xf bank_mask:0xf
	v_add_f32_e32 v132, 1.0, v132
	v_rcp_f32_e32 v132, v132
	v_mov_b32_dpp v100, v105 row_shr:1 row_mask:0xf bank_mask:0xf
	v_mov_b32_dpp v136, v134 row_ror:1 row_mask:0xf bank_mask:0xf
	v_mul_f32_e32 v129, v129, v132
	v_pk_mul_f32 v[132:133], v[148:149], v[186:187]
	v_mul_f32_e32 v109, v109, v129
	v_fma_f32 v113, v113, v145, v132
	v_add_f32_e32 v113, v113, v133
	v_add_f32_e32 v113, v153, v113
	v_mul_f32_e32 v129, 0xbfb8aa3b, v113
	v_exp_f32_e32 v129, v129
	v_mov_b32_dpp v137, v106 row_ror:15 row_mask:0xf bank_mask:0xf
	v_add_f32_e32 v129, 1.0, v129
	v_rcp_f32_e32 v129, v129
	v_mov_b32_dpp v132, v138 row_ror:1 row_mask:0xf bank_mask:0xf
	v_mov_b32_dpp v133, v114 row_ror:15 row_mask:0xf bank_mask:0xf
	v_mov_b32_dpp v136, v114 row_shr:1 row_mask:0xf bank_mask:0xf
	v_mul_f32_e32 v113, v113, v129
	v_mul_f32_e32 v113, v101, v113
	v_mov_b32_e32 v101, v169
	v_mov_b32_dpp v132, v134 row_shr:1 row_mask:0xf bank_mask:0xf
	v_mov_b32_dpp v133, v134 row_shl:1 row_mask:0xf bank_mask:0xf
	v_mov_b32_dpp v101, v105 row_shl:1 row_mask:0xf bank_mask:0xf
	v_pk_mul_f32 v[100:101], v[148:149], v[100:101]
	v_mov_b32_dpp v137, v114 row_shl:1 row_mask:0xf bank_mask:0xf
	v_fma_f32 v100, v105, v145, v100
	v_add_f32_e32 v100, v100, v101
	v_add_f32_e32 v100, v153, v100
	v_mul_f32_e32 v101, 0xbfb8aa3b, v100
	v_exp_f32_e32 v101, v101
	v_mov_b32_e32 v153, v150
	v_pk_mul_f32 v[132:133], v[152:153], v[132:133]
	v_add_f32_e32 v101, 1.0, v101
	v_rcp_f32_e32 v101, v101
	v_mov_b32_dpp v145, v134 row_ror:15 row_mask:0xf bank_mask:0xf
	v_mov_b32_e32 v149, v169
	s_nop 0
	v_mov_b32_dpp v145, v138 row_shl:1 row_mask:0xf bank_mask:0xf
	v_mul_f32_e32 v100, v100, v101
	v_pk_mul_f32 v[144:145], v[152:153], v[144:145]
	v_mul_f32_e32 v100, v97, v100
	v_fma_f32 v97, v138, v146, v144
	v_add_f32_e32 v97, v97, v145
	v_add_f32_e32 v97, v154, v97
	v_mul_f32_e32 v101, 0xbfb8aa3b, v97
	v_exp_f32_e32 v101, v101
	v_mov_b32_dpp v148, v114 row_ror:1 row_mask:0xf bank_mask:0xf
	v_mov_b32_dpp v149, v106 row_shl:1 row_mask:0xf bank_mask:0xf
	v_add_f32_e32 v101, 1.0, v101
	v_rcp_f32_e32 v101, v101
	v_mov_b32_dpp v148, v106 row_shr:1 row_mask:0xf bank_mask:0xf
	v_mov_b32_dpp v145, v135 row_ror:15 row_mask:0xf bank_mask:0xf
	v_mov_b32_e32 v144, v169
	v_mul_f32_e32 v97, v97, v101
	v_fma_f32 v101, v134, v146, v132
	v_add_f32_e32 v101, v101, v133
	v_add_f32_e32 v101, v154, v101
	v_mul_f32_e32 v105, 0xbfb8aa3b, v101
	v_exp_f32_e32 v105, v105
	v_pk_mul_f32 v[132:133], v[152:153], v[136:137]
	v_mov_b32_dpp v144, v139 row_shr:1 row_mask:0xf bank_mask:0xf
	v_mov_b32_dpp v145, v139 row_shl:1 row_mask:0xf bank_mask:0xf
	v_add_f32_e32 v105, 1.0, v105
	v_rcp_f32_e32 v105, v105
	v_mov_b32_e32 v150, v159
	v_pk_mul_f32 v[144:145], v[150:151], v[144:145]
	v_mul_f32_e32 v97, v130, v97
	v_mul_f32_e32 v101, v101, v105
	v_fma_f32 v105, v114, v146, v132
	v_add_f32_e32 v105, v105, v133
	v_add_f32_e32 v105, v154, v105
	v_mul_f32_e32 v101, v110, v101
	v_mul_f32_e32 v110, 0xbfb8aa3b, v105
	v_exp_f32_e32 v110, v110
	v_pk_mul_f32 v[132:133], v[152:153], v[148:149]
	v_add_f32_e32 v110, 1.0, v110
	v_rcp_f32_e32 v110, v110
	v_mov_b32_dpp v136, v135 row_ror:1 row_mask:0xf bank_mask:0xf
	v_mov_b32_dpp v137, v107 row_ror:15 row_mask:0xf bank_mask:0xf
	v_mov_b32_e32 v134, v140
	v_mul_f32_e32 v105, v105, v110
	v_mul_f32_e32 v102, v102, v105
	v_fma_f32 v105, v106, v146, v132
	v_add_f32_e32 v105, v105, v133
	v_add_f32_e32 v105, v154, v105
	v_mul_f32_e32 v106, 0xbfb8aa3b, v105
	v_exp_f32_e32 v106, v106
	v_mov_b32_dpp v136, v115 row_shr:1 row_mask:0xf bank_mask:0xf
	v_add_f32_e32 v106, 1.0, v106
	v_rcp_f32_e32 v106, v106
	v_mov_b32_dpp v132, v139 row_ror:1 row_mask:0xf bank_mask:0xf
	v_mov_b32_dpp v133, v115 row_ror:15 row_mask:0xf bank_mask:0xf
	v_mov_b32_dpp v137, v115 row_shl:1 row_mask:0xf bank_mask:0xf
	v_mul_f32_e32 v105, v105, v106
	v_mul_f32_e32 v98, v98, v105
	v_fma_f32 v105, v139, v147, v144
	v_add_f32_e32 v105, v105, v145
	v_add_f32_e32 v105, v155, v105
	v_mul_f32_e32 v106, 0xbfb8aa3b, v105
	v_exp_f32_e32 v106, v106
	v_mov_b32_dpp v132, v135 row_shr:1 row_mask:0xf bank_mask:0xf
	v_mov_b32_dpp v133, v135 row_shl:1 row_mask:0xf bank_mask:0xf
	v_add_f32_e32 v106, 1.0, v106
	v_rcp_f32_e32 v106, v106
	v_mov_b32_dpp v110, v115 row_ror:1 row_mask:0xf bank_mask:0xf
	v_mul_f32_e32 v105, v105, v106
	v_mul_f32_e32 v105, v131, v105
	v_pk_mul_f32 v[130:131], v[150:151], v[132:133]
	v_mov_b32_dpp v110, v107 row_shr:1 row_mask:0xf bank_mask:0xf
	v_fma_f32 v106, v135, v147, v130
	v_add_f32_e32 v106, v106, v131
	v_add_f32_e32 v106, v155, v106
	v_mul_f32_e32 v114, 0xbfb8aa3b, v106
	v_exp_f32_e32 v114, v114
	v_pk_mul_f32 v[130:131], v[150:151], v[136:137]
	v_mov_b32_e32 v135, v120
	v_add_f32_e32 v114, 1.0, v114
	v_rcp_f32_e32 v114, v114
	v_mov_b32_dpp v132, v80 row_ror:1 row_mask:0xf bank_mask:0xf
	v_mov_b32_e32 v133, v169
	v_mov_b32_e32 v120, v141
	v_mul_f32_e32 v106, v106, v114
	v_mul_f32_e32 v106, v111, v106
	v_fma_f32 v111, v115, v147, v130
	v_add_f32_e32 v111, v111, v131
	v_add_f32_e32 v111, v155, v111
	v_mul_f32_e32 v114, 0xbfb8aa3b, v111
	v_exp_f32_e32 v114, v114
	v_mov_b32_e32 v130, v169
	v_add_f32_e32 v114, 1.0, v114
	v_rcp_f32_e32 v114, v114
	v_mov_b32_dpp v131, v88 row_ror:15 row_mask:0xf bank_mask:0xf
	v_mov_b32_dpp v130, v92 row_shr:1 row_mask:0xf bank_mask:0xf
	v_mov_b32_dpp v115, v72 row_ror:15 row_mask:0xf bank_mask:0xf
	v_mul_f32_e32 v111, v111, v114
	v_mul_f32_e32 v103, v103, v111
	v_mov_b32_e32 v111, v169
	v_mov_b32_dpp v131, v92 row_shl:1 row_mask:0xf bank_mask:0xf
	v_pk_mul_f32 v[130:131], v[134:135], v[130:131]
	v_mov_b32_dpp v111, v107 row_shl:1 row_mask:0xf bank_mask:0xf
	v_pk_mul_f32 v[110:111], v[150:151], v[110:111]
	v_fma_f32 v107, v107, v147, v110
	v_add_f32_e32 v107, v107, v111
	v_add_f32_e32 v107, v155, v107
	v_mul_f32_e32 v110, 0xbfb8aa3b, v107
	v_exp_f32_e32 v110, v110
	v_mov_b32_dpp v114, v88 row_ror:1 row_mask:0xf bank_mask:0xf
	v_mov_b32_dpp v115, v80 row_shl:1 row_mask:0xf bank_mask:0xf
	v_add_f32_e32 v110, 1.0, v110
	v_rcp_f32_e32 v110, v110
	v_mov_b32_dpp v111, v80 row_ror:15 row_mask:0xf bank_mask:0xf
	v_mov_b32_dpp v114, v80 row_shr:1 row_mask:0xf bank_mask:0xf
	v_mov_b32_dpp v132, v72 row_shr:1 row_mask:0xf bank_mask:0xf
	v_mul_f32_e32 v107, v107, v110
	v_mul_f32_e32 v99, v99, v107
	v_mov_b32_dpp v111, v88 row_shl:1 row_mask:0xf bank_mask:0xf
	v_mov_b32_dpp v110, v92 row_ror:1 row_mask:0xf bank_mask:0xf
	v_fma_f32 v92, v92, v116, v130
	v_add_f32_e32 v92, v92, v131
	v_add_f32_e32 v92, v124, v92
	v_mul_f32_e32 v107, 0xbfb8aa3b, v92
	v_exp_f32_e32 v107, v107
	v_mov_b32_dpp v110, v88 row_shr:1 row_mask:0xf bank_mask:0xf
	v_pk_mul_f32 v[110:111], v[134:135], v[110:111]
	v_mov_b32_dpp v133, v72 row_shl:1 row_mask:0xf bank_mask:0xf
	v_add_f32_e32 v107, 1.0, v107
	v_rcp_f32_e32 v107, v107
	v_fma_f32 v88, v88, v116, v110
	v_add_f32_e32 v88, v88, v111
	v_add_f32_e32 v88, v124, v88
	v_mul_f32_e32 v92, v92, v107
	v_mul_f32_e32 v84, v84, v92
	v_mul_f32_e32 v92, 0xbfb8aa3b, v88
	v_exp_f32_e32 v92, v92
	v_pk_mul_f32 v[110:111], v[134:135], v[114:115]
	v_fma_f32 v80, v80, v116, v110
	v_add_f32_e32 v92, 1.0, v92
	v_rcp_f32_e32 v92, v92
	v_add_f32_e32 v80, v80, v111
	v_add_f32_e32 v80, v124, v80
	v_pk_mul_f32 v[110:111], v[134:135], v[132:133]
	v_mul_f32_e32 v88, v88, v92
	v_mul_f32_e32 v76, v76, v88
	v_mul_f32_e32 v88, 0xbfb8aa3b, v80
	v_exp_f32_e32 v88, v88
	v_fma_f32 v72, v72, v116, v110
	v_add_f32_e32 v72, v72, v111
	v_add_f32_e32 v72, v124, v72
	v_add_f32_e32 v88, 1.0, v88
	v_rcp_f32_e32 v88, v88
	v_mov_b32_dpp v131, v89 row_ror:15 row_mask:0xf bank_mask:0xf
	v_mov_b32_e32 v130, v169
	v_mul_f32_e32 v80, v80, v88
	v_mul_f32_e32 v68, v68, v80
	v_mul_f32_e32 v80, 0xbfb8aa3b, v72
	v_exp_f32_e32 v80, v80
	v_mov_b32_dpp v130, v93 row_shr:1 row_mask:0xf bank_mask:0xf
	v_mov_b32_dpp v131, v93 row_shl:1 row_mask:0xf bank_mask:0xf
	v_pk_mul_f32 v[130:131], v[120:121], v[130:131]
	v_add_f32_e32 v80, 1.0, v80
	v_rcp_f32_e32 v80, v80
	v_mov_b32_dpp v110, v93 row_ror:1 row_mask:0xf bank_mask:0xf
	v_mul_f32_e32 v72, v72, v80
	v_mul_f32_e32 v64, v64, v72
	v_fma_f32 v72, v93, v117, v130
	v_add_f32_e32 v72, v72, v131
	v_add_f32_e32 v72, v125, v72
	v_mul_f32_e32 v88, 0xbfb8aa3b, v72
	v_exp_f32_e32 v88, v88
	v_mov_b32_dpp v111, v81 row_ror:15 row_mask:0xf bank_mask:0xf
	v_mov_b32_dpp v110, v89 row_shr:1 row_mask:0xf bank_mask:0xf
	v_add_f32_e32 v88, 1.0, v88
	v_rcp_f32_e32 v88, v88
	v_mov_b32_dpp v111, v89 row_shl:1 row_mask:0xf bank_mask:0xf
	v_pk_mul_f32 v[92:93], v[120:121], v[110:111]
	v_mov_b32_dpp v114, v89 row_ror:1 row_mask:0xf bank_mask:0xf
	v_mul_f32_e32 v72, v72, v88
	v_mul_f32_e32 v85, v85, v72
	v_fma_f32 v72, v89, v117, v92
	v_add_f32_e32 v72, v72, v93
	v_add_f32_e32 v72, v125, v72
	v_mul_f32_e32 v88, 0xbfb8aa3b, v72
	v_exp_f32_e32 v88, v88
	v_mov_b32_dpp v115, v73 row_ror:15 row_mask:0xf bank_mask:0xf
	v_mov_b32_dpp v114, v81 row_shr:1 row_mask:0xf bank_mask:0xf
	v_add_f32_e32 v88, 1.0, v88
	v_rcp_f32_e32 v88, v88
	v_mov_b32_dpp v115, v81 row_shl:1 row_mask:0xf bank_mask:0xf
	v_mov_b32_dpp v80, v81 row_ror:1 row_mask:0xf bank_mask:0xf
	v_mov_b32_e32 v110, v142
	v_mul_f32_e32 v72, v72, v88
	v_pk_mul_f32 v[88:89], v[120:121], v[114:115]
	v_mul_f32_e32 v77, v77, v72
	v_fma_f32 v72, v81, v117, v88
	v_add_f32_e32 v72, v72, v89
	v_add_f32_e32 v72, v125, v72
	v_mul_f32_e32 v81, 0xbfb8aa3b, v72
	v_exp_f32_e32 v81, v81
	v_mov_b32_dpp v80, v73 row_shr:1 row_mask:0xf bank_mask:0xf
	v_mov_b32_e32 v111, v122
	v_add_f32_e32 v81, 1.0, v81
	v_rcp_f32_e32 v81, v81
	v_mov_b32_dpp v92, v82 row_ror:1 row_mask:0xf bank_mask:0xf
	v_mov_b32_e32 v93, v169
	v_mov_b32_e32 v122, v143
	v_mul_f32_e32 v72, v72, v81
	v_mov_b32_e32 v81, v169
	v_mul_f32_e32 v69, v69, v72
	v_mov_b32_dpp v92, v74 row_shr:1 row_mask:0xf bank_mask:0xf
	v_mov_b32_dpp v81, v73 row_shl:1 row_mask:0xf bank_mask:0xf
	v_pk_mul_f32 v[80:81], v[120:121], v[80:81]
	v_mov_b32_dpp v93, v74 row_shl:1 row_mask:0xf bank_mask:0xf
	v_fma_f32 v72, v73, v117, v80
	v_add_f32_e32 v72, v72, v81
	v_add_f32_e32 v72, v125, v72
	v_mul_f32_e32 v73, 0xbfb8aa3b, v72
	v_exp_f32_e32 v73, v73
	s_nop 0
	v_add_f32_e32 v73, 1.0, v73
	v_rcp_f32_e32 v73, v73
	v_mov_b32_dpp v80, v90 row_ror:1 row_mask:0xf bank_mask:0xf
	v_mov_b32_dpp v81, v74 row_ror:15 row_mask:0xf bank_mask:0xf
	v_mov_b32_dpp v89, v90 row_ror:15 row_mask:0xf bank_mask:0xf
	v_mul_f32_e32 v72, v72, v73
	v_mul_f32_e32 v65, v65, v72
	v_mov_b32_dpp v80, v82 row_shr:1 row_mask:0xf bank_mask:0xf
	v_mov_b32_dpp v72, v94 row_ror:1 row_mask:0xf bank_mask:0xf
	v_mov_b32_dpp v73, v82 row_ror:15 row_mask:0xf bank_mask:0xf
	v_mov_b32_dpp v81, v82 row_shl:1 row_mask:0xf bank_mask:0xf
	v_mov_b32_dpp v72, v90 row_shr:1 row_mask:0xf bank_mask:0xf
	v_mov_b32_dpp v73, v90 row_shl:1 row_mask:0xf bank_mask:0xf
	v_pk_mul_f32 v[72:73], v[110:111], v[72:73]
	v_mov_b32_e32 v88, v169
	v_fma_f32 v72, v90, v118, v72
	v_add_f32_e32 v72, v72, v73
	v_add_f32_e32 v72, v126, v72
	v_mul_f32_e32 v73, 0xbfb8aa3b, v72
	v_exp_f32_e32 v73, v73
	v_mov_b32_dpp v88, v94 row_shr:1 row_mask:0xf bank_mask:0xf
	v_mov_b32_dpp v89, v94 row_shl:1 row_mask:0xf bank_mask:0xf
	v_pk_mul_f32 v[88:89], v[110:111], v[88:89]
	v_add_f32_e32 v73, 1.0, v73
	v_rcp_f32_e32 v73, v73
	v_fma_f32 v88, v94, v118, v88
	v_add_f32_e32 v88, v88, v89
	v_add_f32_e32 v88, v126, v88
	v_mul_f32_e32 v72, v72, v73
	v_mul_f32_e32 v78, v78, v72
	v_pk_mul_f32 v[72:73], v[110:111], v[80:81]
	v_fma_f32 v72, v82, v118, v72
	v_add_f32_e32 v72, v72, v73
	v_add_f32_e32 v72, v126, v72
	v_mul_f32_e32 v73, 0xbfb8aa3b, v72
	v_exp_f32_e32 v73, v73
	v_mov_b32_dpp v80, v91 row_ror:1 row_mask:0xf bank_mask:0xf
	v_mul_f32_e32 v89, 0xbfb8aa3b, v88
	v_add_f32_e32 v73, 1.0, v73
	v_rcp_f32_e32 v73, v73
	v_mov_b32_dpp v81, v75 row_ror:15 row_mask:0xf bank_mask:0xf
	v_mov_b32_dpp v80, v83 row_shr:1 row_mask:0xf bank_mask:0xf
	v_exp_f32_e32 v89, v89
	v_mul_f32_e32 v72, v72, v73
	v_mul_f32_e32 v82, v70, v72
	v_pk_mul_f32 v[72:73], v[110:111], v[92:93]
	v_mov_b32_dpp v81, v83 row_shl:1 row_mask:0xf bank_mask:0xf
	v_fma_f32 v70, v74, v118, v72
	v_add_f32_e32 v70, v70, v73
	v_add_f32_e32 v70, v126, v70
	v_mul_f32_e32 v72, 0xbfb8aa3b, v70
	v_exp_f32_e32 v72, v72
	v_add_f32_e32 v89, 1.0, v89
	v_rcp_f32_e32 v89, v89
	v_add_f32_e32 v72, 1.0, v72
	v_rcp_f32_e32 v72, v72
	v_mov_b32_dpp v73, v83 row_ror:15 row_mask:0xf bank_mask:0xf
	v_mul_f32_e32 v88, v88, v89
	v_mul_f32_e32 v70, v70, v72
	v_mov_b32_dpp v73, v91 row_shl:1 row_mask:0xf bank_mask:0xf
	v_mul_f32_e32 v86, v86, v88
	v_mov_b32_dpp v72, v95 row_ror:1 row_mask:0xf bank_mask:0xf
	v_mul_f32_e32 v74, v66, v70
	v_mov_b32_dpp v89, v91 row_ror:15 row_mask:0xf bank_mask:0xf
	v_mov_b32_dpp v72, v91 row_shr:1 row_mask:0xf bank_mask:0xf
	v_pk_mul_f32 v[72:73], v[122:123], v[72:73]
	v_fma_f32 v72, v91, v119, v72
	v_add_f32_e32 v72, v72, v73
	v_add_f32_e32 v72, v127, v72
	v_mul_f32_e32 v73, 0xbfb8aa3b, v72
	v_exp_f32_e32 v73, v73
	v_mov_b32_e32 v88, v169
	v_mov_b32_dpp v70, v83 row_ror:1 row_mask:0xf bank_mask:0xf
	v_mov_b32_dpp v89, v95 row_shl:1 row_mask:0xf bank_mask:0xf
	v_add_f32_e32 v73, 1.0, v73
	v_rcp_f32_e32 v73, v73
	v_mov_b32_dpp v88, v95 row_shr:1 row_mask:0xf bank_mask:0xf
	v_pk_mul_f32 v[88:89], v[122:123], v[88:89]
	v_mov_b32_dpp v70, v75 row_shr:1 row_mask:0xf bank_mask:0xf
	v_mul_f32_e32 v72, v72, v73
	v_mul_f32_e32 v79, v79, v72
	v_pk_mul_f32 v[72:73], v[122:123], v[80:81]
	v_fma_f32 v66, v95, v119, v88
	v_fma_f32 v72, v83, v119, v72
	v_add_f32_e32 v72, v72, v73
	v_add_f32_e32 v72, v127, v72
	v_mul_f32_e32 v73, 0xbfb8aa3b, v72
	v_exp_f32_e32 v73, v73
	v_add_f32_e32 v66, v66, v89
	v_add_f32_e32 v66, v127, v66
	v_mul_f32_e32 v88, 0xbfb8aa3b, v66
	v_add_f32_e32 v73, 1.0, v73
	v_rcp_f32_e32 v73, v73
	v_exp_f32_e32 v88, v88
	v_mul_f32_e32 v72, v72, v73
	v_mul_f32_e32 v80, v71, v72
	v_mov_b32_e32 v71, v169
	v_add_f32_e32 v88, 1.0, v88
	v_rcp_f32_e32 v88, v88
	v_mov_b32_dpp v71, v75 row_shl:1 row_mask:0xf bank_mask:0xf
	v_pk_mul_f32 v[70:71], v[122:123], v[70:71]
	v_mul_f32_e32 v66, v66, v88
	v_fma_f32 v70, v75, v119, v70
	v_add_f32_e32 v70, v70, v71
	v_add_f32_e32 v70, v127, v70
	v_mul_f32_e32 v71, 0xbfb8aa3b, v70
	v_exp_f32_e32 v71, v71
	v_mul_f32_e32 v66, v87, v66
	v_add_f32_e32 v71, 1.0, v71
	v_rcp_f32_e32 v71, v71
	s_nop 0
	v_mul_f32_e32 v70, v70, v71
	v_mul_f32_e32 v75, v67, v70
	v_cvt_pk_bf16_f32 v70, v128, v104
	v_cvt_pk_bf16_f32 v71, v97, v105
	v_cvt_pk_bf16_f32 v72, v84, v85
	v_cvt_pk_bf16_f32 v73, v86, v66
	v_mul_lo_u32 v66, v194, s17
	v_add_lshl_u32 v97, v66, v184, 1
	buffer_store_dwordx4 v[70:73], v97, s[24:27], 0 offen sc1
	v_add_u32_e32 v66, 0x16000, v97
	s_nop 0
	v_cvt_pk_bf16_f32 v70, v108, v109
	v_cvt_pk_bf16_f32 v71, v101, v106
	v_cvt_pk_bf16_f32 v72, v76, v77
	v_cvt_pk_bf16_f32 v73, v78, v79
	buffer_store_dwordx4 v[70:73], v66, s[24:27], 0 offen sc1
	v_cvt_pk_bf16_f32 v66, v112, v113
	v_cvt_pk_bf16_f32 v67, v102, v103
	v_cvt_pk_bf16_f32 v68, v68, v69
	v_cvt_pk_bf16_f32 v69, v82, v80
	s_nop 0
	v_add_u32_e32 v70, 0x2c000, v97
	buffer_store_dwordx4 v[66:69], v70, s[24:27], 0 offen sc1
	v_mov_b32_dpp v103, v56 row_ror:15 row_mask:0xf bank_mask:0xf
	v_mov_b32_e32 v102, v169
	v_cvt_pk_bf16_f32 v66, v96, v100
	v_cvt_pk_bf16_f32 v67, v98, v99
	v_cvt_pk_bf16_f32 v68, v64, v65
	v_add_u32_e32 v64, 0x42000, v97
	v_cvt_pk_bf16_f32 v69, v74, v75
	buffer_store_dwordx4 v[66:69], v64, s[24:27], 0 offen sc1
	global_load_dwordx4 v[76:79], v[182:183], off offset:16
	global_load_dwordx4 v[92:95], v[182:183], off
	s_nop 0
	global_load_dwordx4 v[64:67], v[180:181], off offset:16
	global_load_dwordx4 v[80:83], v[180:181], off
	global_load_dwordx4 v[68:71], v[178:179], off offset:16
	global_load_dwordx4 v[84:87], v[178:179], off
	global_load_dwordx4 v[72:75], v[176:177], off offset:16
	global_load_dwordx4 v[88:91], v[176:177], off
	v_mov_b32_dpp v102, v60 row_shr:1 row_mask:0xf bank_mask:0xf
	v_mov_b32_dpp v103, v60 row_shl:1 row_mask:0xf bank_mask:0xf
	v_mov_b32_dpp v98, v60 row_ror:1 row_mask:0xf bank_mask:0xf
	v_mov_b32_dpp v99, v48 row_ror:15 row_mask:0xf bank_mask:0xf
	v_mov_b32_dpp v100, v56 row_ror:1 row_mask:0xf bank_mask:0xf
	v_mov_b32_dpp v98, v56 row_shr:1 row_mask:0xf bank_mask:0xf
	v_mov_b32_dpp v99, v56 row_shl:1 row_mask:0xf bank_mask:0xf
	v_mov_b32_dpp v100, v48 row_shr:1 row_mask:0xf bank_mask:0xf
	v_mov_b32_dpp v104, v48 row_ror:1 row_mask:0xf bank_mask:0xf
	v_mov_b32_dpp v101, v40 row_ror:15 row_mask:0xf bank_mask:0xf
	v_mov_b32_e32 v105, v169
	v_mov_b32_dpp v104, v40 row_shr:1 row_mask:0xf bank_mask:0xf
	v_mov_b32_dpp v101, v48 row_shl:1 row_mask:0xf bank_mask:0xf
	v_mov_b32_dpp v105, v40 row_shl:1 row_mask:0xf bank_mask:0xf
	s_waitcnt vmcnt(6)
	v_mov_b32_e32 v106, v92
	s_waitcnt vmcnt(2)
	v_mov_b32_e32 v107, v84
	v_pk_mul_f32 v[102:103], v[106:107], v[102:103]
	v_pk_mul_f32 v[98:99], v[106:107], v[98:99]
	v_fma_f32 v60, v60, v80, v102
	v_add_f32_e32 v60, v60, v103
	s_waitcnt vmcnt(0)
	v_add_f32_e32 v60, v88, v60
	v_mul_f32_e32 v84, 0xbfb8aa3b, v60
	v_exp_f32_e32 v84, v84
	v_fma_f32 v56, v56, v80, v98
	v_add_f32_e32 v56, v56, v99
	v_add_f32_e32 v56, v88, v56
	v_add_f32_e32 v84, 1.0, v84
	v_rcp_f32_e32 v84, v84
	v_pk_mul_f32 v[98:99], v[106:107], v[100:101]
	v_fma_f32 v48, v48, v80, v98
	v_mul_f32_e32 v60, v60, v84
	v_mul_f32_e32 v52, v52, v60
	v_mul_f32_e32 v60, 0xbfb8aa3b, v56
	v_exp_f32_e32 v60, v60
	v_add_f32_e32 v48, v48, v99
	v_add_f32_e32 v48, v88, v48
	v_pk_mul_f32 v[98:99], v[106:107], v[104:105]
	v_add_f32_e32 v60, 1.0, v60
	v_rcp_f32_e32 v60, v60
	v_fma_f32 v40, v40, v80, v98
	v_add_f32_e32 v40, v40, v99
	v_add_f32_e32 v40, v88, v40
	v_mul_f32_e32 v56, v56, v60
	v_mul_f32_e32 v44, v44, v56
	v_mul_f32_e32 v56, 0xbfb8aa3b, v48
	v_exp_f32_e32 v56, v56
	v_mov_b32_dpp v103, v57 row_ror:15 row_mask:0xf bank_mask:0xf
	v_mov_b32_e32 v102, v169
	v_mov_b32_e32 v84, v93
	v_add_f32_e32 v56, 1.0, v56
	v_rcp_f32_e32 v56, v56
	v_mov_b32_dpp v102, v61 row_shr:1 row_mask:0xf bank_mask:0xf
	v_mov_b32_dpp v103, v61 row_shl:1 row_mask:0xf bank_mask:0xf
	v_pk_mul_f32 v[92:93], v[84:85], v[102:103]
	v_mul_f32_e32 v48, v48, v56
	v_mul_f32_e32 v36, v36, v48
	v_mul_f32_e32 v48, 0xbfb8aa3b, v40
	v_exp_f32_e32 v48, v48
	s_nop 0
	v_add_f32_e32 v48, 1.0, v48
	v_rcp_f32_e32 v48, v48
	v_mov_b32_dpp v98, v61 row_ror:1 row_mask:0xf bank_mask:0xf
	v_mov_b32_dpp v99, v49 row_ror:15 row_mask:0xf bank_mask:0xf
	v_mul_f32_e32 v40, v40, v48
	v_mul_f32_e32 v32, v32, v40
	v_fma_f32 v40, v61, v81, v92
	v_add_f32_e32 v40, v40, v93
	v_add_f32_e32 v40, v89, v40
	v_mul_f32_e32 v56, 0xbfb8aa3b, v40
	v_exp_f32_e32 v56, v56
	v_mov_b32_dpp v98, v57 row_shr:1 row_mask:0xf bank_mask:0xf
	v_mov_b32_dpp v99, v57 row_shl:1 row_mask:0xf bank_mask:0xf
	v_pk_mul_f32 v[60:61], v[84:85], v[98:99]
	v_add_f32_e32 v56, 1.0, v56
	v_rcp_f32_e32 v56, v56
	v_mov_b32_dpp v100, v57 row_ror:1 row_mask:0xf bank_mask:0xf
	v_mov_b32_dpp v101, v41 row_ror:15 row_mask:0xf bank_mask:0xf
	v_mul_f32_e32 v40, v40, v56
	v_mul_f32_e32 v40, v53, v40
	v_fma_f32 v53, v57, v81, v60
	v_add_f32_e32 v53, v53, v61
	v_add_f32_e32 v53, v89, v53
	v_mul_f32_e32 v56, 0xbfb8aa3b, v53
	v_exp_f32_e32 v56, v56
	v_mov_b32_dpp v100, v49 row_shr:1 row_mask:0xf bank_mask:0xf
	v_mov_b32_dpp v101, v49 row_shl:1 row_mask:0xf bank_mask:0xf
	v_mov_b32_dpp v48, v49 row_ror:1 row_mask:0xf bank_mask:0xf
	v_add_f32_e32 v56, 1.0, v56
	v_rcp_f32_e32 v56, v56
	v_mov_b32_dpp v48, v41 row_shr:1 row_mask:0xf bank_mask:0xf
	v_mul_f32_e32 v53, v53, v56
	v_pk_mul_f32 v[56:57], v[84:85], v[100:101]
	v_mul_f32_e32 v45, v45, v53
	v_fma_f32 v49, v49, v81, v56
	v_add_f32_e32 v49, v49, v57
	v_add_f32_e32 v49, v89, v49
	v_mul_f32_e32 v53, 0xbfb8aa3b, v49
	v_exp_f32_e32 v53, v53
	v_mov_b32_dpp v80, v50 row_ror:1 row_mask:0xf bank_mask:0xf
	v_add_f32_e32 v53, 1.0, v53
	v_rcp_f32_e32 v53, v53
	v_mov_b32_dpp v56, v58 row_ror:1 row_mask:0xf bank_mask:0xf
	v_mov_b32_dpp v57, v42 row_ror:15 row_mask:0xf bank_mask:0xf
	v_mov_b32_dpp v80, v42 row_shr:1 row_mask:0xf bank_mask:0xf
	v_mul_f32_e32 v49, v49, v53
	v_mul_f32_e32 v37, v37, v49
	v_mov_b32_e32 v49, v169
	v_mov_b32_dpp v56, v50 row_shr:1 row_mask:0xf bank_mask:0xf
	v_mov_b32_dpp v57, v50 row_shl:1 row_mask:0xf bank_mask:0xf
	v_mov_b32_dpp v49, v41 row_shl:1 row_mask:0xf bank_mask:0xf
	v_pk_mul_f32 v[48:49], v[84:85], v[48:49]
	v_mov_b32_e32 v84, v94
	v_fma_f32 v41, v41, v81, v48
	v_add_f32_e32 v41, v41, v49
	v_add_f32_e32 v41, v89, v41
	v_mul_f32_e32 v48, 0xbfb8aa3b, v41
	v_exp_f32_e32 v48, v48
	v_mov_b32_e32 v85, v86
	v_mov_b32_e32 v81, v169
	v_add_f32_e32 v48, 1.0, v48
	v_rcp_f32_e32 v48, v48
	v_mov_b32_dpp v49, v50 row_ror:15 row_mask:0xf bank_mask:0xf
	v_mov_b32_dpp v81, v42 row_shl:1 row_mask:0xf bank_mask:0xf
	v_mov_b32_e32 v86, v95
	v_mul_f32_e32 v41, v41, v48
	v_mov_b32_dpp v49, v58 row_shl:1 row_mask:0xf bank_mask:0xf
	v_mov_b32_dpp v61, v58 row_ror:15 row_mask:0xf bank_mask:0xf
	v_mov_b32_dpp v48, v62 row_ror:1 row_mask:0xf bank_mask:0xf
	v_mov_b32_e32 v60, v169
	v_mov_b32_dpp v61, v62 row_shl:1 row_mask:0xf bank_mask:0xf
	v_mov_b32_dpp v48, v58 row_shr:1 row_mask:0xf bank_mask:0xf
	v_pk_mul_f32 v[48:49], v[84:85], v[48:49]
	v_mov_b32_dpp v60, v62 row_shr:1 row_mask:0xf bank_mask:0xf
	v_fma_f32 v48, v58, v82, v48
	v_add_f32_e32 v48, v48, v49
	v_add_f32_e32 v48, v90, v48
	v_mul_f32_e32 v49, 0xbfb8aa3b, v48
	v_exp_f32_e32 v49, v49
	v_pk_mul_f32 v[60:61], v[84:85], v[60:61]
	v_mul_f32_e32 v33, v33, v41
	v_fma_f32 v41, v62, v82, v60
	v_add_f32_e32 v49, 1.0, v49
	v_rcp_f32_e32 v49, v49
	v_add_f32_e32 v41, v41, v61
	v_add_f32_e32 v41, v90, v41
	v_mul_f32_e32 v53, 0xbfb8aa3b, v41
	v_mul_f32_e32 v48, v48, v49
	v_mul_f32_e32 v46, v46, v48
	v_pk_mul_f32 v[48:49], v[84:85], v[56:57]
	v_fma_f32 v48, v50, v82, v48
	v_add_f32_e32 v48, v48, v49
	v_add_f32_e32 v48, v90, v48
	v_mul_f32_e32 v49, 0xbfb8aa3b, v48
	v_exp_f32_e32 v49, v49
	v_mov_b32_dpp v56, v59 row_ror:1 row_mask:0xf bank_mask:0xf
	v_exp_f32_e32 v53, v53
	v_add_f32_e32 v49, 1.0, v49
	v_rcp_f32_e32 v49, v49
	v_mov_b32_dpp v57, v43 row_ror:15 row_mask:0xf bank_mask:0xf
	v_mov_b32_dpp v56, v51 row_shr:1 row_mask:0xf bank_mask:0xf
	v_mul_f32_e32 v48, v48, v49
	v_mul_f32_e32 v38, v38, v48
	v_pk_mul_f32 v[48:49], v[84:85], v[80:81]
	v_mov_b32_dpp v57, v51 row_shl:1 row_mask:0xf bank_mask:0xf
	v_fma_f32 v42, v42, v82, v48
	v_add_f32_e32 v42, v42, v49
	v_add_f32_e32 v42, v90, v42
	v_mul_f32_e32 v48, 0xbfb8aa3b, v42
	v_exp_f32_e32 v48, v48
	v_mov_b32_dpp v61, v59 row_ror:15 row_mask:0xf bank_mask:0xf
	v_mov_b32_e32 v60, v169
	v_add_f32_e32 v48, 1.0, v48
	v_rcp_f32_e32 v48, v48
	v_mov_b32_dpp v49, v51 row_ror:15 row_mask:0xf bank_mask:0xf
	v_add_f32_e32 v53, 1.0, v53
	v_mov_b32_dpp v60, v63 row_shr:1 row_mask:0xf bank_mask:0xf
	v_mul_f32_e32 v42, v42, v48
	v_mov_b32_dpp v49, v59 row_shl:1 row_mask:0xf bank_mask:0xf
	v_mov_b32_dpp v61, v63 row_shl:1 row_mask:0xf bank_mask:0xf
	v_mov_b32_dpp v48, v63 row_ror:1 row_mask:0xf bank_mask:0xf
	v_rcp_f32_e32 v53, v53
	v_pk_mul_f32 v[60:61], v[86:87], v[60:61]
	v_mov_b32_dpp v48, v59 row_shr:1 row_mask:0xf bank_mask:0xf
	v_pk_mul_f32 v[48:49], v[86:87], v[48:49]
	v_mul_f32_e32 v34, v34, v42
	v_fma_f32 v48, v59, v83, v48
	v_add_f32_e32 v48, v48, v49
	v_add_f32_e32 v48, v91, v48
	v_mul_f32_e32 v49, 0xbfb8aa3b, v48
	v_exp_f32_e32 v49, v49
	v_fma_f32 v42, v63, v83, v60
	v_add_f32_e32 v42, v42, v61
	v_add_f32_e32 v49, 1.0, v49
	v_rcp_f32_e32 v49, v49
	v_mov_b32_dpp v50, v51 row_ror:1 row_mask:0xf bank_mask:0xf
	v_add_f32_e32 v42, v91, v42
	v_mul_f32_e32 v41, v41, v53
	v_mul_f32_e32 v48, v48, v49
	v_mul_f32_e32 v47, v47, v48
	v_pk_mul_f32 v[48:49], v[86:87], v[56:57]
	v_mov_b32_dpp v50, v43 row_shr:1 row_mask:0xf bank_mask:0xf
	v_fma_f32 v48, v51, v83, v48
	v_add_f32_e32 v48, v48, v49
	v_add_f32_e32 v48, v91, v48
	v_mul_f32_e32 v49, 0xbfb8aa3b, v48
	v_exp_f32_e32 v49, v49
	v_mov_b32_e32 v51, v169
	v_mul_f32_e32 v53, 0xbfb8aa3b, v42
	v_exp_f32_e32 v53, v53
	v_add_f32_e32 v49, 1.0, v49
	v_rcp_f32_e32 v49, v49
	v_mov_b32_dpp v51, v43 row_shl:1 row_mask:0xf bank_mask:0xf
	v_add_f32_e32 v53, 1.0, v53
	v_rcp_f32_e32 v53, v53
	v_mul_f32_e32 v48, v48, v49
	v_mul_f32_e32 v39, v39, v48
	v_pk_mul_f32 v[48:49], v[86:87], v[50:51]
	v_mul_f32_e32 v42, v42, v53
	v_fma_f32 v43, v43, v83, v48
	v_add_f32_e32 v43, v43, v49
	v_add_f32_e32 v43, v91, v43
	v_mul_f32_e32 v48, 0xbfb8aa3b, v43
	v_exp_f32_e32 v48, v48
	v_mul_f32_e32 v42, v55, v42
	v_mul_f32_e32 v41, v54, v41
	v_add_f32_e32 v48, 1.0, v48
	v_rcp_f32_e32 v48, v48
	v_mov_b32_dpp v55, v24 row_ror:15 row_mask:0xf bank_mask:0xf
	v_mov_b32_e32 v54, v169
	v_mov_b32_e32 v58, v76
	v_mov_b32_dpp v55, v28 row_shl:1 row_mask:0xf bank_mask:0xf
	v_mov_b32_dpp v54, v28 row_shr:1 row_mask:0xf bank_mask:0xf
	v_mov_b32_e32 v59, v68
	v_mul_f32_e32 v43, v43, v48
	v_pk_mul_f32 v[54:55], v[58:59], v[54:55]
	v_mul_f32_e32 v35, v35, v43
	v_mov_b32_dpp v48, v28 row_ror:1 row_mask:0xf bank_mask:0xf
	v_fma_f32 v28, v28, v64, v54
	v_add_f32_e32 v28, v28, v55
	v_add_f32_e32 v28, v72, v28
	v_mul_f32_e32 v43, 0xbfb8aa3b, v28
	v_exp_f32_e32 v43, v43
	v_mov_b32_dpp v48, v24 row_shr:1 row_mask:0xf bank_mask:0xf
	v_mov_b32_dpp v49, v16 row_ror:15 row_mask:0xf bank_mask:0xf
	v_add_f32_e32 v43, 1.0, v43
	v_rcp_f32_e32 v43, v43
	v_mov_b32_dpp v49, v24 row_shl:1 row_mask:0xf bank_mask:0xf
	v_pk_mul_f32 v[48:49], v[58:59], v[48:49]
	v_mov_b32_dpp v50, v24 row_ror:1 row_mask:0xf bank_mask:0xf
	v_fma_f32 v24, v24, v64, v48
	v_add_f32_e32 v24, v24, v49
	v_mul_f32_e32 v28, v28, v43
	v_add_f32_e32 v24, v72, v24
	v_mul_f32_e32 v20, v20, v28
	v_mul_f32_e32 v28, 0xbfb8aa3b, v24
	v_exp_f32_e32 v28, v28
	v_mov_b32_dpp v50, v16 row_shr:1 row_mask:0xf bank_mask:0xf
	v_mov_b32_dpp v51, v8 row_ror:15 row_mask:0xf bank_mask:0xf
	v_add_f32_e32 v28, 1.0, v28
	v_rcp_f32_e32 v28, v28
	v_mov_b32_dpp v51, v16 row_shl:1 row_mask:0xf bank_mask:0xf
	v_pk_mul_f32 v[48:49], v[58:59], v[50:51]
	v_mov_b32_dpp v56, v16 row_ror:1 row_mask:0xf bank_mask:0xf
	v_fma_f32 v16, v16, v64, v48
	v_add_f32_e32 v16, v16, v49
	v_mul_f32_e32 v24, v24, v28
	v_add_f32_e32 v16, v72, v16
	v_mul_f32_e32 v12, v12, v24
	v_mul_f32_e32 v24, 0xbfb8aa3b, v16
	v_exp_f32_e32 v24, v24
	v_mov_b32_e32 v57, v169
	v_mov_b32_dpp v56, v8 row_shr:1 row_mask:0xf bank_mask:0xf
	v_add_f32_e32 v24, 1.0, v24
	v_rcp_f32_e32 v24, v24
	v_mov_b32_dpp v57, v8 row_shl:1 row_mask:0xf bank_mask:0xf
	v_pk_mul_f32 v[48:49], v[58:59], v[56:57]
	v_mov_b32_dpp v55, v25 row_ror:15 row_mask:0xf bank_mask:0xf
	v_fma_f32 v8, v8, v64, v48
	v_add_f32_e32 v8, v8, v49
	v_mul_f32_e32 v16, v16, v24
	v_add_f32_e32 v8, v72, v8
	v_mul_f32_e32 v4, v4, v16
	v_mul_f32_e32 v16, 0xbfb8aa3b, v8
	v_exp_f32_e32 v16, v16
	v_mov_b32_e32 v54, v169
	v_mov_b32_dpp v55, v29 row_shl:1 row_mask:0xf bank_mask:0xf
	v_mov_b32_e32 v68, v77
	v_add_f32_e32 v16, 1.0, v16
	v_rcp_f32_e32 v16, v16
	v_mov_b32_dpp v54, v29 row_shr:1 row_mask:0xf bank_mask:0xf
	v_pk_mul_f32 v[54:55], v[68:69], v[54:55]
	v_mul_f32_e32 v8, v8, v16
	v_mul_f32_e32 v0, v0, v8
	v_fma_f32 v8, v29, v65, v54
	v_add_f32_e32 v8, v8, v55
	v_add_f32_e32 v8, v73, v8
	v_mul_f32_e32 v24, 0xbfb8aa3b, v8
	v_exp_f32_e32 v24, v24
	v_mov_b32_dpp v48, v29 row_ror:1 row_mask:0xf bank_mask:0xf
	v_add_f32_e32 v24, 1.0, v24
	v_rcp_f32_e32 v24, v24
	v_mov_b32_dpp v49, v17 row_ror:15 row_mask:0xf bank_mask:0xf
	v_mov_b32_dpp v48, v25 row_shr:1 row_mask:0xf bank_mask:0xf
	s_nop 0
	v_mov_b32_dpp v49, v25 row_shl:1 row_mask:0xf bank_mask:0xf
	v_mul_f32_e32 v8, v8, v24
	v_pk_mul_f32 v[28:29], v[68:69], v[48:49]
	v_mul_f32_e32 v21, v21, v8
	v_fma_f32 v8, v25, v65, v28
	v_add_f32_e32 v8, v8, v29
	v_add_f32_e32 v8, v73, v8
	v_mul_f32_e32 v24, 0xbfb8aa3b, v8
	v_exp_f32_e32 v24, v24
	v_mov_b32_dpp v50, v25 row_ror:1 row_mask:0xf bank_mask:0xf
	v_mov_b32_dpp v51, v9 row_ror:15 row_mask:0xf bank_mask:0xf
	v_add_f32_e32 v24, 1.0, v24
	v_rcp_f32_e32 v24, v24
	v_mov_b32_dpp v50, v17 row_shr:1 row_mask:0xf bank_mask:0xf
	v_mov_b32_dpp v51, v17 row_shl:1 row_mask:0xf bank_mask:0xf
	v_mov_b32_dpp v16, v17 row_ror:1 row_mask:0xf bank_mask:0xf
	v_mul_f32_e32 v8, v8, v24
	v_pk_mul_f32 v[24:25], v[68:69], v[50:51]
	v_mul_f32_e32 v13, v13, v8
	v_fma_f32 v8, v17, v65, v24
	v_add_f32_e32 v8, v8, v25
	v_add_f32_e32 v8, v73, v8
	v_mul_f32_e32 v17, 0xbfb8aa3b, v8
	v_exp_f32_e32 v17, v17
	v_mov_b32_dpp v16, v9 row_shr:1 row_mask:0xf bank_mask:0xf
	v_mov_b32_e32 v48, v78
	v_mov_b32_e32 v49, v70
	v_add_f32_e32 v17, 1.0, v17
	v_rcp_f32_e32 v17, v17
	v_mov_b32_e32 v29, v169
	v_mov_b32_e32 v70, v79
	v_mul_f32_e32 v8, v8, v17
	v_mov_b32_e32 v17, v169
	v_mul_f32_e32 v5, v5, v8
	v_mov_b32_dpp v28, v18 row_ror:1 row_mask:0xf bank_mask:0xf
	v_mov_b32_dpp v17, v9 row_shl:1 row_mask:0xf bank_mask:0xf
	v_pk_mul_f32 v[16:17], v[68:69], v[16:17]
	v_mov_b32_dpp v28, v10 row_shr:1 row_mask:0xf bank_mask:0xf
	v_fma_f32 v8, v9, v65, v16
	v_add_f32_e32 v8, v8, v17
	v_add_f32_e32 v8, v73, v8
	v_mul_f32_e32 v9, 0xbfb8aa3b, v8
	v_exp_f32_e32 v9, v9
	v_mov_b32_dpp v29, v10 row_shl:1 row_mask:0xf bank_mask:0xf
	v_add_f32_e32 v9, 1.0, v9
	v_rcp_f32_e32 v9, v9
	v_mov_b32_dpp v16, v26 row_ror:1 row_mask:0xf bank_mask:0xf
	v_mov_b32_dpp v17, v10 row_ror:15 row_mask:0xf bank_mask:0xf
	v_mul_f32_e32 v8, v8, v9
	v_mul_f32_e32 v1, v1, v8
	v_mov_b32_dpp v16, v18 row_shr:1 row_mask:0xf bank_mask:0xf
	v_mov_b32_dpp v8, v30 row_ror:1 row_mask:0xf bank_mask:0xf
	v_mov_b32_dpp v9, v18 row_ror:15 row_mask:0xf bank_mask:0xf
	v_mov_b32_dpp v17, v18 row_shl:1 row_mask:0xf bank_mask:0xf
	v_mov_b32_dpp v8, v26 row_shr:1 row_mask:0xf bank_mask:0xf
	v_mov_b32_dpp v9, v26 row_shl:1 row_mask:0xf bank_mask:0xf
	v_pk_mul_f32 v[8:9], v[48:49], v[8:9]
	v_mov_b32_dpp v25, v26 row_ror:15 row_mask:0xf bank_mask:0xf
	v_fma_f32 v8, v26, v66, v8
	v_add_f32_e32 v8, v8, v9
	v_add_f32_e32 v8, v74, v8
	v_mul_f32_e32 v9, 0xbfb8aa3b, v8
	v_exp_f32_e32 v9, v9
	v_mov_b32_e32 v24, v169
	v_mov_b32_dpp v25, v30 row_shl:1 row_mask:0xf bank_mask:0xf
	v_add_f32_e32 v9, 1.0, v9
	v_rcp_f32_e32 v9, v9
	v_mov_b32_dpp v24, v30 row_shr:1 row_mask:0xf bank_mask:0xf
	v_pk_mul_f32 v[24:25], v[48:49], v[24:25]
	v_mul_f32_e32 v8, v8, v9
	v_mul_f32_e32 v14, v14, v8
	v_pk_mul_f32 v[8:9], v[48:49], v[16:17]
	v_fma_f32 v8, v18, v66, v8
	v_add_f32_e32 v8, v8, v9
	v_add_f32_e32 v8, v74, v8
	v_mul_f32_e32 v9, 0xbfb8aa3b, v8
	v_exp_f32_e32 v9, v9
	v_mov_b32_dpp v16, v27 row_ror:1 row_mask:0xf bank_mask:0xf
	v_fma_f32 v24, v30, v66, v24
	v_add_f32_e32 v9, 1.0, v9
	v_rcp_f32_e32 v9, v9
	v_mov_b32_dpp v17, v11 row_ror:15 row_mask:0xf bank_mask:0xf
	v_mov_b32_dpp v16, v19 row_shr:1 row_mask:0xf bank_mask:0xf
	v_add_f32_e32 v24, v24, v25
	v_mul_f32_e32 v8, v8, v9
	v_mul_f32_e32 v18, v6, v8
	v_pk_mul_f32 v[8:9], v[48:49], v[28:29]
	v_mov_b32_dpp v17, v19 row_shl:1 row_mask:0xf bank_mask:0xf
	v_fma_f32 v6, v10, v66, v8
	v_add_f32_e32 v6, v6, v9
	v_add_f32_e32 v6, v74, v6
	v_mul_f32_e32 v8, 0xbfb8aa3b, v6
	v_exp_f32_e32 v8, v8
	v_add_f32_e32 v24, v74, v24
	v_mul_f32_e32 v25, 0xbfb8aa3b, v24
	v_add_f32_e32 v8, 1.0, v8
	v_rcp_f32_e32 v8, v8
	v_mov_b32_dpp v9, v19 row_ror:15 row_mask:0xf bank_mask:0xf
	v_exp_f32_e32 v25, v25
	v_mul_f32_e32 v6, v6, v8
	v_mov_b32_dpp v9, v27 row_shl:1 row_mask:0xf bank_mask:0xf
	v_add_f32_e32 v25, 1.0, v25
	v_mov_b32_dpp v8, v31 row_ror:1 row_mask:0xf bank_mask:0xf
	v_rcp_f32_e32 v25, v25
	v_mul_f32_e32 v10, v2, v6
	v_mov_b32_dpp v8, v27 row_shr:1 row_mask:0xf bank_mask:0xf
	v_pk_mul_f32 v[8:9], v[70:71], v[8:9]
	v_mul_f32_e32 v24, v24, v25
	v_fma_f32 v8, v27, v67, v8
	v_add_f32_e32 v8, v8, v9
	v_add_f32_e32 v8, v75, v8
	v_mul_f32_e32 v9, 0xbfb8aa3b, v8
	v_exp_f32_e32 v9, v9
	v_mul_f32_e32 v22, v22, v24
	v_add_f32_e32 v9, 1.0, v9
	v_rcp_f32_e32 v9, v9
	v_mov_b32_dpp v25, v27 row_ror:15 row_mask:0xf bank_mask:0xf
	v_mov_b32_e32 v24, v169
	v_mov_b32_dpp v6, v19 row_ror:1 row_mask:0xf bank_mask:0xf
	v_mul_f32_e32 v8, v8, v9
	v_mul_f32_e32 v15, v15, v8
	v_pk_mul_f32 v[8:9], v[70:71], v[16:17]
	v_mov_b32_dpp v24, v31 row_shr:1 row_mask:0xf bank_mask:0xf
	v_fma_f32 v8, v19, v67, v8
	v_add_f32_e32 v8, v8, v9
	v_add_f32_e32 v8, v75, v8
	v_mul_f32_e32 v9, 0xbfb8aa3b, v8
	v_exp_f32_e32 v9, v9
	v_mov_b32_dpp v25, v31 row_shl:1 row_mask:0xf bank_mask:0xf
	v_pk_mul_f32 v[24:25], v[70:71], v[24:25]
	v_mov_b32_dpp v6, v11 row_shr:1 row_mask:0xf bank_mask:0xf
	v_add_f32_e32 v9, 1.0, v9
	v_rcp_f32_e32 v9, v9
	v_fma_f32 v2, v31, v67, v24
	v_add_f32_e32 v2, v2, v25
	v_add_f32_e32 v2, v75, v2
	v_mul_f32_e32 v8, v8, v9
	v_mul_f32_e32 v16, v7, v8
	v_mov_b32_e32 v7, v169
	v_mul_f32_e32 v24, 0xbfb8aa3b, v2
	v_exp_f32_e32 v24, v24
	v_mov_b32_dpp v7, v11 row_shl:1 row_mask:0xf bank_mask:0xf
	v_pk_mul_f32 v[6:7], v[70:71], v[6:7]
	v_add_f32_e32 v24, 1.0, v24
	v_fma_f32 v6, v11, v67, v6
	v_add_f32_e32 v6, v6, v7
	v_add_f32_e32 v6, v75, v6
	v_mul_f32_e32 v7, 0xbfb8aa3b, v6
	v_exp_f32_e32 v7, v7
	v_rcp_f32_e32 v24, v24
	v_add_f32_e32 v7, 1.0, v7
	v_rcp_f32_e32 v7, v7
	v_mul_f32_e32 v2, v2, v24
	v_mul_f32_e32 v2, v23, v2
	v_mul_f32_e32 v6, v6, v7
	v_mul_f32_e32 v11, v3, v6
	v_cvt_pk_bf16_f32 v6, v52, v40
	v_cvt_pk_bf16_f32 v7, v41, v42
	v_cvt_pk_bf16_f32 v8, v20, v21
	v_cvt_pk_bf16_f32 v9, v22, v2
	v_add_u32_e32 v2, 0xb0000, v97
	buffer_store_dwordx4 v[6:9], v2, s[24:27], 0 offen sc1
	v_add_u32_e32 v2, 0xc6000, v97
	s_nop 0
	v_cvt_pk_bf16_f32 v6, v44, v45
	v_cvt_pk_bf16_f32 v7, v46, v47
	v_cvt_pk_bf16_f32 v8, v12, v13
	v_cvt_pk_bf16_f32 v9, v14, v15
	buffer_store_dwordx4 v[6:9], v2, s[24:27], 0 offen sc1
	v_cvt_pk_bf16_f32 v2, v36, v37
	v_cvt_pk_bf16_f32 v3, v38, v39
	v_cvt_pk_bf16_f32 v4, v4, v5
	v_cvt_pk_bf16_f32 v5, v18, v16
	s_nop 1
	v_add_u32_e32 v6, 0xdc000, v97
	buffer_store_dwordx4 v[2:5], v6, s[24:27], 0 offen sc1
	s_nop 1
	v_cvt_pk_bf16_f32 v2, v32, v33
	v_cvt_pk_bf16_f32 v3, v34, v35
	v_cvt_pk_bf16_f32 v4, v0, v1
	v_add_u32_e32 v0, 0xf2000, v97
	v_cvt_pk_bf16_f32 v5, v10, v11
	buffer_store_dwordx4 v[2:5], v0, s[24:27], 0 offen sc1
	s_mov_b64 s[24:25], -1
	s_cbranch_vccnz .LBB0_775
	s_andn2_b64 vcc, exec, s[8:9]
	s_cbranch_vccnz .LBB0_774
	s_barrier
	s_branch .LBB0_774

.LBB0_791:
	s_add_u32 s14, s30, s12
	s_addc_u32 s15, s31, s13
	s_add_u32 s14, s14, 0x5200100
	s_addc_u32 s15, s15, 0
	s_add_u32 s35, s28, s12
	s_addc_u32 s36, s29, s13
	s_add_i32 s37, 0, 0x10000
	v_add_u32_e32 v141, s37, v139
	ds_read_b128 v[142:145], v141
	ds_read_b128 v[146:149], v141 offset:1024
	ds_read_b128 v[150:153], v141 offset:2048
	ds_read_b128 v[154:157], v141 offset:3072
	s_cmpk_eq_i32 s12, 0x700
	s_cselect_b32 s17, s11, s15
	s_cselect_b32 s16, s10, s14
	s_cselect_b32 s15, s9, s36
	s_cselect_b32 s14, s8, s35
	v_lshl_add_u64 v[166:167], v[136:137], 0, s[12:13]
	s_add_i32 m0, s22, 0xc000
	ds_read_b128 v[158:161], v140
	ds_read_b128 v[162:165], v140 offset:1024
	ds_read_b128 v[170:173], v140 offset:2048
	ds_read_b128 v[176:179], v140 offset:3072
	ds_read_b128 v[180:183], v140 offset:4096
	ds_read_b128 v[184:187], v140 offset:5120
	ds_read_b128 v[188:191], v140 offset:6144
	ds_read_b128 v[192:195], v140 offset:7168
	global_load_lds_dwordx4 v[166:167], off
	v_lshl_add_u64 v[166:167], v[134:135], 0, s[12:13]
	s_add_i32 m0, s22, 0xe000
	s_nop 0
	global_load_lds_dwordx4 v[166:167], off
	s_waitcnt lgkmcnt(8)
	s_barrier
	s_waitcnt lgkmcnt(0)
	s_waitcnt lgkmcnt(0)
	v_mfma_f32_16x16x32_bf16 v[124:127], v[142:145], v[158:161], v[124:127]
	v_mfma_f32_16x16x32_bf16 v[100:103], v[150:153], v[158:161], v[100:103]
	v_mfma_f32_16x16x32_bf16 v[120:123], v[142:145], v[170:173], v[120:123]
	v_mfma_f32_16x16x32_bf16 v[88:91], v[150:153], v[170:173], v[88:91]
	v_mfma_f32_16x16x32_bf16 v[116:119], v[142:145], v[180:183], v[116:119]
	v_mfma_f32_16x16x32_bf16 v[84:87], v[150:153], v[180:183], v[84:87]
	v_mfma_f32_16x16x32_bf16 v[108:111], v[142:145], v[188:191], v[108:111]
	v_mfma_f32_16x16x32_bf16 v[76:79], v[150:153], v[188:191], v[76:79]
	v_mfma_f32_16x16x32_bf16 v[124:127], v[146:149], v[162:165], v[124:127]
	v_mfma_f32_16x16x32_bf16 v[100:103], v[154:157], v[162:165], v[100:103]
	v_mfma_f32_16x16x32_bf16 v[120:123], v[146:149], v[176:179], v[120:123]
	v_mfma_f32_16x16x32_bf16 v[88:91], v[154:157], v[176:179], v[88:91]
	v_mfma_f32_16x16x32_bf16 v[116:119], v[146:149], v[184:187], v[116:119]
	v_mfma_f32_16x16x32_bf16 v[84:87], v[154:157], v[184:187], v[84:87]
	v_mfma_f32_16x16x32_bf16 v[108:111], v[146:149], v[192:195], v[108:111]
	v_mfma_f32_16x16x32_bf16 v[76:79], v[154:157], v[192:195], v[76:79]
	s_barrier
	s_add_i32 s35, 0, 0x14000
	s_add_i32 s36, s37, s20
	v_add_u32_e32 v141, s35, v139
	v_lshl_add_u64 v[166:167], s[14:15], 0, v[168:169]
	s_mov_b32 m0, s36
	ds_read_b128 v[196:199], v141
	ds_read_b128 v[200:203], v141 offset:1024
	ds_read_b128 v[212:215], v141 offset:2048
	ds_read_b128 v[216:219], v141 offset:3072
	global_load_lds_dwordx4 v[166:167], off
	v_lshl_add_u64 v[204:205], s[14:15], 0, v[128:129]
	s_add_i32 m0, s36, 0x2000
	s_nop 0
	global_load_lds_dwordx4 v[204:205], off
	s_barrier
	s_waitcnt lgkmcnt(0)
	s_waitcnt lgkmcnt(0)
	v_mfma_f32_16x16x32_bf16 v[112:115], v[196:199], v[158:161], v[112:115]
	v_mfma_f32_16x16x32_bf16 v[80:83], v[212:215], v[158:161], v[80:83]
	v_mfma_f32_16x16x32_bf16 v[104:107], v[196:199], v[170:173], v[104:107]
	v_mfma_f32_16x16x32_bf16 v[72:75], v[212:215], v[170:173], v[72:75]
	v_mfma_f32_16x16x32_bf16 v[96:99], v[196:199], v[180:183], v[96:99]
	v_mfma_f32_16x16x32_bf16 v[68:71], v[212:215], v[180:183], v[68:71]
	v_mfma_f32_16x16x32_bf16 v[92:95], v[196:199], v[188:191], v[92:95]
	v_mfma_f32_16x16x32_bf16 v[64:67], v[212:215], v[188:191], v[64:67]
	v_mfma_f32_16x16x32_bf16 v[112:115], v[200:203], v[162:165], v[112:115]
	v_mfma_f32_16x16x32_bf16 v[80:83], v[216:219], v[162:165], v[80:83]
	v_mfma_f32_16x16x32_bf16 v[104:107], v[200:203], v[176:179], v[104:107]
	v_mfma_f32_16x16x32_bf16 v[72:75], v[216:219], v[176:179], v[72:75]
	v_mfma_f32_16x16x32_bf16 v[96:99], v[200:203], v[184:187], v[96:99]
	v_mfma_f32_16x16x32_bf16 v[68:71], v[216:219], v[184:187], v[68:71]
	v_mfma_f32_16x16x32_bf16 v[92:95], v[200:203], v[192:195], v[92:95]
	v_mfma_f32_16x16x32_bf16 v[64:67], v[216:219], v[192:195], v[64:67]
	s_mov_b32 m0, s22
	v_lshl_add_u64 v[220:221], s[16:17], 0, v[132:133]
	s_barrier
	ds_read_b128 v[158:161], v140 offset:16384
	ds_read_b128 v[162:165], v140 offset:17408
	ds_read_b128 v[170:173], v140 offset:18432
	ds_read_b128 v[176:179], v140 offset:19456
	ds_read_b128 v[180:183], v140 offset:20480
	ds_read_b128 v[184:187], v140 offset:21504
	ds_read_b128 v[188:191], v140 offset:22528
	ds_read_b128 v[192:195], v140 offset:23552
	global_load_lds_dwordx4 v[220:221], off
	v_lshl_add_u64 v[222:223], s[16:17], 0, v[130:131]
	s_mov_b32 m0, s23
	s_nop 0
	global_load_lds_dwordx4 v[222:223], off
	s_barrier
	s_waitcnt lgkmcnt(0)
	s_waitcnt lgkmcnt(0)
	v_mfma_f32_16x16x32_bf16 v[32:35], v[142:145], v[158:161], v[32:35]
	v_mfma_f32_16x16x32_bf16 v[56:59], v[150:153], v[158:161], v[56:59]
	v_mfma_f32_16x16x32_bf16 v[36:39], v[142:145], v[170:173], v[36:39]
	v_mfma_f32_16x16x32_bf16 v[60:63], v[150:153], v[170:173], v[60:63]
	v_mfma_f32_16x16x32_bf16 v[40:43], v[142:145], v[180:183], v[40:43]
	v_mfma_f32_16x16x32_bf16 v[28:31], v[150:153], v[180:183], v[28:31]
	v_mfma_f32_16x16x32_bf16 v[44:47], v[142:145], v[188:191], v[44:47]
	v_mfma_f32_16x16x32_bf16 v[12:15], v[150:153], v[188:191], v[12:15]
	v_mfma_f32_16x16x32_bf16 v[32:35], v[146:149], v[162:165], v[32:35]
	v_mfma_f32_16x16x32_bf16 v[56:59], v[154:157], v[162:165], v[56:59]
	v_mfma_f32_16x16x32_bf16 v[36:39], v[146:149], v[176:179], v[36:39]
	v_mfma_f32_16x16x32_bf16 v[60:63], v[154:157], v[176:179], v[60:63]
	v_mfma_f32_16x16x32_bf16 v[40:43], v[146:149], v[184:187], v[40:43]
	v_mfma_f32_16x16x32_bf16 v[28:31], v[154:157], v[184:187], v[28:31]
	v_mfma_f32_16x16x32_bf16 v[44:47], v[146:149], v[192:195], v[44:47]
	v_mfma_f32_16x16x32_bf16 v[12:15], v[154:157], v[192:195], v[12:15]
	s_barrier
	s_add_u32 s36, s14, 0x40000
	s_addc_u32 s37, s15, 0
	s_add_i32 s35, s35, s20
	v_lshl_add_u64 v[142:143], s[36:37], 0, v[168:169]
	s_mov_b32 m0, s35
	s_nop 0
	global_load_lds_dwordx4 v[142:143], off
	v_lshl_add_u64 v[142:143], s[36:37], 0, v[128:129]
	s_add_i32 m0, s35, 0x2000
	s_nop 0
	global_load_lds_dwordx4 v[142:143], off
	s_waitcnt vmcnt(6)
	s_barrier
	v_mfma_f32_16x16x32_bf16 v[8:11], v[196:199], v[158:161], v[8:11]
	v_mfma_f32_16x16x32_bf16 v[48:51], v[212:215], v[158:161], v[48:51]
	v_mfma_f32_16x16x32_bf16 v[20:23], v[196:199], v[170:173], v[20:23]
	v_mfma_f32_16x16x32_bf16 v[52:55], v[212:215], v[170:173], v[52:55]
	v_mfma_f32_16x16x32_bf16 v[16:19], v[196:199], v[180:183], v[16:19]
	v_mfma_f32_16x16x32_bf16 v[4:7], v[212:215], v[180:183], v[4:7]
	v_mfma_f32_16x16x32_bf16 v[24:27], v[196:199], v[188:191], v[24:27]
	v_mfma_f32_16x16x32_bf16 v[0:3], v[212:215], v[188:191], v[0:3]
	v_mfma_f32_16x16x32_bf16 v[8:11], v[200:203], v[162:165], v[8:11]
	v_mfma_f32_16x16x32_bf16 v[48:51], v[216:219], v[162:165], v[48:51]
	v_mfma_f32_16x16x32_bf16 v[20:23], v[200:203], v[176:179], v[20:23]
	v_mfma_f32_16x16x32_bf16 v[52:55], v[216:219], v[176:179], v[52:55]
	v_mfma_f32_16x16x32_bf16 v[16:19], v[200:203], v[184:187], v[16:19]
	v_mfma_f32_16x16x32_bf16 v[4:7], v[216:219], v[184:187], v[4:7]
	v_mfma_f32_16x16x32_bf16 v[24:27], v[200:203], v[192:195], v[24:27]
	v_mfma_f32_16x16x32_bf16 v[0:3], v[216:219], v[192:195], v[0:3]
	s_add_i32 s35, 0, 0x18000
	v_add_u32_e32 v141, s35, v139
	s_barrier
	ds_read_b128 v[142:145], v141
	ds_read_b128 v[146:149], v141 offset:1024
	ds_read_b128 v[150:153], v141 offset:2048
	ds_read_b128 v[154:157], v141 offset:3072
	s_add_u32 s16, s16, 0x40000
	s_addc_u32 s17, s17, 0
	s_mov_b32 m0, s24
	v_lshl_add_u64 v[196:197], s[16:17], 0, v[132:133]
	ds_read_b128 v[158:161], v140 offset:32768
	ds_read_b128 v[162:165], v140 offset:33792
	ds_read_b128 v[170:173], v140 offset:34816
	ds_read_b128 v[176:179], v140 offset:35840
	ds_read_b128 v[180:183], v140 offset:36864
	ds_read_b128 v[184:187], v140 offset:37888
	ds_read_b128 v[188:191], v140 offset:38912
	ds_read_b128 v[192:195], v140 offset:39936
	global_load_lds_dwordx4 v[196:197], off
	v_lshl_add_u64 v[196:197], s[16:17], 0, v[130:131]
	s_mov_b32 m0, s25
	s_nop 0
	global_load_lds_dwordx4 v[196:197], off
	s_waitcnt lgkmcnt(8)
	s_barrier
	s_waitcnt lgkmcnt(0)
	s_waitcnt lgkmcnt(0)
	v_mfma_f32_16x16x32_bf16 v[124:127], v[142:145], v[158:161], v[124:127]
	v_mfma_f32_16x16x32_bf16 v[100:103], v[150:153], v[158:161], v[100:103]
	v_mfma_f32_16x16x32_bf16 v[120:123], v[142:145], v[170:173], v[120:123]
	v_mfma_f32_16x16x32_bf16 v[88:91], v[150:153], v[170:173], v[88:91]
	v_mfma_f32_16x16x32_bf16 v[116:119], v[142:145], v[180:183], v[116:119]
	v_mfma_f32_16x16x32_bf16 v[84:87], v[150:153], v[180:183], v[84:87]
	v_mfma_f32_16x16x32_bf16 v[108:111], v[142:145], v[188:191], v[108:111]
	v_mfma_f32_16x16x32_bf16 v[76:79], v[150:153], v[188:191], v[76:79]
	v_mfma_f32_16x16x32_bf16 v[124:127], v[146:149], v[162:165], v[124:127]
	v_mfma_f32_16x16x32_bf16 v[100:103], v[154:157], v[162:165], v[100:103]
	v_mfma_f32_16x16x32_bf16 v[120:123], v[146:149], v[176:179], v[120:123]
	v_mfma_f32_16x16x32_bf16 v[88:91], v[154:157], v[176:179], v[88:91]
	v_mfma_f32_16x16x32_bf16 v[116:119], v[146:149], v[184:187], v[116:119]
	v_mfma_f32_16x16x32_bf16 v[84:87], v[154:157], v[184:187], v[84:87]
	v_mfma_f32_16x16x32_bf16 v[108:111], v[146:149], v[192:195], v[108:111]
	v_mfma_f32_16x16x32_bf16 v[76:79], v[154:157], v[192:195], v[76:79]
	s_barrier
	s_add_i32 s16, 0, 0x1c000
	s_add_i32 s17, s35, s20
	v_add_u32_e32 v141, s16, v139
	v_lshl_add_u64 v[166:167], v[166:167], 0, s[74:75]
	s_mov_b32 m0, s17
	ds_read_b128 v[196:199], v141
	ds_read_b128 v[200:203], v141 offset:1024
	ds_read_b128 v[212:215], v141 offset:2048
	ds_read_b128 v[216:219], v141 offset:3072
	global_load_lds_dwordx4 v[166:167], off
	v_lshl_add_u64 v[166:167], v[204:205], 0, s[74:75]
	s_add_i32 m0, s17, 0x2000
	s_nop 0
	global_load_lds_dwordx4 v[166:167], off
	s_barrier
	s_waitcnt lgkmcnt(0)
	s_waitcnt lgkmcnt(0)
	v_mfma_f32_16x16x32_bf16 v[112:115], v[196:199], v[158:161], v[112:115]
	v_mfma_f32_16x16x32_bf16 v[80:83], v[212:215], v[158:161], v[80:83]
	v_mfma_f32_16x16x32_bf16 v[104:107], v[196:199], v[170:173], v[104:107]
	v_mfma_f32_16x16x32_bf16 v[72:75], v[212:215], v[170:173], v[72:75]
	v_mfma_f32_16x16x32_bf16 v[96:99], v[196:199], v[180:183], v[96:99]
	v_mfma_f32_16x16x32_bf16 v[68:71], v[212:215], v[180:183], v[68:71]
	v_mfma_f32_16x16x32_bf16 v[92:95], v[196:199], v[188:191], v[92:95]
	v_mfma_f32_16x16x32_bf16 v[64:67], v[212:215], v[188:191], v[64:67]
	v_mfma_f32_16x16x32_bf16 v[112:115], v[200:203], v[162:165], v[112:115]
	v_mfma_f32_16x16x32_bf16 v[80:83], v[216:219], v[162:165], v[80:83]
	v_mfma_f32_16x16x32_bf16 v[104:107], v[200:203], v[176:179], v[104:107]
	v_mfma_f32_16x16x32_bf16 v[72:75], v[216:219], v[176:179], v[72:75]
	v_mfma_f32_16x16x32_bf16 v[96:99], v[200:203], v[184:187], v[96:99]
	v_mfma_f32_16x16x32_bf16 v[68:71], v[216:219], v[184:187], v[68:71]
	v_mfma_f32_16x16x32_bf16 v[92:95], v[200:203], v[192:195], v[92:95]
	v_mfma_f32_16x16x32_bf16 v[64:67], v[216:219], v[192:195], v[64:67]
	s_mov_b32 m0, s26
	v_lshl_add_u64 v[166:167], v[220:221], 0, s[74:75]
	s_barrier
	ds_read_b128 v[158:161], v140 offset:49152
	ds_read_b128 v[162:165], v140 offset:50176
	ds_read_b128 v[170:173], v140 offset:51200
	ds_read_b128 v[176:179], v140 offset:52224
	ds_read_b128 v[180:183], v140 offset:53248
	ds_read_b128 v[184:187], v140 offset:54272
	ds_read_b128 v[188:191], v140 offset:55296
	ds_read_b128 v[192:195], v140 offset:56320
	global_load_lds_dwordx4 v[166:167], off
	v_lshl_add_u64 v[166:167], v[222:223], 0, s[74:75]
	s_mov_b32 m0, s27
	s_nop 0
	global_load_lds_dwordx4 v[166:167], off
	s_barrier
	s_waitcnt lgkmcnt(0)
	s_waitcnt lgkmcnt(0)
	v_mfma_f32_16x16x32_bf16 v[32:35], v[142:145], v[158:161], v[32:35]
	v_mfma_f32_16x16x32_bf16 v[56:59], v[150:153], v[158:161], v[56:59]
	v_mfma_f32_16x16x32_bf16 v[36:39], v[142:145], v[170:173], v[36:39]
	v_mfma_f32_16x16x32_bf16 v[60:63], v[150:153], v[170:173], v[60:63]
	v_mfma_f32_16x16x32_bf16 v[40:43], v[142:145], v[180:183], v[40:43]
	v_mfma_f32_16x16x32_bf16 v[28:31], v[150:153], v[180:183], v[28:31]
	v_mfma_f32_16x16x32_bf16 v[44:47], v[142:145], v[188:191], v[44:47]
	v_mfma_f32_16x16x32_bf16 v[12:15], v[150:153], v[188:191], v[12:15]
	v_mfma_f32_16x16x32_bf16 v[32:35], v[146:149], v[162:165], v[32:35]
	v_mfma_f32_16x16x32_bf16 v[56:59], v[154:157], v[162:165], v[56:59]
	v_mfma_f32_16x16x32_bf16 v[36:39], v[146:149], v[176:179], v[36:39]
	v_mfma_f32_16x16x32_bf16 v[60:63], v[154:157], v[176:179], v[60:63]
	v_mfma_f32_16x16x32_bf16 v[40:43], v[146:149], v[184:187], v[40:43]
	v_mfma_f32_16x16x32_bf16 v[28:31], v[154:157], v[184:187], v[28:31]
	v_mfma_f32_16x16x32_bf16 v[44:47], v[146:149], v[192:195], v[44:47]
	v_mfma_f32_16x16x32_bf16 v[12:15], v[154:157], v[192:195], v[12:15]
	s_barrier
	s_add_u32 s14, s14, 0x40080
	s_addc_u32 s15, s15, 0
	s_add_i32 s16, s16, s20
	v_lshl_add_u64 v[142:143], s[14:15], 0, v[168:169]
	s_mov_b32 m0, s16
	s_nop 0
	global_load_lds_dwordx4 v[142:143], off
	v_lshl_add_u64 v[142:143], s[14:15], 0, v[128:129]
	s_add_i32 m0, s16, 0x2000
	s_nop 0
	global_load_lds_dwordx4 v[142:143], off
	s_waitcnt vmcnt(6)
	s_barrier
	v_mfma_f32_16x16x32_bf16 v[8:11], v[196:199], v[158:161], v[8:11]
	v_mfma_f32_16x16x32_bf16 v[48:51], v[212:215], v[158:161], v[48:51]
	v_mfma_f32_16x16x32_bf16 v[20:23], v[196:199], v[170:173], v[20:23]
	v_mfma_f32_16x16x32_bf16 v[52:55], v[212:215], v[170:173], v[52:55]
	v_mfma_f32_16x16x32_bf16 v[16:19], v[196:199], v[180:183], v[16:19]
	v_mfma_f32_16x16x32_bf16 v[4:7], v[212:215], v[180:183], v[4:7]
	v_mfma_f32_16x16x32_bf16 v[24:27], v[196:199], v[188:191], v[24:27]
	v_mfma_f32_16x16x32_bf16 v[0:3], v[212:215], v[188:191], v[0:3]
	v_mfma_f32_16x16x32_bf16 v[8:11], v[200:203], v[162:165], v[8:11]
	v_mfma_f32_16x16x32_bf16 v[48:51], v[216:219], v[162:165], v[48:51]
	v_mfma_f32_16x16x32_bf16 v[20:23], v[200:203], v[176:179], v[20:23]
	v_mfma_f32_16x16x32_bf16 v[52:55], v[216:219], v[176:179], v[52:55]
	v_mfma_f32_16x16x32_bf16 v[16:19], v[200:203], v[184:187], v[16:19]
	v_mfma_f32_16x16x32_bf16 v[4:7], v[216:219], v[184:187], v[4:7]
	v_mfma_f32_16x16x32_bf16 v[24:27], v[200:203], v[192:195], v[24:27]
	v_mfma_f32_16x16x32_bf16 v[0:3], v[216:219], v[192:195], v[0:3]
	s_add_i32 s34, s34, 2
	s_add_u32 s12, s12, 0x100
	s_addc_u32 s13, s13, 0
	s_cmp_gt_u32 s34, 13
	s_barrier
	s_cbranch_scc0 .LBB0_791
	s_cmpk_lt_u32 s19, 0x100
	s_cbranch_scc0 .LBB0_794
	s_barrier

.LBB0_920:
	s_add_i32 s36, 0, 0x10000
	v_add_u32_e32 v13, s36, v12
	ds_read_b128 v[14:17], v13
	ds_read_b128 v[18:21], v13 offset:1024
	ds_read_b128 v[22:25], v13 offset:2048
	ds_read_b128 v[26:29], v13 offset:3072
	s_add_u32 s34, s10, 0xb0080
	s_addc_u32 s35, s11, 0
	s_add_i32 s39, s20, 0xc000
	v_lshl_add_u64 v[10:11], s[34:35], 0, v[2:3]
	s_mov_b32 m0, s39
	s_add_i32 s3, s20, 0xe000
	ds_read_b128 v[30:33], v9
	ds_read_b128 v[34:37], v9 offset:1024
	ds_read_b128 v[38:41], v9 offset:2048
	ds_read_b128 v[42:45], v9 offset:3072
	ds_read_b128 v[46:49], v9 offset:4096
	ds_read_b128 v[50:53], v9 offset:5120
	ds_read_b128 v[54:57], v9 offset:6144
	ds_read_b128 v[58:61], v9 offset:7168
	global_load_lds_dwordx4 v[10:11], off
	v_lshl_add_u64 v[10:11], s[34:35], 0, v[0:1]
	s_mov_b32 m0, s3
	s_nop 0
	global_load_lds_dwordx4 v[10:11], off
	s_waitcnt lgkmcnt(8)
	s_barrier
	s_waitcnt lgkmcnt(0)
	s_waitcnt lgkmcnt(0)
	v_mfma_f32_16x16x32_bf16 v[62:65], v[14:17], v[30:33], 0
	v_mfma_f32_16x16x32_bf16 v[66:69], v[22:25], v[30:33], 0
	v_mfma_f32_16x16x32_bf16 v[70:73], v[14:17], v[38:41], 0
	v_mfma_f32_16x16x32_bf16 v[74:77], v[22:25], v[38:41], 0
	v_mfma_f32_16x16x32_bf16 v[78:81], v[14:17], v[46:49], 0
	v_mfma_f32_16x16x32_bf16 v[82:85], v[22:25], v[46:49], 0
	v_mfma_f32_16x16x32_bf16 v[86:89], v[14:17], v[54:57], 0
	v_mfma_f32_16x16x32_bf16 v[90:93], v[22:25], v[54:57], 0
	v_mfma_f32_16x16x32_bf16 v[62:65], v[18:21], v[34:37], v[62:65]
	v_mfma_f32_16x16x32_bf16 v[66:69], v[26:29], v[34:37], v[66:69]
	v_mfma_f32_16x16x32_bf16 v[70:73], v[18:21], v[42:45], v[70:73]
	v_mfma_f32_16x16x32_bf16 v[74:77], v[26:29], v[42:45], v[74:77]
	v_mfma_f32_16x16x32_bf16 v[78:81], v[18:21], v[50:53], v[78:81]
	v_mfma_f32_16x16x32_bf16 v[82:85], v[26:29], v[50:53], v[82:85]
	v_mfma_f32_16x16x32_bf16 v[86:89], v[18:21], v[58:61], v[86:89]
	v_mfma_f32_16x16x32_bf16 v[90:93], v[26:29], v[58:61], v[90:93]
	s_barrier
	s_add_i32 s37, 0, 0x14000
	v_lshl_add_u64 v[10:11], s[12:13], 0, v[2:3]
	s_mov_b64 s[40:41], 0x100
	s_add_i32 s36, s36, s17
	v_add_u32_e32 v168, s37, v12
	v_lshl_add_u64 v[110:111], v[10:11], 0, s[40:41]
	s_mov_b32 m0, s36
	v_lshl_add_u64 v[166:167], s[12:13], 0, v[0:1]
	s_add_i32 s34, s36, 0x2000
	ds_read_b128 v[94:97], v168
	ds_read_b128 v[98:101], v168 offset:1024
	ds_read_b128 v[102:105], v168 offset:2048
	ds_read_b128 v[106:109], v168 offset:3072
	global_load_lds_dwordx4 v[110:111], off
	v_lshl_add_u64 v[110:111], v[166:167], 0, s[40:41]
	s_mov_b32 m0, s34
	s_nop 0
	global_load_lds_dwordx4 v[110:111], off
	s_barrier
	s_waitcnt lgkmcnt(0)
	s_waitcnt lgkmcnt(0)
	v_mfma_f32_16x16x32_bf16 v[110:113], v[94:97], v[30:33], 0
	v_mfma_f32_16x16x32_bf16 v[30:33], v[102:105], v[30:33], 0
	v_mfma_f32_16x16x32_bf16 v[110:113], v[98:101], v[34:37], v[110:113]
	v_mfma_f32_16x16x32_bf16 v[30:33], v[106:109], v[34:37], v[30:33]
	v_mfma_f32_16x16x32_bf16 v[34:37], v[94:97], v[38:41], 0
	v_mfma_f32_16x16x32_bf16 v[38:41], v[102:105], v[38:41], 0
	v_mfma_f32_16x16x32_bf16 v[34:37], v[98:101], v[42:45], v[34:37]
	v_mfma_f32_16x16x32_bf16 v[38:41], v[106:109], v[42:45], v[38:41]
	v_mfma_f32_16x16x32_bf16 v[42:45], v[94:97], v[46:49], 0
	v_mfma_f32_16x16x32_bf16 v[46:49], v[102:105], v[46:49], 0
	v_mfma_f32_16x16x32_bf16 v[42:45], v[98:101], v[50:53], v[42:45]
	v_mfma_f32_16x16x32_bf16 v[46:49], v[106:109], v[50:53], v[46:49]
	v_mfma_f32_16x16x32_bf16 v[50:53], v[94:97], v[54:57], 0
	v_mfma_f32_16x16x32_bf16 v[54:57], v[102:105], v[54:57], 0
	v_mfma_f32_16x16x32_bf16 v[50:53], v[98:101], v[58:61], v[50:53]
	v_mfma_f32_16x16x32_bf16 v[54:57], v[106:109], v[58:61], v[54:57]
	v_lshl_add_u64 v[216:217], s[10:11], 0, v[2:3]
	s_mov_b32 m0, s20
	v_lshl_add_u64 v[142:143], v[216:217], 0, s[40:41]
	v_lshl_add_u64 v[218:219], s[10:11], 0, v[0:1]
	s_barrier
	ds_read_b128 v[58:61], v9 offset:16384
	ds_read_b128 v[114:117], v9 offset:17408
	ds_read_b128 v[118:121], v9 offset:18432
	ds_read_b128 v[122:125], v9 offset:19456
	ds_read_b128 v[126:129], v9 offset:20480
	ds_read_b128 v[130:133], v9 offset:21504
	ds_read_b128 v[134:137], v9 offset:22528
	ds_read_b128 v[138:141], v9 offset:23552
	global_load_lds_dwordx4 v[142:143], off
	v_lshl_add_u64 v[142:143], v[218:219], 0, s[40:41]
	s_mov_b32 m0, s21
	s_nop 0
	global_load_lds_dwordx4 v[142:143], off
	s_barrier
	s_waitcnt lgkmcnt(0)
	s_waitcnt lgkmcnt(0)
	v_mfma_f32_16x16x32_bf16 v[142:145], v[14:17], v[58:61], 0
	v_mfma_f32_16x16x32_bf16 v[150:153], v[14:17], v[118:121], 0
	v_mfma_f32_16x16x32_bf16 v[158:161], v[14:17], v[126:129], 0
	v_mfma_f32_16x16x32_bf16 v[14:17], v[14:17], v[134:137], 0
	v_mfma_f32_16x16x32_bf16 v[142:145], v[18:21], v[114:117], v[142:145]
	v_mfma_f32_16x16x32_bf16 v[146:149], v[22:25], v[58:61], 0
	v_mfma_f32_16x16x32_bf16 v[150:153], v[18:21], v[122:125], v[150:153]
	v_mfma_f32_16x16x32_bf16 v[154:157], v[22:25], v[118:121], 0
	v_mfma_f32_16x16x32_bf16 v[158:161], v[18:21], v[130:133], v[158:161]
	v_mfma_f32_16x16x32_bf16 v[162:165], v[22:25], v[126:129], 0
	v_mfma_f32_16x16x32_bf16 v[14:17], v[18:21], v[138:141], v[14:17]
	v_mfma_f32_16x16x32_bf16 v[18:21], v[22:25], v[134:137], 0
	v_mfma_f32_16x16x32_bf16 v[146:149], v[26:29], v[114:117], v[146:149]
	v_mfma_f32_16x16x32_bf16 v[154:157], v[26:29], v[122:125], v[154:157]
	v_mfma_f32_16x16x32_bf16 v[162:165], v[26:29], v[130:133], v[162:165]
	v_mfma_f32_16x16x32_bf16 v[18:21], v[26:29], v[138:141], v[18:21]
	s_barrier
	s_add_u32 s40, s12, 0xb0100
	s_addc_u32 s41, s13, 0
	s_add_i32 s37, s37, s17
	v_lshl_add_u64 v[22:23], s[40:41], 0, v[2:3]
	s_mov_b32 m0, s37
	s_add_i32 s35, s37, 0x2000
	global_load_lds_dwordx4 v[22:23], off
	v_lshl_add_u64 v[22:23], s[40:41], 0, v[0:1]
	s_mov_b32 m0, s35
	s_nop 0
	global_load_lds_dwordx4 v[22:23], off
	s_waitcnt vmcnt(6)
	s_barrier
	v_mfma_f32_16x16x32_bf16 v[22:25], v[94:97], v[58:61], 0
	v_mfma_f32_16x16x32_bf16 v[26:29], v[102:105], v[58:61], 0
	v_mfma_f32_16x16x32_bf16 v[22:25], v[98:101], v[114:117], v[22:25]
	v_mfma_f32_16x16x32_bf16 v[26:29], v[106:109], v[114:117], v[26:29]
	v_mfma_f32_16x16x32_bf16 v[58:61], v[94:97], v[118:121], 0
	v_mfma_f32_16x16x32_bf16 v[114:117], v[102:105], v[118:121], 0
	v_mfma_f32_16x16x32_bf16 v[118:121], v[94:97], v[126:129], 0
	v_mfma_f32_16x16x32_bf16 v[94:97], v[94:97], v[134:137], 0
	v_mfma_f32_16x16x32_bf16 v[58:61], v[98:101], v[122:125], v[58:61]
	v_mfma_f32_16x16x32_bf16 v[114:117], v[106:109], v[122:125], v[114:117]
	v_mfma_f32_16x16x32_bf16 v[118:121], v[98:101], v[130:133], v[118:121]
	v_mfma_f32_16x16x32_bf16 v[122:125], v[102:105], v[126:129], 0
	v_mfma_f32_16x16x32_bf16 v[94:97], v[98:101], v[138:141], v[94:97]
	v_mfma_f32_16x16x32_bf16 v[98:101], v[102:105], v[134:137], 0
	v_mfma_f32_16x16x32_bf16 v[122:125], v[106:109], v[130:133], v[122:125]
	v_mfma_f32_16x16x32_bf16 v[98:101], v[106:109], v[138:141], v[98:101]
	s_add_i32 s38, 0, 0x18000
	v_add_u32_e32 v211, s38, v12
	s_barrier
	ds_read_b128 v[102:105], v211
	ds_read_b128 v[106:109], v211 offset:1024
	ds_read_b128 v[126:129], v211 offset:2048
	ds_read_b128 v[130:133], v211 offset:3072
	s_add_u32 s40, s10, 0xb0100
	s_addc_u32 s41, s11, 0
	s_mov_b32 m0, s22
	v_lshl_add_u64 v[194:195], s[40:41], 0, v[2:3]
	ds_read_b128 v[134:137], v9 offset:32768
	ds_read_b128 v[138:141], v9 offset:33792
	ds_read_b128 v[170:173], v9 offset:34816
	ds_read_b128 v[174:177], v9 offset:35840
	ds_read_b128 v[178:181], v9 offset:36864
	ds_read_b128 v[182:185], v9 offset:37888
	ds_read_b128 v[186:189], v9 offset:38912
	ds_read_b128 v[190:193], v9 offset:39936
	global_load_lds_dwordx4 v[194:195], off
	v_lshl_add_u64 v[194:195], s[40:41], 0, v[0:1]
	s_mov_b32 m0, s23
	s_nop 0
	global_load_lds_dwordx4 v[194:195], off
	s_waitcnt lgkmcnt(8)
	s_barrier
	s_waitcnt lgkmcnt(0)
	s_waitcnt lgkmcnt(0)
	v_mfma_f32_16x16x32_bf16 v[62:65], v[102:105], v[134:137], v[62:65]
	v_mfma_f32_16x16x32_bf16 v[66:69], v[126:129], v[134:137], v[66:69]
	v_mfma_f32_16x16x32_bf16 v[70:73], v[102:105], v[170:173], v[70:73]
	v_mfma_f32_16x16x32_bf16 v[74:77], v[126:129], v[170:173], v[74:77]
	v_mfma_f32_16x16x32_bf16 v[78:81], v[102:105], v[178:181], v[78:81]
	v_mfma_f32_16x16x32_bf16 v[82:85], v[126:129], v[178:181], v[82:85]
	v_mfma_f32_16x16x32_bf16 v[86:89], v[102:105], v[186:189], v[86:89]
	v_mfma_f32_16x16x32_bf16 v[90:93], v[126:129], v[186:189], v[90:93]
	v_mfma_f32_16x16x32_bf16 v[62:65], v[106:109], v[138:141], v[62:65]
	v_mfma_f32_16x16x32_bf16 v[66:69], v[130:133], v[138:141], v[66:69]
	v_mfma_f32_16x16x32_bf16 v[70:73], v[106:109], v[174:177], v[70:73]
	v_mfma_f32_16x16x32_bf16 v[74:77], v[130:133], v[174:177], v[74:77]
	v_mfma_f32_16x16x32_bf16 v[78:81], v[106:109], v[182:185], v[78:81]
	v_mfma_f32_16x16x32_bf16 v[82:85], v[130:133], v[182:185], v[82:85]
	v_mfma_f32_16x16x32_bf16 v[86:89], v[106:109], v[190:193], v[86:89]
	v_mfma_f32_16x16x32_bf16 v[90:93], v[130:133], v[190:193], v[90:93]
	s_barrier
	s_add_i32 s41, 0, 0x1c000
	s_mov_b64 s[42:43], 0x180
	s_add_i32 s40, s38, s17
	v_add_u32_e32 v220, s41, v12
	v_lshl_add_u64 v[10:11], v[10:11], 0, s[42:43]
	s_mov_b32 m0, s40
	s_add_i32 s38, s40, 0x2000
	ds_read_b128 v[194:197], v220
	ds_read_b128 v[198:201], v220 offset:1024
	ds_read_b128 v[202:205], v220 offset:2048
	ds_read_b128 v[212:215], v220 offset:3072
	global_load_lds_dwordx4 v[10:11], off
	v_lshl_add_u64 v[10:11], v[166:167], 0, s[42:43]
	s_mov_b32 m0, s38
	s_nop 0
	global_load_lds_dwordx4 v[10:11], off
	s_barrier
	s_waitcnt lgkmcnt(0)
	s_waitcnt lgkmcnt(0)
	v_mfma_f32_16x16x32_bf16 v[110:113], v[194:197], v[134:137], v[110:113]
	v_mfma_f32_16x16x32_bf16 v[30:33], v[202:205], v[134:137], v[30:33]
	v_mfma_f32_16x16x32_bf16 v[34:37], v[194:197], v[170:173], v[34:37]
	v_mfma_f32_16x16x32_bf16 v[38:41], v[202:205], v[170:173], v[38:41]
	v_mfma_f32_16x16x32_bf16 v[42:45], v[194:197], v[178:181], v[42:45]
	v_mfma_f32_16x16x32_bf16 v[46:49], v[202:205], v[178:181], v[46:49]
	v_mfma_f32_16x16x32_bf16 v[50:53], v[194:197], v[186:189], v[50:53]
	v_mfma_f32_16x16x32_bf16 v[54:57], v[202:205], v[186:189], v[54:57]
	v_mfma_f32_16x16x32_bf16 v[110:113], v[198:201], v[138:141], v[110:113]
	v_mfma_f32_16x16x32_bf16 v[30:33], v[212:215], v[138:141], v[30:33]
	v_mfma_f32_16x16x32_bf16 v[34:37], v[198:201], v[174:177], v[34:37]
	v_mfma_f32_16x16x32_bf16 v[38:41], v[212:215], v[174:177], v[38:41]
	v_mfma_f32_16x16x32_bf16 v[42:45], v[198:201], v[182:185], v[42:45]
	v_mfma_f32_16x16x32_bf16 v[46:49], v[212:215], v[182:185], v[46:49]
	v_mfma_f32_16x16x32_bf16 v[50:53], v[198:201], v[190:193], v[50:53]
	v_mfma_f32_16x16x32_bf16 v[54:57], v[212:215], v[190:193], v[54:57]
	s_mov_b32 m0, s26
	v_lshl_add_u64 v[10:11], v[216:217], 0, s[42:43]
	s_barrier
	ds_read_b128 v[134:137], v9 offset:49152
	ds_read_b128 v[138:141], v9 offset:50176
	ds_read_b128 v[170:173], v9 offset:51200
	ds_read_b128 v[174:177], v9 offset:52224
	ds_read_b128 v[178:181], v9 offset:53248
	ds_read_b128 v[182:185], v9 offset:54272
	ds_read_b128 v[186:189], v9 offset:55296
	ds_read_b128 v[190:193], v9 offset:56320
	global_load_lds_dwordx4 v[10:11], off
	v_lshl_add_u64 v[10:11], v[218:219], 0, s[42:43]
	s_mov_b32 m0, s27
	s_nop 0
	global_load_lds_dwordx4 v[10:11], off
	s_barrier
	s_waitcnt lgkmcnt(0)
	s_waitcnt lgkmcnt(0)
	v_mfma_f32_16x16x32_bf16 v[142:145], v[102:105], v[134:137], v[142:145]
	v_mfma_f32_16x16x32_bf16 v[146:149], v[126:129], v[134:137], v[146:149]
	v_mfma_f32_16x16x32_bf16 v[150:153], v[102:105], v[170:173], v[150:153]
	v_mfma_f32_16x16x32_bf16 v[154:157], v[126:129], v[170:173], v[154:157]
	v_mfma_f32_16x16x32_bf16 v[158:161], v[102:105], v[178:181], v[158:161]
	v_mfma_f32_16x16x32_bf16 v[162:165], v[126:129], v[178:181], v[162:165]
	v_mfma_f32_16x16x32_bf16 v[14:17], v[102:105], v[186:189], v[14:17]
	v_mfma_f32_16x16x32_bf16 v[18:21], v[126:129], v[186:189], v[18:21]
	v_mfma_f32_16x16x32_bf16 v[142:145], v[106:109], v[138:141], v[142:145]
	v_mfma_f32_16x16x32_bf16 v[146:149], v[130:133], v[138:141], v[146:149]
	v_mfma_f32_16x16x32_bf16 v[150:153], v[106:109], v[174:177], v[150:153]
	v_mfma_f32_16x16x32_bf16 v[154:157], v[130:133], v[174:177], v[154:157]
	v_mfma_f32_16x16x32_bf16 v[158:161], v[106:109], v[182:185], v[158:161]
	v_mfma_f32_16x16x32_bf16 v[162:165], v[130:133], v[182:185], v[162:165]
	v_mfma_f32_16x16x32_bf16 v[14:17], v[106:109], v[190:193], v[14:17]
	v_mfma_f32_16x16x32_bf16 v[18:21], v[130:133], v[190:193], v[18:21]
	s_barrier
	s_add_u32 s42, s12, 0xb0180
	s_addc_u32 s43, s13, 0
	s_add_i32 s13, s41, s17
	v_lshl_add_u64 v[10:11], s[42:43], 0, v[2:3]
	s_mov_b32 m0, s13
	s_add_i32 s12, s13, 0x2000
	global_load_lds_dwordx4 v[10:11], off
	v_lshl_add_u64 v[10:11], s[42:43], 0, v[0:1]
	s_mov_b32 m0, s12
	s_nop 0
	global_load_lds_dwordx4 v[10:11], off
	s_waitcnt vmcnt(6)
	s_barrier
	v_mfma_f32_16x16x32_bf16 v[22:25], v[194:197], v[134:137], v[22:25]
	v_mfma_f32_16x16x32_bf16 v[26:29], v[202:205], v[134:137], v[26:29]
	v_mfma_f32_16x16x32_bf16 v[58:61], v[194:197], v[170:173], v[58:61]
	v_mfma_f32_16x16x32_bf16 v[102:105], v[202:205], v[170:173], v[114:117]
	v_mfma_f32_16x16x32_bf16 v[106:109], v[194:197], v[178:181], v[118:121]
	v_mfma_f32_16x16x32_bf16 v[114:117], v[202:205], v[178:181], v[122:125]
	v_mfma_f32_16x16x32_bf16 v[94:97], v[194:197], v[186:189], v[94:97]
	v_mfma_f32_16x16x32_bf16 v[98:101], v[202:205], v[186:189], v[98:101]
	v_mfma_f32_16x16x32_bf16 v[22:25], v[198:201], v[138:141], v[22:25]
	v_mfma_f32_16x16x32_bf16 v[26:29], v[212:215], v[138:141], v[26:29]
	v_mfma_f32_16x16x32_bf16 v[58:61], v[198:201], v[174:177], v[58:61]
	v_mfma_f32_16x16x32_bf16 v[102:105], v[212:215], v[174:177], v[102:105]
	v_mfma_f32_16x16x32_bf16 v[106:109], v[198:201], v[182:185], v[106:109]
	v_mfma_f32_16x16x32_bf16 v[114:117], v[212:215], v[182:185], v[114:117]
	v_mfma_f32_16x16x32_bf16 v[94:97], v[198:201], v[190:193], v[94:97]
	v_mfma_f32_16x16x32_bf16 v[98:101], v[212:215], v[190:193], v[98:101]
	s_barrier
	ds_read_b128 v[118:121], v13
	ds_read_b128 v[122:125], v13 offset:1024
	ds_read_b128 v[126:129], v13 offset:2048
	ds_read_b128 v[130:133], v13 offset:3072
	s_add_u32 s10, s10, 0xb0180
	s_addc_u32 s11, s11, 0
	s_mov_b32 m0, s39
	v_lshl_add_u64 v[10:11], s[10:11], 0, v[2:3]
	ds_read_b128 v[134:137], v9
	ds_read_b128 v[138:141], v9 offset:1024
	ds_read_b128 v[170:173], v9 offset:2048
	ds_read_b128 v[174:177], v9 offset:3072
	ds_read_b128 v[178:181], v9 offset:4096
	ds_read_b128 v[182:185], v9 offset:5120
	ds_read_b128 v[186:189], v9 offset:6144
	ds_read_b128 v[190:193], v9 offset:7168
	global_load_lds_dwordx4 v[10:11], off
	v_lshl_add_u64 v[10:11], s[10:11], 0, v[0:1]
	s_mov_b32 m0, s3
	s_nop 0
	global_load_lds_dwordx4 v[10:11], off
	s_waitcnt lgkmcnt(8)
	s_barrier
	s_waitcnt lgkmcnt(0)
	s_waitcnt lgkmcnt(0)
	v_mfma_f32_16x16x32_bf16 v[62:65], v[118:121], v[134:137], v[62:65]
	v_mfma_f32_16x16x32_bf16 v[66:69], v[126:129], v[134:137], v[66:69]
	v_mfma_f32_16x16x32_bf16 v[70:73], v[118:121], v[170:173], v[70:73]
	v_mfma_f32_16x16x32_bf16 v[74:77], v[126:129], v[170:173], v[74:77]
	v_mfma_f32_16x16x32_bf16 v[78:81], v[118:121], v[178:181], v[78:81]
	v_mfma_f32_16x16x32_bf16 v[82:85], v[126:129], v[178:181], v[82:85]
	v_mfma_f32_16x16x32_bf16 v[86:89], v[118:121], v[186:189], v[86:89]
	v_mfma_f32_16x16x32_bf16 v[90:93], v[126:129], v[186:189], v[90:93]
	v_mfma_f32_16x16x32_bf16 v[62:65], v[122:125], v[138:141], v[62:65]
	v_mfma_f32_16x16x32_bf16 v[66:69], v[130:133], v[138:141], v[66:69]
	v_mfma_f32_16x16x32_bf16 v[70:73], v[122:125], v[174:177], v[70:73]
	v_mfma_f32_16x16x32_bf16 v[74:77], v[130:133], v[174:177], v[74:77]
	v_mfma_f32_16x16x32_bf16 v[78:81], v[122:125], v[182:185], v[78:81]
	v_mfma_f32_16x16x32_bf16 v[82:85], v[130:133], v[182:185], v[82:85]
	v_mfma_f32_16x16x32_bf16 v[86:89], v[122:125], v[190:193], v[86:89]
	v_mfma_f32_16x16x32_bf16 v[90:93], v[130:133], v[190:193], v[90:93]
	s_barrier
	s_mov_b32 m0, s36
	v_lshl_add_u64 v[10:11], s[6:7], 0, v[2:3]
	ds_read_b128 v[194:197], v168
	ds_read_b128 v[198:201], v168 offset:1024
	ds_read_b128 v[202:205], v168 offset:2048
	ds_read_b128 v[212:215], v168 offset:3072
	global_load_lds_dwordx4 v[10:11], off
	v_lshl_add_u64 v[166:167], s[6:7], 0, v[0:1]
	s_mov_b32 m0, s34
	s_nop 0
	global_load_lds_dwordx4 v[166:167], off
	s_barrier
	s_waitcnt lgkmcnt(0)
	s_waitcnt lgkmcnt(0)
	v_mfma_f32_16x16x32_bf16 v[110:113], v[194:197], v[134:137], v[110:113]
	v_mfma_f32_16x16x32_bf16 v[30:33], v[202:205], v[134:137], v[30:33]
	v_mfma_f32_16x16x32_bf16 v[34:37], v[194:197], v[170:173], v[34:37]
	v_mfma_f32_16x16x32_bf16 v[38:41], v[202:205], v[170:173], v[38:41]
	v_mfma_f32_16x16x32_bf16 v[42:45], v[194:197], v[178:181], v[42:45]
	v_mfma_f32_16x16x32_bf16 v[46:49], v[202:205], v[178:181], v[46:49]
	v_mfma_f32_16x16x32_bf16 v[50:53], v[194:197], v[186:189], v[50:53]
	v_mfma_f32_16x16x32_bf16 v[54:57], v[202:205], v[186:189], v[54:57]
	v_mfma_f32_16x16x32_bf16 v[110:113], v[198:201], v[138:141], v[110:113]
	v_mfma_f32_16x16x32_bf16 v[30:33], v[212:215], v[138:141], v[30:33]
	v_mfma_f32_16x16x32_bf16 v[34:37], v[198:201], v[174:177], v[34:37]
	v_mfma_f32_16x16x32_bf16 v[38:41], v[212:215], v[174:177], v[38:41]
	v_mfma_f32_16x16x32_bf16 v[42:45], v[198:201], v[182:185], v[42:45]
	v_mfma_f32_16x16x32_bf16 v[46:49], v[212:215], v[182:185], v[46:49]
	v_mfma_f32_16x16x32_bf16 v[50:53], v[198:201], v[190:193], v[50:53]
	v_mfma_f32_16x16x32_bf16 v[54:57], v[212:215], v[190:193], v[54:57]
	s_mov_b32 m0, s20
	v_lshl_add_u64 v[216:217], s[0:1], 0, v[2:3]
	s_barrier
	ds_read_b128 v[134:137], v9 offset:16384
	ds_read_b128 v[138:141], v9 offset:17408
	ds_read_b128 v[170:173], v9 offset:18432
	ds_read_b128 v[174:177], v9 offset:19456
	ds_read_b128 v[178:181], v9 offset:20480
	ds_read_b128 v[182:185], v9 offset:21504
	ds_read_b128 v[186:189], v9 offset:22528
	ds_read_b128 v[190:193], v9 offset:23552
	global_load_lds_dwordx4 v[216:217], off
	v_lshl_add_u64 v[218:219], s[0:1], 0, v[0:1]
	s_mov_b32 m0, s21
	s_nop 0
	global_load_lds_dwordx4 v[218:219], off
	s_barrier
	s_waitcnt lgkmcnt(0)
	s_waitcnt lgkmcnt(0)
	v_mfma_f32_16x16x32_bf16 v[142:145], v[118:121], v[134:137], v[142:145]
	v_mfma_f32_16x16x32_bf16 v[146:149], v[126:129], v[134:137], v[146:149]
	v_mfma_f32_16x16x32_bf16 v[150:153], v[118:121], v[170:173], v[150:153]
	v_mfma_f32_16x16x32_bf16 v[154:157], v[126:129], v[170:173], v[154:157]
	v_mfma_f32_16x16x32_bf16 v[158:161], v[118:121], v[178:181], v[158:161]
	v_mfma_f32_16x16x32_bf16 v[162:165], v[126:129], v[178:181], v[162:165]
	v_mfma_f32_16x16x32_bf16 v[14:17], v[118:121], v[186:189], v[14:17]
	v_mfma_f32_16x16x32_bf16 v[18:21], v[126:129], v[186:189], v[18:21]
	v_mfma_f32_16x16x32_bf16 v[142:145], v[122:125], v[138:141], v[142:145]
	v_mfma_f32_16x16x32_bf16 v[146:149], v[130:133], v[138:141], v[146:149]
	v_mfma_f32_16x16x32_bf16 v[150:153], v[122:125], v[174:177], v[150:153]
	v_mfma_f32_16x16x32_bf16 v[154:157], v[130:133], v[174:177], v[154:157]
	v_mfma_f32_16x16x32_bf16 v[158:161], v[122:125], v[182:185], v[158:161]
	v_mfma_f32_16x16x32_bf16 v[162:165], v[130:133], v[182:185], v[162:165]
	v_mfma_f32_16x16x32_bf16 v[14:17], v[122:125], v[190:193], v[14:17]
	v_mfma_f32_16x16x32_bf16 v[18:21], v[130:133], v[190:193], v[18:21]
	s_barrier
	s_add_u32 s10, s6, 0xb0000
	s_addc_u32 s11, s7, 0
	s_mov_b32 m0, s37
	v_lshl_add_u64 v[118:119], s[10:11], 0, v[2:3]
	global_load_lds_dwordx4 v[118:119], off
	v_lshl_add_u64 v[118:119], s[10:11], 0, v[0:1]
	s_mov_b32 m0, s35
	s_nop 0
	global_load_lds_dwordx4 v[118:119], off
	s_waitcnt vmcnt(6)
	s_barrier
	v_mfma_f32_16x16x32_bf16 v[22:25], v[194:197], v[134:137], v[22:25]
	v_mfma_f32_16x16x32_bf16 v[26:29], v[202:205], v[134:137], v[26:29]
	v_mfma_f32_16x16x32_bf16 v[58:61], v[194:197], v[170:173], v[58:61]
	v_mfma_f32_16x16x32_bf16 v[102:105], v[202:205], v[170:173], v[102:105]
	v_mfma_f32_16x16x32_bf16 v[106:109], v[194:197], v[178:181], v[106:109]
	v_mfma_f32_16x16x32_bf16 v[114:117], v[202:205], v[178:181], v[114:117]
	v_mfma_f32_16x16x32_bf16 v[94:97], v[194:197], v[186:189], v[94:97]
	v_mfma_f32_16x16x32_bf16 v[98:101], v[202:205], v[186:189], v[98:101]
	v_mfma_f32_16x16x32_bf16 v[22:25], v[198:201], v[138:141], v[22:25]
	v_mfma_f32_16x16x32_bf16 v[26:29], v[212:215], v[138:141], v[26:29]
	v_mfma_f32_16x16x32_bf16 v[58:61], v[198:201], v[174:177], v[58:61]
	v_mfma_f32_16x16x32_bf16 v[102:105], v[212:215], v[174:177], v[102:105]
	v_mfma_f32_16x16x32_bf16 v[106:109], v[198:201], v[182:185], v[106:109]
	v_mfma_f32_16x16x32_bf16 v[114:117], v[212:215], v[182:185], v[114:117]
	v_mfma_f32_16x16x32_bf16 v[94:97], v[198:201], v[190:193], v[94:97]
	v_mfma_f32_16x16x32_bf16 v[98:101], v[212:215], v[190:193], v[98:101]
	s_barrier
	ds_read_b128 v[118:121], v211
	ds_read_b128 v[122:125], v211 offset:1024
	ds_read_b128 v[126:129], v211 offset:2048
	ds_read_b128 v[130:133], v211 offset:3072
	s_add_u32 s10, s0, 0xb0000
	s_addc_u32 s11, s1, 0
	s_mov_b32 m0, s22
	v_lshl_add_u64 v[194:195], s[10:11], 0, v[2:3]
	ds_read_b128 v[134:137], v9 offset:32768
	ds_read_b128 v[138:141], v9 offset:33792
	ds_read_b128 v[170:173], v9 offset:34816
	ds_read_b128 v[174:177], v9 offset:35840
	ds_read_b128 v[178:181], v9 offset:36864
	ds_read_b128 v[182:185], v9 offset:37888
	ds_read_b128 v[186:189], v9 offset:38912
	ds_read_b128 v[190:193], v9 offset:39936
	global_load_lds_dwordx4 v[194:195], off
	v_lshl_add_u64 v[194:195], s[10:11], 0, v[0:1]
	s_mov_b32 m0, s23
	s_nop 0
	global_load_lds_dwordx4 v[194:195], off
	s_waitcnt lgkmcnt(8)
	s_barrier
	s_waitcnt lgkmcnt(0)
	s_waitcnt lgkmcnt(0)
	v_mfma_f32_16x16x32_bf16 v[62:65], v[118:121], v[134:137], v[62:65]
	v_mfma_f32_16x16x32_bf16 v[66:69], v[126:129], v[134:137], v[66:69]
	v_mfma_f32_16x16x32_bf16 v[70:73], v[118:121], v[170:173], v[70:73]
	v_mfma_f32_16x16x32_bf16 v[74:77], v[126:129], v[170:173], v[74:77]
	v_mfma_f32_16x16x32_bf16 v[78:81], v[118:121], v[178:181], v[78:81]
	v_mfma_f32_16x16x32_bf16 v[82:85], v[126:129], v[178:181], v[82:85]
	v_mfma_f32_16x16x32_bf16 v[86:89], v[118:121], v[186:189], v[86:89]
	v_mfma_f32_16x16x32_bf16 v[90:93], v[126:129], v[186:189], v[90:93]
	v_mfma_f32_16x16x32_bf16 v[62:65], v[122:125], v[138:141], v[62:65]
	v_mfma_f32_16x16x32_bf16 v[66:69], v[130:133], v[138:141], v[66:69]
	v_mfma_f32_16x16x32_bf16 v[70:73], v[122:125], v[174:177], v[70:73]
	v_mfma_f32_16x16x32_bf16 v[74:77], v[130:133], v[174:177], v[74:77]
	v_mfma_f32_16x16x32_bf16 v[78:81], v[122:125], v[182:185], v[78:81]
	v_mfma_f32_16x16x32_bf16 v[82:85], v[130:133], v[182:185], v[82:85]
	v_mfma_f32_16x16x32_bf16 v[86:89], v[122:125], v[190:193], v[86:89]
	v_mfma_f32_16x16x32_bf16 v[90:93], v[130:133], v[190:193], v[90:93]
	s_barrier
	s_mov_b32 m0, s40
	v_lshl_add_u64 v[10:11], v[10:11], 0, s[74:75]
	ds_read_b128 v[194:197], v220
	ds_read_b128 v[198:201], v220 offset:1024
	ds_read_b128 v[202:205], v220 offset:2048
	ds_read_b128 v[212:215], v220 offset:3072
	global_load_lds_dwordx4 v[10:11], off
	v_lshl_add_u64 v[10:11], v[166:167], 0, s[74:75]
	s_mov_b32 m0, s38
	s_nop 0
	global_load_lds_dwordx4 v[10:11], off
	s_barrier
	s_waitcnt lgkmcnt(0)
	s_waitcnt lgkmcnt(0)
	v_mfma_f32_16x16x32_bf16 v[110:113], v[194:197], v[134:137], v[110:113]
	v_mfma_f32_16x16x32_bf16 v[30:33], v[202:205], v[134:137], v[30:33]
	v_mfma_f32_16x16x32_bf16 v[34:37], v[194:197], v[170:173], v[34:37]
	v_mfma_f32_16x16x32_bf16 v[38:41], v[202:205], v[170:173], v[38:41]
	v_mfma_f32_16x16x32_bf16 v[42:45], v[194:197], v[178:181], v[42:45]
	v_mfma_f32_16x16x32_bf16 v[46:49], v[202:205], v[178:181], v[46:49]
	v_mfma_f32_16x16x32_bf16 v[50:53], v[194:197], v[186:189], v[50:53]
	v_mfma_f32_16x16x32_bf16 v[54:57], v[202:205], v[186:189], v[54:57]
	v_mfma_f32_16x16x32_bf16 v[110:113], v[198:201], v[138:141], v[110:113]
	v_mfma_f32_16x16x32_bf16 v[30:33], v[212:215], v[138:141], v[30:33]
	v_mfma_f32_16x16x32_bf16 v[34:37], v[198:201], v[174:177], v[34:37]
	v_mfma_f32_16x16x32_bf16 v[38:41], v[212:215], v[174:177], v[38:41]
	v_mfma_f32_16x16x32_bf16 v[42:45], v[198:201], v[182:185], v[42:45]
	v_mfma_f32_16x16x32_bf16 v[46:49], v[212:215], v[182:185], v[46:49]
	v_mfma_f32_16x16x32_bf16 v[50:53], v[198:201], v[190:193], v[50:53]
	v_mfma_f32_16x16x32_bf16 v[54:57], v[212:215], v[190:193], v[54:57]
	s_mov_b32 m0, s26
	v_lshl_add_u64 v[10:11], v[216:217], 0, s[74:75]
	s_barrier
	ds_read_b128 v[134:137], v9 offset:49152
	ds_read_b128 v[138:141], v9 offset:50176
	ds_read_b128 v[170:173], v9 offset:51200
	ds_read_b128 v[174:177], v9 offset:52224
	ds_read_b128 v[178:181], v9 offset:53248
	ds_read_b128 v[182:185], v9 offset:54272
	ds_read_b128 v[186:189], v9 offset:55296
	ds_read_b128 v[190:193], v9 offset:56320
	global_load_lds_dwordx4 v[10:11], off
	v_lshl_add_u64 v[10:11], v[218:219], 0, s[74:75]
	s_mov_b32 m0, s27
	s_nop 0
	global_load_lds_dwordx4 v[10:11], off
	s_barrier
	s_waitcnt lgkmcnt(0)
	s_waitcnt lgkmcnt(0)
	v_mfma_f32_16x16x32_bf16 v[142:145], v[118:121], v[134:137], v[142:145]
	v_mfma_f32_16x16x32_bf16 v[146:149], v[126:129], v[134:137], v[146:149]
	v_mfma_f32_16x16x32_bf16 v[150:153], v[118:121], v[170:173], v[150:153]
	v_mfma_f32_16x16x32_bf16 v[154:157], v[126:129], v[170:173], v[154:157]
	v_mfma_f32_16x16x32_bf16 v[158:161], v[118:121], v[178:181], v[158:161]
	v_mfma_f32_16x16x32_bf16 v[162:165], v[126:129], v[178:181], v[162:165]
	v_mfma_f32_16x16x32_bf16 v[14:17], v[118:121], v[186:189], v[14:17]
	v_mfma_f32_16x16x32_bf16 v[18:21], v[126:129], v[186:189], v[18:21]
	v_mfma_f32_16x16x32_bf16 v[142:145], v[122:125], v[138:141], v[142:145]
	v_mfma_f32_16x16x32_bf16 v[146:149], v[130:133], v[138:141], v[146:149]
	v_mfma_f32_16x16x32_bf16 v[150:153], v[122:125], v[174:177], v[150:153]
	v_mfma_f32_16x16x32_bf16 v[154:157], v[130:133], v[174:177], v[154:157]
	v_mfma_f32_16x16x32_bf16 v[158:161], v[122:125], v[182:185], v[158:161]
	v_mfma_f32_16x16x32_bf16 v[162:165], v[130:133], v[182:185], v[162:165]
	v_mfma_f32_16x16x32_bf16 v[14:17], v[122:125], v[190:193], v[14:17]
	v_mfma_f32_16x16x32_bf16 v[18:21], v[130:133], v[190:193], v[18:21]
	s_barrier
	s_add_u32 s10, s6, 0xb0080
	s_addc_u32 s11, s7, 0
	s_mov_b32 m0, s13
	v_lshl_add_u64 v[10:11], s[10:11], 0, v[2:3]
	global_load_lds_dwordx4 v[10:11], off
	v_lshl_add_u64 v[10:11], s[10:11], 0, v[0:1]
	s_mov_b32 m0, s12
	s_nop 0
	global_load_lds_dwordx4 v[10:11], off
	s_waitcnt vmcnt(6)
	s_barrier
	v_mfma_f32_16x16x32_bf16 v[22:25], v[194:197], v[134:137], v[22:25]
	v_mfma_f32_16x16x32_bf16 v[26:29], v[202:205], v[134:137], v[26:29]
	v_mfma_f32_16x16x32_bf16 v[58:61], v[194:197], v[170:173], v[58:61]
	v_mfma_f32_16x16x32_bf16 v[102:105], v[202:205], v[170:173], v[102:105]
	v_mfma_f32_16x16x32_bf16 v[106:109], v[194:197], v[178:181], v[106:109]
	v_mfma_f32_16x16x32_bf16 v[114:117], v[202:205], v[178:181], v[114:117]
	v_mfma_f32_16x16x32_bf16 v[94:97], v[194:197], v[186:189], v[94:97]
	v_mfma_f32_16x16x32_bf16 v[98:101], v[202:205], v[186:189], v[98:101]
	v_mfma_f32_16x16x32_bf16 v[22:25], v[198:201], v[138:141], v[22:25]
	v_mfma_f32_16x16x32_bf16 v[26:29], v[212:215], v[138:141], v[26:29]
	v_mfma_f32_16x16x32_bf16 v[58:61], v[198:201], v[174:177], v[58:61]
	v_mfma_f32_16x16x32_bf16 v[102:105], v[212:215], v[174:177], v[102:105]
	v_mfma_f32_16x16x32_bf16 v[106:109], v[198:201], v[182:185], v[106:109]
	v_mfma_f32_16x16x32_bf16 v[114:117], v[212:215], v[182:185], v[114:117]
	v_mfma_f32_16x16x32_bf16 v[94:97], v[198:201], v[190:193], v[94:97]
	v_mfma_f32_16x16x32_bf16 v[98:101], v[212:215], v[190:193], v[98:101]
	s_lshl_b32 s3, s9, 8
	s_ashr_i32 s9, s8, 31
	v_add_u32_e32 v10, s3, v4
	s_lshl_b64 s[8:9], s[8:9], 21
	v_ashrrev_i32_e32 v11, 31, v10
	s_add_u32 s8, s24, s8
	s_addc_u32 s9, s25, s9
	v_lshlrev_b64 v[118:119], 12, v[10:11]
	v_lshl_or_b32 v168, s31, 8, v8
	v_lshl_add_u64 v[118:119], s[8:9], 0, v[118:119]
	v_lshlrev_b64 v[120:121], 2, v[168:169]
	v_lshl_add_u64 v[118:119], v[118:119], 0, v[120:121]
	s_barrier
	global_store_dwordx4 v[118:119], v[62:65], off
	global_store_dwordx4 v[118:119], v[66:69], off offset:64
	global_store_dwordx4 v[118:119], v[110:113], off offset:512
	global_store_dwordx4 v[118:119], v[30:33], off offset:576
	s_andn2_b64 vcc, exec, s[4:5]
	s_mov_b32 s31, s30
	v_add_u32_e32 v30, s3, v5
	v_ashrrev_i32_e32 v31, 31, v30
	v_lshlrev_b64 v[30:31], 12, v[30:31]
	v_lshl_add_u64 v[30:31], s[8:9], 0, v[30:31]
	v_lshl_add_u64 v[30:31], v[30:31], 0, v[120:121]
	global_store_dwordx4 v[30:31], v[70:73], off
	global_store_dwordx4 v[30:31], v[74:77], off offset:64
	global_store_dwordx4 v[30:31], v[34:37], off offset:512
	global_store_dwordx4 v[30:31], v[38:41], off offset:576
	v_add_u32_e32 v30, s3, v6
	v_ashrrev_i32_e32 v31, 31, v30
	v_lshlrev_b64 v[30:31], 12, v[30:31]
	v_lshl_add_u64 v[30:31], s[8:9], 0, v[30:31]
	v_lshl_add_u64 v[30:31], v[30:31], 0, v[120:121]
	global_store_dwordx4 v[30:31], v[78:81], off
	global_store_dwordx4 v[30:31], v[82:85], off offset:64
	global_store_dwordx4 v[30:31], v[42:45], off offset:512
	global_store_dwordx4 v[30:31], v[46:49], off offset:576
	v_add_u32_e32 v30, s3, v7
	v_ashrrev_i32_e32 v31, 31, v30
	v_lshlrev_b64 v[30:31], 12, v[30:31]
	v_lshl_add_u64 v[30:31], s[8:9], 0, v[30:31]
	v_lshl_add_u64 v[30:31], v[30:31], 0, v[120:121]
	global_store_dwordx4 v[30:31], v[86:89], off
	global_store_dwordx4 v[30:31], v[90:93], off offset:64
	global_store_dwordx4 v[30:31], v[50:53], off offset:512
	global_store_dwordx4 v[30:31], v[54:57], off offset:576
	v_add_u32_e32 v30, 0x80, v10
	v_ashrrev_i32_e32 v31, 31, v30
	v_lshlrev_b64 v[30:31], 12, v[30:31]
	v_lshl_add_u64 v[30:31], s[8:9], 0, v[30:31]
	v_lshl_add_u64 v[30:31], v[30:31], 0, v[120:121]
	global_store_dwordx4 v[30:31], v[142:145], off
	global_store_dwordx4 v[30:31], v[146:149], off offset:64
	global_store_dwordx4 v[30:31], v[22:25], off offset:512
	global_store_dwordx4 v[30:31], v[26:29], off offset:576
	s_mov_b64 s[12:13], s[6:7]
	v_add_u32_e32 v22, 0x90, v10
	v_ashrrev_i32_e32 v23, 31, v22
	v_lshlrev_b64 v[22:23], 12, v[22:23]
	v_lshl_add_u64 v[22:23], s[8:9], 0, v[22:23]
	v_lshl_add_u64 v[22:23], v[22:23], 0, v[120:121]
	global_store_dwordx4 v[22:23], v[150:153], off
	global_store_dwordx4 v[22:23], v[154:157], off offset:64
	global_store_dwordx4 v[22:23], v[58:61], off offset:512
	global_store_dwordx4 v[22:23], v[102:105], off offset:576
	v_add_u32_e32 v22, 0xa0, v10
	v_add_u32_e32 v10, 0xb0, v10
	v_ashrrev_i32_e32 v23, 31, v22
	v_ashrrev_i32_e32 v11, 31, v10
	v_lshlrev_b64 v[22:23], 12, v[22:23]
	v_lshlrev_b64 v[10:11], 12, v[10:11]
	v_lshl_add_u64 v[22:23], s[8:9], 0, v[22:23]
	v_lshl_add_u64 v[10:11], s[8:9], 0, v[10:11]
	v_lshl_add_u64 v[22:23], v[22:23], 0, v[120:121]
	v_lshl_add_u64 v[10:11], v[10:11], 0, v[120:121]
	s_mov_b32 s8, s2
	s_mov_b32 s9, s29
	s_mov_b64 s[10:11], s[0:1]
	global_store_dwordx4 v[22:23], v[158:161], off
	global_store_dwordx4 v[22:23], v[162:165], off offset:64
	global_store_dwordx4 v[22:23], v[106:109], off offset:512
	global_store_dwordx4 v[22:23], v[114:117], off offset:576
	global_store_dwordx4 v[10:11], v[14:17], off
	global_store_dwordx4 v[10:11], v[18:21], off offset:64
	global_store_dwordx4 v[10:11], v[94:97], off offset:512
	global_store_dwordx4 v[10:11], v[98:101], off offset:576
	s_cbranch_vccz .LBB0_925

.LBB0_948:
	s_add_u32 s18, s16, 0x100
	s_addc_u32 s19, s17, 0
	s_add_i32 s49, 0, 0x10000
	s_cmp_eq_u32 s48, 40
	s_cselect_b32 s23, s3, s19
	s_cselect_b32 s22, s2, s18
	s_cselect_b32 s21, s15, s47
	s_cselect_b32 s20, s14, s46
	s_add_i32 s50, 0, 0x14000
	v_add_u32_e32 v140, s49, v163
	v_add_u32_e32 v166, s50, v163
	ds_read_b128 v[128:131], v140
	ds_read_b128 v[132:135], v140 offset:1024
	ds_read_b128 v[136:139], v140 offset:2048
	ds_read_b128 v[140:143], v140 offset:3072
	ds_read_b128 v[154:157], v166
	ds_read_b128 v[158:161], v166 offset:1024
	ds_read_b128 v[170:173], v166 offset:2048
	ds_read_b128 v[174:177], v166 offset:3072
	v_lshl_add_u64 v[166:167], s[16:17], 0, v[152:153]
	s_add_i32 m0, s25, 0xc000
	ds_read_b128 v[178:181], v165
	ds_read_b128 v[182:185], v165 offset:1024
	ds_read_b128 v[186:189], v165 offset:2048
	ds_read_b128 v[190:193], v165 offset:3072
	ds_read_b128 v[194:197], v165 offset:4096
	ds_read_b128 v[198:201], v165 offset:5120
	ds_read_b128 v[212:215], v165 offset:6144
	ds_read_b128 v[216:219], v165 offset:7168
	global_load_lds_dwordx4 v[166:167], off
	v_lshl_add_u64 v[166:167], s[16:17], 0, v[150:151]
	s_add_i32 m0, s25, 0xe000
	s_nop 0
	global_load_lds_dwordx4 v[166:167], off
	s_waitcnt vmcnt(8)
	s_waitcnt lgkmcnt(0)
	s_barrier
	s_waitcnt lgkmcnt(0)
	v_mfma_f32_16x16x32_bf16 v[124:127], v[128:131], v[178:181], v[124:127]
	v_mfma_f32_16x16x32_bf16 v[120:123], v[136:139], v[178:181], v[120:123]
	v_mfma_f32_16x16x32_bf16 v[116:119], v[128:131], v[186:189], v[116:119]
	v_mfma_f32_16x16x32_bf16 v[112:115], v[136:139], v[186:189], v[112:115]
	v_mfma_f32_16x16x32_bf16 v[92:95], v[128:131], v[194:197], v[92:95]
	v_mfma_f32_16x16x32_bf16 v[88:91], v[136:139], v[194:197], v[88:91]
	v_mfma_f32_16x16x32_bf16 v[76:79], v[128:131], v[212:215], v[76:79]
	v_mfma_f32_16x16x32_bf16 v[72:75], v[136:139], v[212:215], v[72:75]
	v_mfma_f32_16x16x32_bf16 v[124:127], v[132:135], v[182:185], v[124:127]
	v_mfma_f32_16x16x32_bf16 v[120:123], v[140:143], v[182:185], v[120:123]
	v_mfma_f32_16x16x32_bf16 v[116:119], v[132:135], v[190:193], v[116:119]
	v_mfma_f32_16x16x32_bf16 v[112:115], v[140:143], v[190:193], v[112:115]
	v_mfma_f32_16x16x32_bf16 v[92:95], v[132:135], v[198:201], v[92:95]
	v_mfma_f32_16x16x32_bf16 v[88:91], v[140:143], v[198:201], v[88:91]
	v_mfma_f32_16x16x32_bf16 v[76:79], v[132:135], v[216:219], v[76:79]
	v_mfma_f32_16x16x32_bf16 v[72:75], v[140:143], v[216:219], v[72:75]
	v_mfma_f32_16x16x32_bf16 v[108:111], v[154:157], v[178:181], v[108:111]
	v_mfma_f32_16x16x32_bf16 v[104:107], v[170:173], v[178:181], v[104:107]
	v_mfma_f32_16x16x32_bf16 v[100:103], v[154:157], v[186:189], v[100:103]
	v_mfma_f32_16x16x32_bf16 v[96:99], v[170:173], v[186:189], v[96:99]
	v_mfma_f32_16x16x32_bf16 v[84:87], v[154:157], v[194:197], v[84:87]
	v_mfma_f32_16x16x32_bf16 v[80:83], v[170:173], v[194:197], v[80:83]
	v_mfma_f32_16x16x32_bf16 v[68:71], v[154:157], v[212:215], v[68:71]
	v_mfma_f32_16x16x32_bf16 v[64:67], v[170:173], v[212:215], v[64:67]
	v_mfma_f32_16x16x32_bf16 v[108:111], v[158:161], v[182:185], v[108:111]
	v_mfma_f32_16x16x32_bf16 v[104:107], v[174:177], v[182:185], v[104:107]
	v_mfma_f32_16x16x32_bf16 v[100:103], v[158:161], v[190:193], v[100:103]
	v_mfma_f32_16x16x32_bf16 v[96:99], v[174:177], v[190:193], v[96:99]
	v_mfma_f32_16x16x32_bf16 v[84:87], v[158:161], v[198:201], v[84:87]
	v_mfma_f32_16x16x32_bf16 v[80:83], v[174:177], v[198:201], v[80:83]
	v_mfma_f32_16x16x32_bf16 v[68:71], v[158:161], v[216:219], v[68:71]
	v_mfma_f32_16x16x32_bf16 v[64:67], v[174:177], v[216:219], v[64:67]
	s_barrier
	s_add_i32 s16, s49, s24
	v_lshl_add_u64 v[166:167], s[20:21], 0, v[168:169]
	s_mov_b32 m0, s16
	ds_read_b128 v[178:181], v165 offset:16384
	ds_read_b128 v[182:185], v165 offset:17408
	ds_read_b128 v[186:189], v165 offset:18432
	ds_read_b128 v[190:193], v165 offset:19456
	ds_read_b128 v[194:197], v165 offset:20480
	ds_read_b128 v[198:201], v165 offset:21504
	ds_read_b128 v[212:215], v165 offset:22528
	ds_read_b128 v[216:219], v165 offset:23552
	global_load_lds_dwordx4 v[166:167], off
	s_add_i32 m0, s16, 0x2000
	s_add_u32 s16, s20, 0xb0000
	v_lshl_add_u64 v[202:203], s[20:21], 0, v[144:145]
	s_addc_u32 s17, s21, 0
	s_add_i32 s49, s50, s24
	global_load_lds_dwordx4 v[202:203], off
	v_lshl_add_u64 v[220:221], s[16:17], 0, v[168:169]
	s_mov_b32 m0, s49
	v_lshl_add_u64 v[222:223], s[22:23], 0, v[146:147]
	global_load_lds_dwordx4 v[220:221], off
	v_lshl_add_u64 v[220:221], s[16:17], 0, v[144:145]
	s_add_i32 m0, s49, 0x2000
	s_nop 0
	global_load_lds_dwordx4 v[220:221], off
	v_lshl_add_u64 v[220:221], s[22:23], 0, v[148:149]
	s_mov_b32 m0, s25
	s_nop 0
	global_load_lds_dwordx4 v[220:221], off
	s_mov_b32 m0, s36
	s_nop 0
	global_load_lds_dwordx4 v[222:223], off
	s_waitcnt vmcnt(8)
	s_waitcnt lgkmcnt(0)
	s_barrier
	s_waitcnt lgkmcnt(0)
	v_mfma_f32_16x16x32_bf16 v[60:63], v[128:131], v[178:181], v[60:63]
	v_mfma_f32_16x16x32_bf16 v[56:59], v[136:139], v[178:181], v[56:59]
	v_mfma_f32_16x16x32_bf16 v[44:47], v[128:131], v[186:189], v[44:47]
	v_mfma_f32_16x16x32_bf16 v[40:43], v[136:139], v[186:189], v[40:43]
	v_mfma_f32_16x16x32_bf16 v[28:31], v[128:131], v[194:197], v[28:31]
	v_mfma_f32_16x16x32_bf16 v[24:27], v[136:139], v[194:197], v[24:27]
	v_mfma_f32_16x16x32_bf16 v[12:15], v[128:131], v[212:215], v[12:15]
	v_mfma_f32_16x16x32_bf16 v[8:11], v[136:139], v[212:215], v[8:11]
	v_mfma_f32_16x16x32_bf16 v[60:63], v[132:135], v[182:185], v[60:63]
	v_mfma_f32_16x16x32_bf16 v[56:59], v[140:143], v[182:185], v[56:59]
	v_mfma_f32_16x16x32_bf16 v[44:47], v[132:135], v[190:193], v[44:47]
	v_mfma_f32_16x16x32_bf16 v[40:43], v[140:143], v[190:193], v[40:43]
	v_mfma_f32_16x16x32_bf16 v[28:31], v[132:135], v[198:201], v[28:31]
	v_mfma_f32_16x16x32_bf16 v[24:27], v[140:143], v[198:201], v[24:27]
	v_mfma_f32_16x16x32_bf16 v[12:15], v[132:135], v[216:219], v[12:15]
	v_mfma_f32_16x16x32_bf16 v[8:11], v[140:143], v[216:219], v[8:11]
	v_mfma_f32_16x16x32_bf16 v[52:55], v[154:157], v[178:181], v[52:55]
	v_mfma_f32_16x16x32_bf16 v[48:51], v[170:173], v[178:181], v[48:51]
	v_mfma_f32_16x16x32_bf16 v[36:39], v[154:157], v[186:189], v[36:39]
	v_mfma_f32_16x16x32_bf16 v[32:35], v[170:173], v[186:189], v[32:35]
	v_mfma_f32_16x16x32_bf16 v[20:23], v[154:157], v[194:197], v[20:23]
	v_mfma_f32_16x16x32_bf16 v[16:19], v[170:173], v[194:197], v[16:19]
	v_mfma_f32_16x16x32_bf16 v[4:7], v[154:157], v[212:215], v[4:7]
	v_mfma_f32_16x16x32_bf16 v[0:3], v[170:173], v[212:215], v[0:3]
	v_mfma_f32_16x16x32_bf16 v[52:55], v[158:161], v[182:185], v[52:55]
	v_mfma_f32_16x16x32_bf16 v[48:51], v[174:177], v[182:185], v[48:51]
	v_mfma_f32_16x16x32_bf16 v[36:39], v[158:161], v[190:193], v[36:39]
	v_mfma_f32_16x16x32_bf16 v[32:35], v[174:177], v[190:193], v[32:35]
	v_mfma_f32_16x16x32_bf16 v[20:23], v[158:161], v[198:201], v[20:23]
	v_mfma_f32_16x16x32_bf16 v[16:19], v[174:177], v[198:201], v[16:19]
	v_mfma_f32_16x16x32_bf16 v[4:7], v[158:161], v[216:219], v[4:7]
	v_mfma_f32_16x16x32_bf16 v[0:3], v[174:177], v[216:219], v[0:3]
	s_barrier
	s_add_i32 s49, 0, 0x18000
	s_add_i32 s50, 0, 0x1c000
	v_add_u32_e32 v140, s49, v163
	v_add_u32_e32 v174, s50, v163
	ds_read_b128 v[128:131], v140
	ds_read_b128 v[132:135], v140 offset:1024
	ds_read_b128 v[136:139], v140 offset:2048
	ds_read_b128 v[140:143], v140 offset:3072
	ds_read_b128 v[154:157], v174
	ds_read_b128 v[158:161], v174 offset:1024
	ds_read_b128 v[170:173], v174 offset:2048
	ds_read_b128 v[174:177], v174 offset:3072
	s_add_u32 s16, s22, 0xb0000
	s_addc_u32 s17, s23, 0
	s_mov_b32 m0, s37
	v_lshl_add_u64 v[224:225], s[16:17], 0, v[148:149]
	ds_read_b128 v[178:181], v165 offset:32768
	ds_read_b128 v[182:185], v165 offset:33792
	ds_read_b128 v[186:189], v165 offset:34816
	ds_read_b128 v[190:193], v165 offset:35840
	ds_read_b128 v[194:197], v165 offset:36864
	ds_read_b128 v[198:201], v165 offset:37888
	ds_read_b128 v[212:215], v165 offset:38912
	ds_read_b128 v[216:219], v165 offset:39936
	global_load_lds_dwordx4 v[224:225], off
	v_lshl_add_u64 v[224:225], s[16:17], 0, v[146:147]
	s_mov_b32 m0, s38
	s_nop 0
	global_load_lds_dwordx4 v[224:225], off
	s_waitcnt vmcnt(8)
	s_waitcnt lgkmcnt(0)
	s_barrier
	s_waitcnt lgkmcnt(0)
	v_mfma_f32_16x16x32_bf16 v[124:127], v[128:131], v[178:181], v[124:127]
	v_mfma_f32_16x16x32_bf16 v[120:123], v[136:139], v[178:181], v[120:123]
	v_mfma_f32_16x16x32_bf16 v[116:119], v[128:131], v[186:189], v[116:119]
	v_mfma_f32_16x16x32_bf16 v[112:115], v[136:139], v[186:189], v[112:115]
	v_mfma_f32_16x16x32_bf16 v[92:95], v[128:131], v[194:197], v[92:95]
	v_mfma_f32_16x16x32_bf16 v[88:91], v[136:139], v[194:197], v[88:91]
	v_mfma_f32_16x16x32_bf16 v[76:79], v[128:131], v[212:215], v[76:79]
	v_mfma_f32_16x16x32_bf16 v[72:75], v[136:139], v[212:215], v[72:75]
	v_mfma_f32_16x16x32_bf16 v[124:127], v[132:135], v[182:185], v[124:127]
	v_mfma_f32_16x16x32_bf16 v[120:123], v[140:143], v[182:185], v[120:123]
	v_mfma_f32_16x16x32_bf16 v[116:119], v[132:135], v[190:193], v[116:119]
	v_mfma_f32_16x16x32_bf16 v[112:115], v[140:143], v[190:193], v[112:115]
	v_mfma_f32_16x16x32_bf16 v[92:95], v[132:135], v[198:201], v[92:95]
	v_mfma_f32_16x16x32_bf16 v[88:91], v[140:143], v[198:201], v[88:91]
	v_mfma_f32_16x16x32_bf16 v[76:79], v[132:135], v[216:219], v[76:79]
	v_mfma_f32_16x16x32_bf16 v[72:75], v[140:143], v[216:219], v[72:75]
	v_mfma_f32_16x16x32_bf16 v[108:111], v[154:157], v[178:181], v[108:111]
	v_mfma_f32_16x16x32_bf16 v[104:107], v[170:173], v[178:181], v[104:107]
	v_mfma_f32_16x16x32_bf16 v[100:103], v[154:157], v[186:189], v[100:103]
	v_mfma_f32_16x16x32_bf16 v[96:99], v[170:173], v[186:189], v[96:99]
	v_mfma_f32_16x16x32_bf16 v[84:87], v[154:157], v[194:197], v[84:87]
	v_mfma_f32_16x16x32_bf16 v[80:83], v[170:173], v[194:197], v[80:83]
	v_mfma_f32_16x16x32_bf16 v[68:71], v[154:157], v[212:215], v[68:71]
	v_mfma_f32_16x16x32_bf16 v[64:67], v[170:173], v[212:215], v[64:67]
	v_mfma_f32_16x16x32_bf16 v[108:111], v[158:161], v[182:185], v[108:111]
	v_mfma_f32_16x16x32_bf16 v[104:107], v[174:177], v[182:185], v[104:107]
	v_mfma_f32_16x16x32_bf16 v[100:103], v[158:161], v[190:193], v[100:103]
	v_mfma_f32_16x16x32_bf16 v[96:99], v[174:177], v[190:193], v[96:99]
	v_mfma_f32_16x16x32_bf16 v[84:87], v[158:161], v[198:201], v[84:87]
	v_mfma_f32_16x16x32_bf16 v[80:83], v[174:177], v[198:201], v[80:83]
	v_mfma_f32_16x16x32_bf16 v[68:71], v[158:161], v[216:219], v[68:71]
	v_mfma_f32_16x16x32_bf16 v[64:67], v[174:177], v[216:219], v[64:67]
	s_barrier
	s_add_i32 s16, s49, s24
	v_lshl_add_u64 v[166:167], v[166:167], 0, s[74:75]
	s_mov_b32 m0, s16
	ds_read_b128 v[178:181], v165 offset:49152
	ds_read_b128 v[182:185], v165 offset:50176
	ds_read_b128 v[186:189], v165 offset:51200
	ds_read_b128 v[190:193], v165 offset:52224
	ds_read_b128 v[194:197], v165 offset:53248
	ds_read_b128 v[198:201], v165 offset:54272
	ds_read_b128 v[212:215], v165 offset:55296
	ds_read_b128 v[216:219], v165 offset:56320
	global_load_lds_dwordx4 v[166:167], off
	s_add_i32 m0, s16, 0x2000
	s_add_u32 s16, s20, 0xb0080
	v_lshl_add_u64 v[166:167], v[202:203], 0, s[74:75]
	s_addc_u32 s17, s21, 0
	s_add_i32 s20, s50, s24
	global_load_lds_dwordx4 v[166:167], off
	v_lshl_add_u64 v[166:167], s[16:17], 0, v[168:169]
	s_mov_b32 m0, s20
	s_nop 0
	global_load_lds_dwordx4 v[166:167], off
	v_lshl_add_u64 v[166:167], s[16:17], 0, v[144:145]
	s_add_i32 m0, s20, 0x2000
	s_nop 0
	global_load_lds_dwordx4 v[166:167], off
	v_lshl_add_u64 v[166:167], v[220:221], 0, s[74:75]
	s_mov_b32 m0, s39
	s_nop 0
	global_load_lds_dwordx4 v[166:167], off
	v_lshl_add_u64 v[166:167], v[222:223], 0, s[74:75]
	s_mov_b32 m0, s40
	s_nop 0
	global_load_lds_dwordx4 v[166:167], off
	s_waitcnt vmcnt(8)
	s_waitcnt lgkmcnt(0)
	s_barrier
	s_waitcnt lgkmcnt(0)
	v_mfma_f32_16x16x32_bf16 v[60:63], v[128:131], v[178:181], v[60:63]
	v_mfma_f32_16x16x32_bf16 v[56:59], v[136:139], v[178:181], v[56:59]
	v_mfma_f32_16x16x32_bf16 v[44:47], v[128:131], v[186:189], v[44:47]
	v_mfma_f32_16x16x32_bf16 v[40:43], v[136:139], v[186:189], v[40:43]
	v_mfma_f32_16x16x32_bf16 v[28:31], v[128:131], v[194:197], v[28:31]
	v_mfma_f32_16x16x32_bf16 v[24:27], v[136:139], v[194:197], v[24:27]
	v_mfma_f32_16x16x32_bf16 v[12:15], v[128:131], v[212:215], v[12:15]
	v_mfma_f32_16x16x32_bf16 v[8:11], v[136:139], v[212:215], v[8:11]
	v_mfma_f32_16x16x32_bf16 v[60:63], v[132:135], v[182:185], v[60:63]
	v_mfma_f32_16x16x32_bf16 v[56:59], v[140:143], v[182:185], v[56:59]
	v_mfma_f32_16x16x32_bf16 v[44:47], v[132:135], v[190:193], v[44:47]
	v_mfma_f32_16x16x32_bf16 v[40:43], v[140:143], v[190:193], v[40:43]
	v_mfma_f32_16x16x32_bf16 v[28:31], v[132:135], v[198:201], v[28:31]
	v_mfma_f32_16x16x32_bf16 v[24:27], v[140:143], v[198:201], v[24:27]
	v_mfma_f32_16x16x32_bf16 v[12:15], v[132:135], v[216:219], v[12:15]
	v_mfma_f32_16x16x32_bf16 v[8:11], v[140:143], v[216:219], v[8:11]
	v_mfma_f32_16x16x32_bf16 v[52:55], v[154:157], v[178:181], v[52:55]
	v_mfma_f32_16x16x32_bf16 v[48:51], v[170:173], v[178:181], v[48:51]
	v_mfma_f32_16x16x32_bf16 v[36:39], v[154:157], v[186:189], v[36:39]
	v_mfma_f32_16x16x32_bf16 v[32:35], v[170:173], v[186:189], v[32:35]
	v_mfma_f32_16x16x32_bf16 v[20:23], v[154:157], v[194:197], v[20:23]
	v_mfma_f32_16x16x32_bf16 v[16:19], v[170:173], v[194:197], v[16:19]
	v_mfma_f32_16x16x32_bf16 v[4:7], v[154:157], v[212:215], v[4:7]
	v_mfma_f32_16x16x32_bf16 v[0:3], v[170:173], v[212:215], v[0:3]
	v_mfma_f32_16x16x32_bf16 v[52:55], v[158:161], v[182:185], v[52:55]
	v_mfma_f32_16x16x32_bf16 v[48:51], v[174:177], v[182:185], v[48:51]
	v_mfma_f32_16x16x32_bf16 v[36:39], v[158:161], v[190:193], v[36:39]
	v_mfma_f32_16x16x32_bf16 v[32:35], v[174:177], v[190:193], v[32:35]
	v_mfma_f32_16x16x32_bf16 v[20:23], v[158:161], v[198:201], v[20:23]
	v_mfma_f32_16x16x32_bf16 v[16:19], v[174:177], v[198:201], v[16:19]
	v_mfma_f32_16x16x32_bf16 v[4:7], v[158:161], v[216:219], v[4:7]
	v_mfma_f32_16x16x32_bf16 v[0:3], v[174:177], v[216:219], v[0:3]
	s_barrier
	s_add_i32 s48, s48, 2
	s_add_u32 s46, s46, 0x100
	s_addc_u32 s47, s47, 0
	s_cmp_gt_u32 s48, 41
	s_mov_b64 s[16:17], s[18:19]
	s_cbranch_scc0 .LBB0_948
	s_and_b64 vcc, exec, s[10:11]
	s_cbranch_vccz .LBB0_951
	s_barrier

.LBB0_973:
	s_add_u32 s22, s16, s20
	s_addc_u32 s23, s17, s21
	s_add_u32 s22, s22, 0x100
	s_addc_u32 s23, s23, 0
	s_add_u32 s54, s51, s20
	s_addc_u32 s55, s52, s21
	s_add_i32 s56, 0, 0x10000
	s_cmpk_eq_i32 s20, 0x1500
	s_cselect_b32 s25, s19, s23
	s_cselect_b32 s24, s18, s22
	s_cselect_b32 s23, s5, s55
	s_cselect_b32 s22, s4, s54
	s_add_i32 s57, 0, 0x14000
	v_add_u32_e32 v156, s56, v142
	v_add_u32_e32 v174, s57, v142
	ds_read_b128 v[144:147], v156
	ds_read_b128 v[148:151], v156 offset:1024
	ds_read_b128 v[152:155], v156 offset:2048
	ds_read_b128 v[156:159], v156 offset:3072
	ds_read_b128 v[160:163], v174
	ds_read_b128 v[164:167], v174 offset:1024
	ds_read_b128 v[170:173], v174 offset:2048
	ds_read_b128 v[174:177], v174 offset:3072
	v_lshl_add_u64 v[202:203], v[140:141], 0, s[20:21]
	s_add_i32 m0, s41, 0xc000
	ds_read_b128 v[178:181], v143
	ds_read_b128 v[182:185], v143 offset:1024
	ds_read_b128 v[186:189], v143 offset:2048
	ds_read_b128 v[190:193], v143 offset:3072
	ds_read_b128 v[194:197], v143 offset:4096
	ds_read_b128 v[198:201], v143 offset:5120
	ds_read_b128 v[212:215], v143 offset:6144
	ds_read_b128 v[222:225], v143 offset:7168
	global_load_lds_dwordx4 v[202:203], off
	v_lshl_add_u64 v[202:203], v[138:139], 0, s[20:21]
	s_add_i32 m0, s41, 0xe000
	s_nop 0
	global_load_lds_dwordx4 v[202:203], off
	s_waitcnt vmcnt(8)
	s_waitcnt lgkmcnt(0)
	s_barrier
	s_waitcnt lgkmcnt(0)
	v_mfma_f32_16x16x32_bf16 v[124:127], v[144:147], v[178:181], v[124:127]
	v_mfma_f32_16x16x32_bf16 v[120:123], v[152:155], v[178:181], v[120:123]
	v_mfma_f32_16x16x32_bf16 v[108:111], v[144:147], v[186:189], v[108:111]
	v_mfma_f32_16x16x32_bf16 v[104:107], v[152:155], v[186:189], v[104:107]
	v_mfma_f32_16x16x32_bf16 v[96:99], v[144:147], v[194:197], v[96:99]
	v_mfma_f32_16x16x32_bf16 v[88:91], v[152:155], v[194:197], v[88:91]
	v_mfma_f32_16x16x32_bf16 v[80:83], v[144:147], v[212:215], v[80:83]
	v_mfma_f32_16x16x32_bf16 v[72:75], v[152:155], v[212:215], v[72:75]
	v_mfma_f32_16x16x32_bf16 v[124:127], v[148:151], v[182:185], v[124:127]
	v_mfma_f32_16x16x32_bf16 v[120:123], v[156:159], v[182:185], v[120:123]
	v_mfma_f32_16x16x32_bf16 v[108:111], v[148:151], v[190:193], v[108:111]
	v_mfma_f32_16x16x32_bf16 v[104:107], v[156:159], v[190:193], v[104:107]
	v_mfma_f32_16x16x32_bf16 v[96:99], v[148:151], v[198:201], v[96:99]
	v_mfma_f32_16x16x32_bf16 v[88:91], v[156:159], v[198:201], v[88:91]
	v_mfma_f32_16x16x32_bf16 v[80:83], v[148:151], v[222:225], v[80:83]
	v_mfma_f32_16x16x32_bf16 v[72:75], v[156:159], v[222:225], v[72:75]
	v_mfma_f32_16x16x32_bf16 v[116:119], v[160:163], v[178:181], v[116:119]
	v_mfma_f32_16x16x32_bf16 v[112:115], v[170:173], v[178:181], v[112:115]
	v_mfma_f32_16x16x32_bf16 v[100:103], v[160:163], v[186:189], v[100:103]
	v_mfma_f32_16x16x32_bf16 v[92:95], v[170:173], v[186:189], v[92:95]
	v_mfma_f32_16x16x32_bf16 v[84:87], v[160:163], v[194:197], v[84:87]
	v_mfma_f32_16x16x32_bf16 v[76:79], v[170:173], v[194:197], v[76:79]
	v_mfma_f32_16x16x32_bf16 v[68:71], v[160:163], v[212:215], v[68:71]
	v_mfma_f32_16x16x32_bf16 v[64:67], v[170:173], v[212:215], v[64:67]
	v_mfma_f32_16x16x32_bf16 v[116:119], v[164:167], v[182:185], v[116:119]
	v_mfma_f32_16x16x32_bf16 v[112:115], v[174:177], v[182:185], v[112:115]
	v_mfma_f32_16x16x32_bf16 v[100:103], v[164:167], v[190:193], v[100:103]
	v_mfma_f32_16x16x32_bf16 v[92:95], v[174:177], v[190:193], v[92:95]
	v_mfma_f32_16x16x32_bf16 v[84:87], v[164:167], v[198:201], v[84:87]
	v_mfma_f32_16x16x32_bf16 v[76:79], v[174:177], v[198:201], v[76:79]
	v_mfma_f32_16x16x32_bf16 v[68:71], v[164:167], v[222:225], v[68:71]
	v_mfma_f32_16x16x32_bf16 v[64:67], v[174:177], v[222:225], v[64:67]
	s_barrier
	s_add_i32 s54, s56, s39
	v_lshl_add_u64 v[202:203], s[22:23], 0, v[168:169]
	s_mov_b32 m0, s54
	ds_read_b128 v[178:181], v143 offset:16384
	ds_read_b128 v[182:185], v143 offset:17408
	ds_read_b128 v[186:189], v143 offset:18432
	ds_read_b128 v[190:193], v143 offset:19456
	ds_read_b128 v[194:197], v143 offset:20480
	ds_read_b128 v[198:201], v143 offset:21504
	ds_read_b128 v[212:215], v143 offset:22528
	ds_read_b128 v[222:225], v143 offset:23552
	global_load_lds_dwordx4 v[202:203], off
	s_add_i32 m0, s54, 0x2000
	s_add_u32 s54, s22, 0xb0000
	v_lshl_add_u64 v[216:217], s[22:23], 0, v[128:129]
	s_addc_u32 s55, s23, 0
	s_add_i32 s56, s57, s39
	global_load_lds_dwordx4 v[216:217], off
	v_lshl_add_u64 v[226:227], s[54:55], 0, v[168:169]
	s_mov_b32 m0, s56
	v_lshl_add_u64 v[228:229], s[24:25], 0, v[130:131]
	global_load_lds_dwordx4 v[226:227], off
	v_lshl_add_u64 v[226:227], s[54:55], 0, v[128:129]
	s_add_i32 m0, s56, 0x2000
	s_nop 0
	global_load_lds_dwordx4 v[226:227], off
	v_lshl_add_u64 v[226:227], s[24:25], 0, v[132:133]
	s_mov_b32 m0, s41
	s_nop 0
	global_load_lds_dwordx4 v[226:227], off
	s_mov_b32 m0, s42
	s_nop 0
	global_load_lds_dwordx4 v[228:229], off
	s_waitcnt vmcnt(8)
	s_waitcnt lgkmcnt(0)
	s_barrier
	s_waitcnt lgkmcnt(0)
	v_mfma_f32_16x16x32_bf16 v[60:63], v[144:147], v[178:181], v[60:63]
	v_mfma_f32_16x16x32_bf16 v[56:59], v[152:155], v[178:181], v[56:59]
	v_mfma_f32_16x16x32_bf16 v[44:47], v[144:147], v[186:189], v[44:47]
	v_mfma_f32_16x16x32_bf16 v[40:43], v[152:155], v[186:189], v[40:43]
	v_mfma_f32_16x16x32_bf16 v[32:35], v[144:147], v[194:197], v[32:35]
	v_mfma_f32_16x16x32_bf16 v[24:27], v[152:155], v[194:197], v[24:27]
	v_mfma_f32_16x16x32_bf16 v[16:19], v[144:147], v[212:215], v[16:19]
	v_mfma_f32_16x16x32_bf16 v[8:11], v[152:155], v[212:215], v[8:11]
	v_mfma_f32_16x16x32_bf16 v[60:63], v[148:151], v[182:185], v[60:63]
	v_mfma_f32_16x16x32_bf16 v[56:59], v[156:159], v[182:185], v[56:59]
	v_mfma_f32_16x16x32_bf16 v[44:47], v[148:151], v[190:193], v[44:47]
	v_mfma_f32_16x16x32_bf16 v[40:43], v[156:159], v[190:193], v[40:43]
	v_mfma_f32_16x16x32_bf16 v[32:35], v[148:151], v[198:201], v[32:35]
	v_mfma_f32_16x16x32_bf16 v[24:27], v[156:159], v[198:201], v[24:27]
	v_mfma_f32_16x16x32_bf16 v[16:19], v[148:151], v[222:225], v[16:19]
	v_mfma_f32_16x16x32_bf16 v[8:11], v[156:159], v[222:225], v[8:11]
	v_mfma_f32_16x16x32_bf16 v[52:55], v[160:163], v[178:181], v[52:55]
	v_mfma_f32_16x16x32_bf16 v[48:51], v[170:173], v[178:181], v[48:51]
	v_mfma_f32_16x16x32_bf16 v[36:39], v[160:163], v[186:189], v[36:39]
	v_mfma_f32_16x16x32_bf16 v[28:31], v[170:173], v[186:189], v[28:31]
	v_mfma_f32_16x16x32_bf16 v[20:23], v[160:163], v[194:197], v[20:23]
	v_mfma_f32_16x16x32_bf16 v[12:15], v[170:173], v[194:197], v[12:15]
	v_mfma_f32_16x16x32_bf16 v[4:7], v[160:163], v[212:215], v[4:7]
	v_mfma_f32_16x16x32_bf16 v[0:3], v[170:173], v[212:215], v[0:3]
	v_mfma_f32_16x16x32_bf16 v[52:55], v[164:167], v[182:185], v[52:55]
	v_mfma_f32_16x16x32_bf16 v[48:51], v[174:177], v[182:185], v[48:51]
	v_mfma_f32_16x16x32_bf16 v[36:39], v[164:167], v[190:193], v[36:39]
	v_mfma_f32_16x16x32_bf16 v[28:31], v[174:177], v[190:193], v[28:31]
	v_mfma_f32_16x16x32_bf16 v[20:23], v[164:167], v[198:201], v[20:23]
	v_mfma_f32_16x16x32_bf16 v[12:15], v[174:177], v[198:201], v[12:15]
	v_mfma_f32_16x16x32_bf16 v[4:7], v[164:167], v[222:225], v[4:7]
	v_mfma_f32_16x16x32_bf16 v[0:3], v[174:177], v[222:225], v[0:3]
	s_barrier
	s_add_i32 s54, 0, 0x18000
	s_add_i32 s55, 0, 0x1c000
	v_add_u32_e32 v156, s54, v142
	v_add_u32_e32 v174, s55, v142
	ds_read_b128 v[144:147], v156
	ds_read_b128 v[148:151], v156 offset:1024
	ds_read_b128 v[152:155], v156 offset:2048
	ds_read_b128 v[156:159], v156 offset:3072
	ds_read_b128 v[160:163], v174
	ds_read_b128 v[164:167], v174 offset:1024
	ds_read_b128 v[170:173], v174 offset:2048
	ds_read_b128 v[174:177], v174 offset:3072
	s_add_u32 s24, s24, 0xb0000
	s_addc_u32 s25, s25, 0
	s_mov_b32 m0, s43
	v_lshl_add_u64 v[230:231], s[24:25], 0, v[132:133]
	ds_read_b128 v[178:181], v143 offset:32768
	ds_read_b128 v[182:185], v143 offset:33792
	ds_read_b128 v[186:189], v143 offset:34816
	ds_read_b128 v[190:193], v143 offset:35840
	ds_read_b128 v[194:197], v143 offset:36864
	ds_read_b128 v[198:201], v143 offset:37888
	ds_read_b128 v[212:215], v143 offset:38912
	ds_read_b128 v[222:225], v143 offset:39936
	global_load_lds_dwordx4 v[230:231], off
	v_lshl_add_u64 v[230:231], s[24:25], 0, v[130:131]
	s_mov_b32 m0, s44
	s_nop 0
	global_load_lds_dwordx4 v[230:231], off
	s_waitcnt vmcnt(8)
	s_waitcnt lgkmcnt(0)
	s_barrier
	s_waitcnt lgkmcnt(0)
	v_mfma_f32_16x16x32_bf16 v[124:127], v[144:147], v[178:181], v[124:127]
	v_mfma_f32_16x16x32_bf16 v[120:123], v[152:155], v[178:181], v[120:123]
	v_mfma_f32_16x16x32_bf16 v[108:111], v[144:147], v[186:189], v[108:111]
	v_mfma_f32_16x16x32_bf16 v[104:107], v[152:155], v[186:189], v[104:107]
	v_mfma_f32_16x16x32_bf16 v[96:99], v[144:147], v[194:197], v[96:99]
	v_mfma_f32_16x16x32_bf16 v[88:91], v[152:155], v[194:197], v[88:91]
	v_mfma_f32_16x16x32_bf16 v[80:83], v[144:147], v[212:215], v[80:83]
	v_mfma_f32_16x16x32_bf16 v[72:75], v[152:155], v[212:215], v[72:75]
	v_mfma_f32_16x16x32_bf16 v[124:127], v[148:151], v[182:185], v[124:127]
	v_mfma_f32_16x16x32_bf16 v[120:123], v[156:159], v[182:185], v[120:123]
	v_mfma_f32_16x16x32_bf16 v[108:111], v[148:151], v[190:193], v[108:111]
	v_mfma_f32_16x16x32_bf16 v[104:107], v[156:159], v[190:193], v[104:107]
	v_mfma_f32_16x16x32_bf16 v[96:99], v[148:151], v[198:201], v[96:99]
	v_mfma_f32_16x16x32_bf16 v[88:91], v[156:159], v[198:201], v[88:91]
	v_mfma_f32_16x16x32_bf16 v[80:83], v[148:151], v[222:225], v[80:83]
	v_mfma_f32_16x16x32_bf16 v[72:75], v[156:159], v[222:225], v[72:75]
	v_mfma_f32_16x16x32_bf16 v[116:119], v[160:163], v[178:181], v[116:119]
	v_mfma_f32_16x16x32_bf16 v[112:115], v[170:173], v[178:181], v[112:115]
	v_mfma_f32_16x16x32_bf16 v[100:103], v[160:163], v[186:189], v[100:103]
	v_mfma_f32_16x16x32_bf16 v[92:95], v[170:173], v[186:189], v[92:95]
	v_mfma_f32_16x16x32_bf16 v[84:87], v[160:163], v[194:197], v[84:87]
	v_mfma_f32_16x16x32_bf16 v[76:79], v[170:173], v[194:197], v[76:79]
	v_mfma_f32_16x16x32_bf16 v[68:71], v[160:163], v[212:215], v[68:71]
	v_mfma_f32_16x16x32_bf16 v[64:67], v[170:173], v[212:215], v[64:67]
	v_mfma_f32_16x16x32_bf16 v[116:119], v[164:167], v[182:185], v[116:119]
	v_mfma_f32_16x16x32_bf16 v[112:115], v[174:177], v[182:185], v[112:115]
	v_mfma_f32_16x16x32_bf16 v[100:103], v[164:167], v[190:193], v[100:103]
	v_mfma_f32_16x16x32_bf16 v[92:95], v[174:177], v[190:193], v[92:95]
	v_mfma_f32_16x16x32_bf16 v[84:87], v[164:167], v[198:201], v[84:87]
	v_mfma_f32_16x16x32_bf16 v[76:79], v[174:177], v[198:201], v[76:79]
	v_mfma_f32_16x16x32_bf16 v[68:71], v[164:167], v[222:225], v[68:71]
	v_mfma_f32_16x16x32_bf16 v[64:67], v[174:177], v[222:225], v[64:67]
	s_barrier
	s_add_i32 s24, s54, s39
	v_lshl_add_u64 v[202:203], v[202:203], 0, s[74:75]
	s_mov_b32 m0, s24
	ds_read_b128 v[178:181], v143 offset:49152
	ds_read_b128 v[182:185], v143 offset:50176
	ds_read_b128 v[186:189], v143 offset:51200
	ds_read_b128 v[190:193], v143 offset:52224
	ds_read_b128 v[194:197], v143 offset:53248
	ds_read_b128 v[198:201], v143 offset:54272
	ds_read_b128 v[212:215], v143 offset:55296
	ds_read_b128 v[222:225], v143 offset:56320
	global_load_lds_dwordx4 v[202:203], off
	s_add_i32 m0, s24, 0x2000
	s_add_u32 s22, s22, 0xb0080
	v_lshl_add_u64 v[202:203], v[216:217], 0, s[74:75]
	s_addc_u32 s23, s23, 0
	s_add_i32 s24, s55, s39
	global_load_lds_dwordx4 v[202:203], off
	v_lshl_add_u64 v[202:203], s[22:23], 0, v[168:169]
	s_mov_b32 m0, s24
	s_nop 0
	global_load_lds_dwordx4 v[202:203], off
	v_lshl_add_u64 v[202:203], s[22:23], 0, v[128:129]
	s_add_i32 m0, s24, 0x2000
	s_nop 0
	global_load_lds_dwordx4 v[202:203], off
	v_lshl_add_u64 v[202:203], v[226:227], 0, s[74:75]
	s_mov_b32 m0, s45
	s_nop 0
	global_load_lds_dwordx4 v[202:203], off
	v_lshl_add_u64 v[202:203], v[228:229], 0, s[74:75]
	s_mov_b32 m0, s46
	s_nop 0
	global_load_lds_dwordx4 v[202:203], off
	s_waitcnt vmcnt(8)
	s_waitcnt lgkmcnt(0)
	s_barrier
	s_waitcnt lgkmcnt(0)
	v_mfma_f32_16x16x32_bf16 v[60:63], v[144:147], v[178:181], v[60:63]
	v_mfma_f32_16x16x32_bf16 v[56:59], v[152:155], v[178:181], v[56:59]
	v_mfma_f32_16x16x32_bf16 v[44:47], v[144:147], v[186:189], v[44:47]
	v_mfma_f32_16x16x32_bf16 v[40:43], v[152:155], v[186:189], v[40:43]
	v_mfma_f32_16x16x32_bf16 v[32:35], v[144:147], v[194:197], v[32:35]
	v_mfma_f32_16x16x32_bf16 v[24:27], v[152:155], v[194:197], v[24:27]
	v_mfma_f32_16x16x32_bf16 v[16:19], v[144:147], v[212:215], v[16:19]
	v_mfma_f32_16x16x32_bf16 v[8:11], v[152:155], v[212:215], v[8:11]
	v_mfma_f32_16x16x32_bf16 v[60:63], v[148:151], v[182:185], v[60:63]
	v_mfma_f32_16x16x32_bf16 v[56:59], v[156:159], v[182:185], v[56:59]
	v_mfma_f32_16x16x32_bf16 v[44:47], v[148:151], v[190:193], v[44:47]
	v_mfma_f32_16x16x32_bf16 v[40:43], v[156:159], v[190:193], v[40:43]
	v_mfma_f32_16x16x32_bf16 v[32:35], v[148:151], v[198:201], v[32:35]
	v_mfma_f32_16x16x32_bf16 v[24:27], v[156:159], v[198:201], v[24:27]
	v_mfma_f32_16x16x32_bf16 v[16:19], v[148:151], v[222:225], v[16:19]
	v_mfma_f32_16x16x32_bf16 v[8:11], v[156:159], v[222:225], v[8:11]
	v_mfma_f32_16x16x32_bf16 v[52:55], v[160:163], v[178:181], v[52:55]
	v_mfma_f32_16x16x32_bf16 v[48:51], v[170:173], v[178:181], v[48:51]
	v_mfma_f32_16x16x32_bf16 v[36:39], v[160:163], v[186:189], v[36:39]
	v_mfma_f32_16x16x32_bf16 v[28:31], v[170:173], v[186:189], v[28:31]
	v_mfma_f32_16x16x32_bf16 v[20:23], v[160:163], v[194:197], v[20:23]
	v_mfma_f32_16x16x32_bf16 v[12:15], v[170:173], v[194:197], v[12:15]
	v_mfma_f32_16x16x32_bf16 v[4:7], v[160:163], v[212:215], v[4:7]
	v_mfma_f32_16x16x32_bf16 v[0:3], v[170:173], v[212:215], v[0:3]
	v_mfma_f32_16x16x32_bf16 v[52:55], v[164:167], v[182:185], v[52:55]
	v_mfma_f32_16x16x32_bf16 v[48:51], v[174:177], v[182:185], v[48:51]
	v_mfma_f32_16x16x32_bf16 v[36:39], v[164:167], v[190:193], v[36:39]
	v_mfma_f32_16x16x32_bf16 v[28:31], v[174:177], v[190:193], v[28:31]
	v_mfma_f32_16x16x32_bf16 v[20:23], v[164:167], v[198:201], v[20:23]
	v_mfma_f32_16x16x32_bf16 v[12:15], v[174:177], v[198:201], v[12:15]
	v_mfma_f32_16x16x32_bf16 v[4:7], v[164:167], v[222:225], v[4:7]
	v_mfma_f32_16x16x32_bf16 v[0:3], v[174:177], v[222:225], v[0:3]
	s_barrier
	s_add_i32 s53, s53, 2
	s_add_u32 s20, s20, 0x100
	s_addc_u32 s21, s21, 0
	s_cmp_gt_u32 s53, 41
	s_cbranch_scc0 .LBB0_973
	s_add_u32 s20, s51, 0xffffff00
	s_addc_u32 s21, s52, -1
	s_and_b64 vcc, exec, s[2:3]
	s_cbranch_vccnz .LBB0_976
	v_mov_b32_e32 v0, 0
	s_mov_b32 s14, s48
	s_mov_b32 s38, s49
	s_mov_b64 s[16:17], s[18:19]
	s_mov_b32 s47, s50
	v_mov_b32_e32 v1, v0
	v_mov_b32_e32 v2, v0
	v_mov_b32_e32 v3, v0
	v_mov_b32_e32 v4, v0
	v_mov_b32_e32 v5, v0
	v_mov_b32_e32 v6, v0
	v_mov_b32_e32 v7, v0
	v_mov_b32_e32 v12, v0
	v_mov_b32_e32 v13, v0
	v_mov_b32_e32 v14, v0
	v_mov_b32_e32 v15, v0
	v_mov_b32_e32 v20, v0
	v_mov_b32_e32 v21, v0
	v_mov_b32_e32 v22, v0
	v_mov_b32_e32 v23, v0
	v_mov_b32_e32 v28, v0
	v_mov_b32_e32 v29, v0
	v_mov_b32_e32 v30, v0
	v_mov_b32_e32 v31, v0
	v_mov_b32_e32 v36, v0
	v_mov_b32_e32 v37, v0
	v_mov_b32_e32 v38, v0
	v_mov_b32_e32 v39, v0
	v_mov_b32_e32 v48, v0
	v_mov_b32_e32 v49, v0
	v_mov_b32_e32 v50, v0
	v_mov_b32_e32 v51, v0
	v_mov_b32_e32 v52, v0
	v_mov_b32_e32 v53, v0
	v_mov_b32_e32 v54, v0
	v_mov_b32_e32 v55, v0
	v_mov_b32_e32 v8, v0
	v_mov_b32_e32 v9, v0
	v_mov_b32_e32 v10, v0
	v_mov_b32_e32 v11, v0
	v_mov_b32_e32 v16, v0
	v_mov_b32_e32 v17, v0
	v_mov_b32_e32 v18, v0
	v_mov_b32_e32 v19, v0
	v_mov_b32_e32 v24, v0
	v_mov_b32_e32 v25, v0
	v_mov_b32_e32 v26, v0
	v_mov_b32_e32 v27, v0
	v_mov_b32_e32 v32, v0
	v_mov_b32_e32 v33, v0
	v_mov_b32_e32 v34, v0
	v_mov_b32_e32 v35, v0
	v_mov_b32_e32 v40, v0
	v_mov_b32_e32 v41, v0
	v_mov_b32_e32 v42, v0
	v_mov_b32_e32 v43, v0
	v_mov_b32_e32 v44, v0
	v_mov_b32_e32 v45, v0
	v_mov_b32_e32 v46, v0
	v_mov_b32_e32 v47, v0
	v_mov_b32_e32 v56, v0
	v_mov_b32_e32 v57, v0
	v_mov_b32_e32 v58, v0
	v_mov_b32_e32 v59, v0
	v_mov_b32_e32 v60, v0
	v_mov_b32_e32 v61, v0
	v_mov_b32_e32 v62, v0
	v_mov_b32_e32 v63, v0
	v_mov_b32_e32 v64, v0
	v_mov_b32_e32 v65, v0
	v_mov_b32_e32 v66, v0
	v_mov_b32_e32 v67, v0
	v_mov_b32_e32 v68, v0
	v_mov_b32_e32 v69, v0
	v_mov_b32_e32 v70, v0
	v_mov_b32_e32 v71, v0
	v_mov_b32_e32 v76, v0
	v_mov_b32_e32 v77, v0
	v_mov_b32_e32 v78, v0
	v_mov_b32_e32 v79, v0
	v_mov_b32_e32 v84, v0
	v_mov_b32_e32 v85, v0
	v_mov_b32_e32 v86, v0
	v_mov_b32_e32 v87, v0
	v_mov_b32_e32 v92, v0
	v_mov_b32_e32 v93, v0
	v_mov_b32_e32 v94, v0
	v_mov_b32_e32 v95, v0
	v_mov_b32_e32 v100, v0
	v_mov_b32_e32 v101, v0
	v_mov_b32_e32 v102, v0
	v_mov_b32_e32 v103, v0
	v_mov_b32_e32 v112, v0
	v_mov_b32_e32 v113, v0
	v_mov_b32_e32 v114, v0
	v_mov_b32_e32 v115, v0
	v_mov_b32_e32 v116, v0
	v_mov_b32_e32 v117, v0
	v_mov_b32_e32 v118, v0
	v_mov_b32_e32 v119, v0
	v_mov_b32_e32 v72, v0
	v_mov_b32_e32 v73, v0
	v_mov_b32_e32 v74, v0
	v_mov_b32_e32 v75, v0
	v_mov_b32_e32 v80, v0
	v_mov_b32_e32 v81, v0
	v_mov_b32_e32 v82, v0
	v_mov_b32_e32 v83, v0
	v_mov_b32_e32 v88, v0
	v_mov_b32_e32 v89, v0
	v_mov_b32_e32 v90, v0
	v_mov_b32_e32 v91, v0
	v_mov_b32_e32 v96, v0
	v_mov_b32_e32 v97, v0
	v_mov_b32_e32 v98, v0
	v_mov_b32_e32 v99, v0
	v_mov_b32_e32 v104, v0
	v_mov_b32_e32 v105, v0
	v_mov_b32_e32 v106, v0
	v_mov_b32_e32 v107, v0
	v_mov_b32_e32 v108, v0
	v_mov_b32_e32 v109, v0
	v_mov_b32_e32 v110, v0
	v_mov_b32_e32 v111, v0
	v_mov_b32_e32 v120, v0
	v_mov_b32_e32 v121, v0
	v_mov_b32_e32 v122, v0
	v_mov_b32_e32 v123, v0
	v_mov_b32_e32 v124, v0
	v_mov_b32_e32 v125, v0
	v_mov_b32_e32 v126, v0
	v_mov_b32_e32 v127, v0
	s_mov_b32 s57, 0xf800000
	s_andn2_b64 vcc, exec, s[0:1]
	s_cbranch_vccnz .LBB0_977
	s_branch .LBB0_978

.LBB0_1032:
	s_add_u32 s14, s12, 0x100
	s_addc_u32 s15, s13, 0
	s_add_i32 s43, 0, 0x10000
	s_cmp_eq_u32 s42, 40
	s_cselect_b32 s19, s3, s15
	s_cselect_b32 s18, s2, s14
	s_cselect_b32 s17, s11, s41
	s_cselect_b32 s16, s10, s40
	s_add_i32 s44, 0, 0x14000
	v_add_u32_e32 v140, s43, v163
	v_add_u32_e32 v166, s44, v163
	ds_read_b128 v[128:131], v140
	ds_read_b128 v[132:135], v140 offset:1024
	ds_read_b128 v[136:139], v140 offset:2048
	ds_read_b128 v[140:143], v140 offset:3072
	ds_read_b128 v[154:157], v166
	ds_read_b128 v[158:161], v166 offset:1024
	ds_read_b128 v[170:173], v166 offset:2048
	ds_read_b128 v[174:177], v166 offset:3072
	v_lshl_add_u64 v[166:167], s[12:13], 0, v[152:153]
	s_add_i32 m0, s21, 0xc000
	ds_read_b128 v[178:181], v165
	ds_read_b128 v[182:185], v165 offset:1024
	ds_read_b128 v[186:189], v165 offset:2048
	ds_read_b128 v[190:193], v165 offset:3072
	ds_read_b128 v[194:197], v165 offset:4096
	ds_read_b128 v[198:201], v165 offset:5120
	ds_read_b128 v[202:205], v165 offset:6144
	ds_read_b128 v[212:215], v165 offset:7168
	global_load_lds_dwordx4 v[166:167], off
	v_lshl_add_u64 v[166:167], s[12:13], 0, v[150:151]
	s_add_i32 m0, s21, 0xe000
	s_nop 0
	global_load_lds_dwordx4 v[166:167], off
	s_waitcnt vmcnt(8)
	s_waitcnt lgkmcnt(0)
	s_barrier
	s_waitcnt lgkmcnt(0)
	v_mfma_f32_16x16x32_bf16 v[124:127], v[128:131], v[178:181], v[124:127]
	v_mfma_f32_16x16x32_bf16 v[120:123], v[136:139], v[178:181], v[120:123]
	v_mfma_f32_16x16x32_bf16 v[112:115], v[128:131], v[186:189], v[112:115]
	v_mfma_f32_16x16x32_bf16 v[104:107], v[136:139], v[186:189], v[104:107]
	v_mfma_f32_16x16x32_bf16 v[92:95], v[128:131], v[194:197], v[92:95]
	v_mfma_f32_16x16x32_bf16 v[88:91], v[136:139], v[194:197], v[88:91]
	v_mfma_f32_16x16x32_bf16 v[76:79], v[128:131], v[202:205], v[76:79]
	v_mfma_f32_16x16x32_bf16 v[72:75], v[136:139], v[202:205], v[72:75]
	v_mfma_f32_16x16x32_bf16 v[124:127], v[132:135], v[182:185], v[124:127]
	v_mfma_f32_16x16x32_bf16 v[120:123], v[140:143], v[182:185], v[120:123]
	v_mfma_f32_16x16x32_bf16 v[112:115], v[132:135], v[190:193], v[112:115]
	v_mfma_f32_16x16x32_bf16 v[104:107], v[140:143], v[190:193], v[104:107]
	v_mfma_f32_16x16x32_bf16 v[92:95], v[132:135], v[198:201], v[92:95]
	v_mfma_f32_16x16x32_bf16 v[88:91], v[140:143], v[198:201], v[88:91]
	v_mfma_f32_16x16x32_bf16 v[76:79], v[132:135], v[212:215], v[76:79]
	v_mfma_f32_16x16x32_bf16 v[72:75], v[140:143], v[212:215], v[72:75]
	v_mfma_f32_16x16x32_bf16 v[116:119], v[154:157], v[178:181], v[116:119]
	v_mfma_f32_16x16x32_bf16 v[108:111], v[170:173], v[178:181], v[108:111]
	v_mfma_f32_16x16x32_bf16 v[100:103], v[154:157], v[186:189], v[100:103]
	v_mfma_f32_16x16x32_bf16 v[96:99], v[170:173], v[186:189], v[96:99]
	v_mfma_f32_16x16x32_bf16 v[84:87], v[154:157], v[194:197], v[84:87]
	v_mfma_f32_16x16x32_bf16 v[80:83], v[170:173], v[194:197], v[80:83]
	v_mfma_f32_16x16x32_bf16 v[68:71], v[154:157], v[202:205], v[68:71]
	v_mfma_f32_16x16x32_bf16 v[64:67], v[170:173], v[202:205], v[64:67]
	v_mfma_f32_16x16x32_bf16 v[116:119], v[158:161], v[182:185], v[116:119]
	v_mfma_f32_16x16x32_bf16 v[108:111], v[174:177], v[182:185], v[108:111]
	v_mfma_f32_16x16x32_bf16 v[100:103], v[158:161], v[190:193], v[100:103]
	v_mfma_f32_16x16x32_bf16 v[96:99], v[174:177], v[190:193], v[96:99]
	v_mfma_f32_16x16x32_bf16 v[84:87], v[158:161], v[198:201], v[84:87]
	v_mfma_f32_16x16x32_bf16 v[80:83], v[174:177], v[198:201], v[80:83]
	v_mfma_f32_16x16x32_bf16 v[68:71], v[158:161], v[212:215], v[68:71]
	v_mfma_f32_16x16x32_bf16 v[64:67], v[174:177], v[212:215], v[64:67]
	s_barrier
	s_add_i32 s12, s43, s20
	v_lshl_add_u64 v[166:167], s[16:17], 0, v[168:169]
	s_mov_b32 m0, s12
	ds_read_b128 v[178:181], v165 offset:16384
	ds_read_b128 v[182:185], v165 offset:17408
	ds_read_b128 v[186:189], v165 offset:18432
	ds_read_b128 v[190:193], v165 offset:19456
	ds_read_b128 v[194:197], v165 offset:20480
	ds_read_b128 v[198:201], v165 offset:21504
	ds_read_b128 v[202:205], v165 offset:22528
	ds_read_b128 v[212:215], v165 offset:23552
	global_load_lds_dwordx4 v[166:167], off
	s_add_i32 m0, s12, 0x2000
	s_add_u32 s12, s16, 0xb0000
	v_lshl_add_u64 v[216:217], s[16:17], 0, v[144:145]
	s_addc_u32 s13, s17, 0
	s_add_i32 s43, s44, s20
	global_load_lds_dwordx4 v[216:217], off
	v_lshl_add_u64 v[218:219], s[12:13], 0, v[168:169]
	s_mov_b32 m0, s43
	v_lshl_add_u64 v[220:221], s[18:19], 0, v[146:147]
	global_load_lds_dwordx4 v[218:219], off
	v_lshl_add_u64 v[218:219], s[12:13], 0, v[144:145]
	s_add_i32 m0, s43, 0x2000
	s_nop 0
	global_load_lds_dwordx4 v[218:219], off
	v_lshl_add_u64 v[218:219], s[18:19], 0, v[148:149]
	s_mov_b32 m0, s21
	s_nop 0
	global_load_lds_dwordx4 v[218:219], off
	s_mov_b32 m0, s22
	s_nop 0
	global_load_lds_dwordx4 v[220:221], off
	s_waitcnt vmcnt(8)
	s_waitcnt lgkmcnt(0)
	s_barrier
	s_waitcnt lgkmcnt(0)
	v_mfma_f32_16x16x32_bf16 v[60:63], v[128:131], v[178:181], v[60:63]
	v_mfma_f32_16x16x32_bf16 v[56:59], v[136:139], v[178:181], v[56:59]
	v_mfma_f32_16x16x32_bf16 v[44:47], v[128:131], v[186:189], v[44:47]
	v_mfma_f32_16x16x32_bf16 v[40:43], v[136:139], v[186:189], v[40:43]
	v_mfma_f32_16x16x32_bf16 v[28:31], v[128:131], v[194:197], v[28:31]
	v_mfma_f32_16x16x32_bf16 v[24:27], v[136:139], v[194:197], v[24:27]
	v_mfma_f32_16x16x32_bf16 v[12:15], v[128:131], v[202:205], v[12:15]
	v_mfma_f32_16x16x32_bf16 v[8:11], v[136:139], v[202:205], v[8:11]
	v_mfma_f32_16x16x32_bf16 v[60:63], v[132:135], v[182:185], v[60:63]
	v_mfma_f32_16x16x32_bf16 v[56:59], v[140:143], v[182:185], v[56:59]
	v_mfma_f32_16x16x32_bf16 v[44:47], v[132:135], v[190:193], v[44:47]
	v_mfma_f32_16x16x32_bf16 v[40:43], v[140:143], v[190:193], v[40:43]
	v_mfma_f32_16x16x32_bf16 v[28:31], v[132:135], v[198:201], v[28:31]
	v_mfma_f32_16x16x32_bf16 v[24:27], v[140:143], v[198:201], v[24:27]
	v_mfma_f32_16x16x32_bf16 v[12:15], v[132:135], v[212:215], v[12:15]
	v_mfma_f32_16x16x32_bf16 v[8:11], v[140:143], v[212:215], v[8:11]
	v_mfma_f32_16x16x32_bf16 v[52:55], v[154:157], v[178:181], v[52:55]
	v_mfma_f32_16x16x32_bf16 v[48:51], v[170:173], v[178:181], v[48:51]
	v_mfma_f32_16x16x32_bf16 v[36:39], v[154:157], v[186:189], v[36:39]
	v_mfma_f32_16x16x32_bf16 v[32:35], v[170:173], v[186:189], v[32:35]
	v_mfma_f32_16x16x32_bf16 v[20:23], v[154:157], v[194:197], v[20:23]
	v_mfma_f32_16x16x32_bf16 v[16:19], v[170:173], v[194:197], v[16:19]
	v_mfma_f32_16x16x32_bf16 v[4:7], v[154:157], v[202:205], v[4:7]
	v_mfma_f32_16x16x32_bf16 v[0:3], v[170:173], v[202:205], v[0:3]
	v_mfma_f32_16x16x32_bf16 v[52:55], v[158:161], v[182:185], v[52:55]
	v_mfma_f32_16x16x32_bf16 v[48:51], v[174:177], v[182:185], v[48:51]
	v_mfma_f32_16x16x32_bf16 v[36:39], v[158:161], v[190:193], v[36:39]
	v_mfma_f32_16x16x32_bf16 v[32:35], v[174:177], v[190:193], v[32:35]
	v_mfma_f32_16x16x32_bf16 v[20:23], v[158:161], v[198:201], v[20:23]
	v_mfma_f32_16x16x32_bf16 v[16:19], v[174:177], v[198:201], v[16:19]
	v_mfma_f32_16x16x32_bf16 v[4:7], v[158:161], v[212:215], v[4:7]
	v_mfma_f32_16x16x32_bf16 v[0:3], v[174:177], v[212:215], v[0:3]
	s_barrier
	s_add_i32 s43, 0, 0x18000
	s_add_i32 s44, 0, 0x1c000
	v_add_u32_e32 v140, s43, v163
	v_add_u32_e32 v174, s44, v163
	ds_read_b128 v[128:131], v140
	ds_read_b128 v[132:135], v140 offset:1024
	ds_read_b128 v[136:139], v140 offset:2048
	ds_read_b128 v[140:143], v140 offset:3072
	ds_read_b128 v[154:157], v174
	ds_read_b128 v[158:161], v174 offset:1024
	ds_read_b128 v[170:173], v174 offset:2048
	ds_read_b128 v[174:177], v174 offset:3072
	s_add_u32 s12, s18, 0xb0000
	s_addc_u32 s13, s19, 0
	s_mov_b32 m0, s23
	v_lshl_add_u64 v[222:223], s[12:13], 0, v[148:149]
	ds_read_b128 v[178:181], v165 offset:32768
	ds_read_b128 v[182:185], v165 offset:33792
	ds_read_b128 v[186:189], v165 offset:34816
	ds_read_b128 v[190:193], v165 offset:35840
	ds_read_b128 v[194:197], v165 offset:36864
	ds_read_b128 v[198:201], v165 offset:37888
	ds_read_b128 v[202:205], v165 offset:38912
	ds_read_b128 v[212:215], v165 offset:39936
	global_load_lds_dwordx4 v[222:223], off
	v_lshl_add_u64 v[222:223], s[12:13], 0, v[146:147]
	s_mov_b32 m0, s24
	s_nop 0
	global_load_lds_dwordx4 v[222:223], off
	s_waitcnt vmcnt(8)
	s_waitcnt lgkmcnt(0)
	s_barrier
	s_waitcnt lgkmcnt(0)
	v_mfma_f32_16x16x32_bf16 v[124:127], v[128:131], v[178:181], v[124:127]
	v_mfma_f32_16x16x32_bf16 v[120:123], v[136:139], v[178:181], v[120:123]
	v_mfma_f32_16x16x32_bf16 v[112:115], v[128:131], v[186:189], v[112:115]
	v_mfma_f32_16x16x32_bf16 v[104:107], v[136:139], v[186:189], v[104:107]
	v_mfma_f32_16x16x32_bf16 v[92:95], v[128:131], v[194:197], v[92:95]
	v_mfma_f32_16x16x32_bf16 v[88:91], v[136:139], v[194:197], v[88:91]
	v_mfma_f32_16x16x32_bf16 v[76:79], v[128:131], v[202:205], v[76:79]
	v_mfma_f32_16x16x32_bf16 v[72:75], v[136:139], v[202:205], v[72:75]
	v_mfma_f32_16x16x32_bf16 v[124:127], v[132:135], v[182:185], v[124:127]
	v_mfma_f32_16x16x32_bf16 v[120:123], v[140:143], v[182:185], v[120:123]
	v_mfma_f32_16x16x32_bf16 v[112:115], v[132:135], v[190:193], v[112:115]
	v_mfma_f32_16x16x32_bf16 v[104:107], v[140:143], v[190:193], v[104:107]
	v_mfma_f32_16x16x32_bf16 v[92:95], v[132:135], v[198:201], v[92:95]
	v_mfma_f32_16x16x32_bf16 v[88:91], v[140:143], v[198:201], v[88:91]
	v_mfma_f32_16x16x32_bf16 v[76:79], v[132:135], v[212:215], v[76:79]
	v_mfma_f32_16x16x32_bf16 v[72:75], v[140:143], v[212:215], v[72:75]
	v_mfma_f32_16x16x32_bf16 v[116:119], v[154:157], v[178:181], v[116:119]
	v_mfma_f32_16x16x32_bf16 v[108:111], v[170:173], v[178:181], v[108:111]
	v_mfma_f32_16x16x32_bf16 v[100:103], v[154:157], v[186:189], v[100:103]
	v_mfma_f32_16x16x32_bf16 v[96:99], v[170:173], v[186:189], v[96:99]
	v_mfma_f32_16x16x32_bf16 v[84:87], v[154:157], v[194:197], v[84:87]
	v_mfma_f32_16x16x32_bf16 v[80:83], v[170:173], v[194:197], v[80:83]
	v_mfma_f32_16x16x32_bf16 v[68:71], v[154:157], v[202:205], v[68:71]
	v_mfma_f32_16x16x32_bf16 v[64:67], v[170:173], v[202:205], v[64:67]
	v_mfma_f32_16x16x32_bf16 v[116:119], v[158:161], v[182:185], v[116:119]
	v_mfma_f32_16x16x32_bf16 v[108:111], v[174:177], v[182:185], v[108:111]
	v_mfma_f32_16x16x32_bf16 v[100:103], v[158:161], v[190:193], v[100:103]
	v_mfma_f32_16x16x32_bf16 v[96:99], v[174:177], v[190:193], v[96:99]
	v_mfma_f32_16x16x32_bf16 v[84:87], v[158:161], v[198:201], v[84:87]
	v_mfma_f32_16x16x32_bf16 v[80:83], v[174:177], v[198:201], v[80:83]
	v_mfma_f32_16x16x32_bf16 v[68:71], v[158:161], v[212:215], v[68:71]
	v_mfma_f32_16x16x32_bf16 v[64:67], v[174:177], v[212:215], v[64:67]
	s_barrier
	s_add_i32 s12, s43, s20
	v_lshl_add_u64 v[166:167], v[166:167], 0, s[74:75]
	s_mov_b32 m0, s12
	ds_read_b128 v[178:181], v165 offset:49152
	ds_read_b128 v[182:185], v165 offset:50176
	ds_read_b128 v[186:189], v165 offset:51200
	ds_read_b128 v[190:193], v165 offset:52224
	ds_read_b128 v[194:197], v165 offset:53248
	ds_read_b128 v[198:201], v165 offset:54272
	ds_read_b128 v[202:205], v165 offset:55296
	ds_read_b128 v[212:215], v165 offset:56320
	global_load_lds_dwordx4 v[166:167], off
	s_add_i32 m0, s12, 0x2000
	s_add_u32 s12, s16, 0xb0080
	v_lshl_add_u64 v[166:167], v[216:217], 0, s[74:75]
	s_addc_u32 s13, s17, 0
	s_add_i32 s16, s44, s20
	global_load_lds_dwordx4 v[166:167], off
	v_lshl_add_u64 v[166:167], s[12:13], 0, v[168:169]
	s_mov_b32 m0, s16
	s_nop 0
	global_load_lds_dwordx4 v[166:167], off
	v_lshl_add_u64 v[166:167], s[12:13], 0, v[144:145]
	s_add_i32 m0, s16, 0x2000
	s_nop 0
	global_load_lds_dwordx4 v[166:167], off
	v_lshl_add_u64 v[166:167], v[218:219], 0, s[74:75]
	s_mov_b32 m0, s31
	s_nop 0
	global_load_lds_dwordx4 v[166:167], off
	v_lshl_add_u64 v[166:167], v[220:221], 0, s[74:75]
	s_mov_b32 m0, s34
	s_nop 0
	global_load_lds_dwordx4 v[166:167], off
	s_waitcnt vmcnt(8)
	s_waitcnt lgkmcnt(0)
	s_barrier
	s_waitcnt lgkmcnt(0)
	v_mfma_f32_16x16x32_bf16 v[60:63], v[128:131], v[178:181], v[60:63]
	v_mfma_f32_16x16x32_bf16 v[56:59], v[136:139], v[178:181], v[56:59]
	v_mfma_f32_16x16x32_bf16 v[44:47], v[128:131], v[186:189], v[44:47]
	v_mfma_f32_16x16x32_bf16 v[40:43], v[136:139], v[186:189], v[40:43]
	v_mfma_f32_16x16x32_bf16 v[28:31], v[128:131], v[194:197], v[28:31]
	v_mfma_f32_16x16x32_bf16 v[24:27], v[136:139], v[194:197], v[24:27]
	v_mfma_f32_16x16x32_bf16 v[12:15], v[128:131], v[202:205], v[12:15]
	v_mfma_f32_16x16x32_bf16 v[8:11], v[136:139], v[202:205], v[8:11]
	v_mfma_f32_16x16x32_bf16 v[60:63], v[132:135], v[182:185], v[60:63]
	v_mfma_f32_16x16x32_bf16 v[56:59], v[140:143], v[182:185], v[56:59]
	v_mfma_f32_16x16x32_bf16 v[44:47], v[132:135], v[190:193], v[44:47]
	v_mfma_f32_16x16x32_bf16 v[40:43], v[140:143], v[190:193], v[40:43]
	v_mfma_f32_16x16x32_bf16 v[28:31], v[132:135], v[198:201], v[28:31]
	v_mfma_f32_16x16x32_bf16 v[24:27], v[140:143], v[198:201], v[24:27]
	v_mfma_f32_16x16x32_bf16 v[12:15], v[132:135], v[212:215], v[12:15]
	v_mfma_f32_16x16x32_bf16 v[8:11], v[140:143], v[212:215], v[8:11]
	v_mfma_f32_16x16x32_bf16 v[52:55], v[154:157], v[178:181], v[52:55]
	v_mfma_f32_16x16x32_bf16 v[48:51], v[170:173], v[178:181], v[48:51]
	v_mfma_f32_16x16x32_bf16 v[36:39], v[154:157], v[186:189], v[36:39]
	v_mfma_f32_16x16x32_bf16 v[32:35], v[170:173], v[186:189], v[32:35]
	v_mfma_f32_16x16x32_bf16 v[20:23], v[154:157], v[194:197], v[20:23]
	v_mfma_f32_16x16x32_bf16 v[16:19], v[170:173], v[194:197], v[16:19]
	v_mfma_f32_16x16x32_bf16 v[4:7], v[154:157], v[202:205], v[4:7]
	v_mfma_f32_16x16x32_bf16 v[0:3], v[170:173], v[202:205], v[0:3]
	v_mfma_f32_16x16x32_bf16 v[52:55], v[158:161], v[182:185], v[52:55]
	v_mfma_f32_16x16x32_bf16 v[48:51], v[174:177], v[182:185], v[48:51]
	v_mfma_f32_16x16x32_bf16 v[36:39], v[158:161], v[190:193], v[36:39]
	v_mfma_f32_16x16x32_bf16 v[32:35], v[174:177], v[190:193], v[32:35]
	v_mfma_f32_16x16x32_bf16 v[20:23], v[158:161], v[198:201], v[20:23]
	v_mfma_f32_16x16x32_bf16 v[16:19], v[174:177], v[198:201], v[16:19]
	v_mfma_f32_16x16x32_bf16 v[4:7], v[158:161], v[212:215], v[4:7]
	v_mfma_f32_16x16x32_bf16 v[0:3], v[174:177], v[212:215], v[0:3]
	s_barrier
	s_add_i32 s42, s42, 2
	s_add_u32 s40, s40, 0x100
	s_addc_u32 s41, s41, 0
	s_cmp_gt_u32 s42, 41
	s_mov_b64 s[12:13], s[14:15]
	s_cbranch_scc0 .LBB0_1032
	s_and_b64 vcc, exec, s[8:9]
	s_cbranch_vccz .LBB0_1035
	s_barrier
